# v23: + SwiGLU epilogue: the eight ss[row] loads issued together at the top, counted vmcnt(7) waits instead of vmcnt(0) after every store
# speedup vs baseline: 1.2155x; 1.0258x over previous
.LBB0_196:
	ds_read_b128 v[144:147], v151
	ds_read_b128 v[156:159], v151 offset:1024
	ds_read_b128 v[160:163], v151 offset:2048
	ds_read_b128 v[164:167], v151 offset:3072
	s_add_u32 s30, s28, 0xfffc0080
	s_addc_u32 s31, s29, -1
	s_cmp_eq_u32 s80, 12
	s_cselect_b32 s35, s13, s31
	s_cselect_b32 s34, s67, s30
	s_cselect_b32 s31, s11, s77
	s_cselect_b32 s30, s68, s69
	v_lshl_add_u64 v[172:173], s[28:29], 0, v[136:137]
	s_add_i32 m0, s27, 0xc000
	ds_read_b128 v[168:171], v152
	ds_read_b128 v[176:179], v152 offset:1024
	ds_read_b128 v[180:183], v152 offset:2048
	ds_read_b128 v[184:187], v152 offset:3072
	ds_read_b128 v[188:191], v152 offset:4096
	ds_read_b128 v[192:195], v152 offset:5120
	ds_read_b128 v[196:199], v152 offset:6144
	ds_read_b128 v[200:203], v152 offset:7168
	global_load_lds_dwordx4 v[172:173], off
	v_lshl_add_u64 v[172:173], s[28:29], 0, v[138:139]
	s_add_i32 m0, s27, 0xe000
	s_nop 0
	global_load_lds_dwordx4 v[172:173], off
	s_waitcnt lgkmcnt(8)
	s_barrier
	s_waitcnt lgkmcnt(0)
	s_setprio 1
	s_waitcnt lgkmcnt(0)
	v_mfma_f32_16x16x32_bf16 v[116:119], v[144:147], v[168:171], v[116:119]
	v_mfma_f32_16x16x32_bf16 v[112:115], v[160:163], v[168:171], v[112:115]
	v_mfma_f32_16x16x32_bf16 v[100:103], v[144:147], v[180:183], v[100:103]
	v_mfma_f32_16x16x32_bf16 v[96:99], v[160:163], v[180:183], v[96:99]
	v_mfma_f32_16x16x32_bf16 v[84:87], v[144:147], v[188:191], v[84:87]
	v_mfma_f32_16x16x32_bf16 v[80:83], v[160:163], v[188:191], v[80:83]
	v_mfma_f32_16x16x32_bf16 v[72:75], v[144:147], v[196:199], v[72:75]
	v_mfma_f32_16x16x32_bf16 v[64:67], v[160:163], v[196:199], v[64:67]
	v_mfma_f32_16x16x32_bf16 v[116:119], v[156:159], v[176:179], v[116:119]
	v_mfma_f32_16x16x32_bf16 v[112:115], v[164:167], v[176:179], v[112:115]
	v_mfma_f32_16x16x32_bf16 v[100:103], v[156:159], v[184:187], v[100:103]
	v_mfma_f32_16x16x32_bf16 v[96:99], v[164:167], v[184:187], v[96:99]
	v_mfma_f32_16x16x32_bf16 v[84:87], v[156:159], v[192:195], v[84:87]
	v_mfma_f32_16x16x32_bf16 v[80:83], v[164:167], v[192:195], v[80:83]
	v_mfma_f32_16x16x32_bf16 v[72:75], v[156:159], v[200:203], v[72:75]
	v_mfma_f32_16x16x32_bf16 v[64:67], v[164:167], v[200:203], v[64:67]
	s_setprio 0
	s_barrier
	s_add_i32 s81, s62, s46
	v_lshl_add_u64 v[172:173], s[30:31], 0, v[130:131]
	s_mov_b32 m0, s81
	ds_read_b128 v[204:207], v153
	ds_read_b128 v[208:211], v153 offset:1024
	ds_read_b128 v[212:215], v153 offset:2048
	ds_read_b128 v[216:219], v153 offset:3072
	global_load_lds_dwordx4 v[172:173], off
	v_lshl_add_u64 v[220:221], s[30:31], 0, v[134:135]
	s_add_i32 m0, s81, 0x2000
	s_nop 0
	global_load_lds_dwordx4 v[220:221], off
	s_barrier
	s_waitcnt lgkmcnt(0)
	s_setprio 1
	s_waitcnt lgkmcnt(0)
	v_mfma_f32_16x16x32_bf16 v[124:127], v[204:207], v[168:171], v[124:127]
	v_mfma_f32_16x16x32_bf16 v[120:123], v[212:215], v[168:171], v[120:123]
	v_mfma_f32_16x16x32_bf16 v[108:111], v[204:207], v[180:183], v[108:111]
	v_mfma_f32_16x16x32_bf16 v[104:107], v[212:215], v[180:183], v[104:107]
	v_mfma_f32_16x16x32_bf16 v[92:95], v[204:207], v[188:191], v[92:95]
	v_mfma_f32_16x16x32_bf16 v[88:91], v[212:215], v[188:191], v[88:91]
	v_mfma_f32_16x16x32_bf16 v[76:79], v[204:207], v[196:199], v[76:79]
	v_mfma_f32_16x16x32_bf16 v[68:71], v[212:215], v[196:199], v[68:71]
	v_mfma_f32_16x16x32_bf16 v[124:127], v[208:211], v[176:179], v[124:127]
	v_mfma_f32_16x16x32_bf16 v[120:123], v[216:219], v[176:179], v[120:123]
	v_mfma_f32_16x16x32_bf16 v[108:111], v[208:211], v[184:187], v[108:111]
	v_mfma_f32_16x16x32_bf16 v[104:107], v[216:219], v[184:187], v[104:107]
	v_mfma_f32_16x16x32_bf16 v[92:95], v[208:211], v[192:195], v[92:95]
	v_mfma_f32_16x16x32_bf16 v[88:91], v[216:219], v[192:195], v[88:91]
	v_mfma_f32_16x16x32_bf16 v[76:79], v[208:211], v[200:203], v[76:79]
	v_mfma_f32_16x16x32_bf16 v[68:71], v[216:219], v[200:203], v[68:71]
	s_setprio 0
	s_mov_b32 m0, s27
	v_lshl_add_u64 v[222:223], s[34:35], 0, v[128:129]
	s_barrier
	ds_read_b128 v[168:171], v152 offset:16384
	ds_read_b128 v[176:179], v152 offset:17408
	ds_read_b128 v[180:183], v152 offset:18432
	ds_read_b128 v[184:187], v152 offset:19456
	ds_read_b128 v[188:191], v152 offset:20480
	ds_read_b128 v[192:195], v152 offset:21504
	ds_read_b128 v[196:199], v152 offset:22528
	ds_read_b128 v[200:203], v152 offset:23552
	global_load_lds_dwordx4 v[222:223], off
	v_lshl_add_u64 v[224:225], s[34:35], 0, v[132:133]
	s_mov_b32 m0, s47
	s_nop 0
	global_load_lds_dwordx4 v[224:225], off
	s_barrier
	s_waitcnt lgkmcnt(0)
	s_setprio 1
	s_waitcnt lgkmcnt(0)
	v_mfma_f32_16x16x32_bf16 v[56:59], v[144:147], v[168:171], v[56:59]
	v_mfma_f32_16x16x32_bf16 v[48:51], v[160:163], v[168:171], v[48:51]
	v_mfma_f32_16x16x32_bf16 v[40:43], v[144:147], v[180:183], v[40:43]
	v_mfma_f32_16x16x32_bf16 v[32:35], v[160:163], v[180:183], v[32:35]
	v_mfma_f32_16x16x32_bf16 v[24:27], v[144:147], v[188:191], v[24:27]
	v_mfma_f32_16x16x32_bf16 v[16:19], v[160:163], v[188:191], v[16:19]
	v_mfma_f32_16x16x32_bf16 v[8:11], v[144:147], v[196:199], v[8:11]
	v_mfma_f32_16x16x32_bf16 v[0:3], v[160:163], v[196:199], v[0:3]
	v_mfma_f32_16x16x32_bf16 v[56:59], v[156:159], v[176:179], v[56:59]
	v_mfma_f32_16x16x32_bf16 v[48:51], v[164:167], v[176:179], v[48:51]
	v_mfma_f32_16x16x32_bf16 v[40:43], v[156:159], v[184:187], v[40:43]
	v_mfma_f32_16x16x32_bf16 v[32:35], v[164:167], v[184:187], v[32:35]
	v_mfma_f32_16x16x32_bf16 v[24:27], v[156:159], v[192:195], v[24:27]
	v_mfma_f32_16x16x32_bf16 v[16:19], v[164:167], v[192:195], v[16:19]
	v_mfma_f32_16x16x32_bf16 v[8:11], v[156:159], v[200:203], v[8:11]
	v_mfma_f32_16x16x32_bf16 v[0:3], v[164:167], v[200:203], v[0:3]
	s_setprio 0
	s_barrier
	s_add_u32 s82, s30, 0x40000
	s_addc_u32 s83, s31, 0
	s_add_i32 s81, s63, s46
	v_lshl_add_u64 v[144:145], s[82:83], 0, v[130:131]
	s_mov_b32 m0, s81
	s_nop 0
	global_load_lds_dwordx4 v[144:145], off
	v_lshl_add_u64 v[144:145], s[82:83], 0, v[134:135]
	s_add_i32 m0, s81, 0x2000
	s_nop 0
	global_load_lds_dwordx4 v[144:145], off
	s_waitcnt vmcnt(6)
	s_barrier
	s_setprio 1
	v_mfma_f32_16x16x32_bf16 v[60:63], v[204:207], v[168:171], v[60:63]
	v_mfma_f32_16x16x32_bf16 v[52:55], v[212:215], v[168:171], v[52:55]
	v_mfma_f32_16x16x32_bf16 v[44:47], v[204:207], v[180:183], v[44:47]
	v_mfma_f32_16x16x32_bf16 v[36:39], v[212:215], v[180:183], v[36:39]
	v_mfma_f32_16x16x32_bf16 v[28:31], v[204:207], v[188:191], v[28:31]
	v_mfma_f32_16x16x32_bf16 v[20:23], v[212:215], v[188:191], v[20:23]
	v_mfma_f32_16x16x32_bf16 v[12:15], v[204:207], v[196:199], v[12:15]
	v_mfma_f32_16x16x32_bf16 v[4:7], v[212:215], v[196:199], v[4:7]
	v_mfma_f32_16x16x32_bf16 v[60:63], v[208:211], v[176:179], v[60:63]
	v_mfma_f32_16x16x32_bf16 v[52:55], v[216:219], v[176:179], v[52:55]
	v_mfma_f32_16x16x32_bf16 v[44:47], v[208:211], v[184:187], v[44:47]
	v_mfma_f32_16x16x32_bf16 v[36:39], v[216:219], v[184:187], v[36:39]
	v_mfma_f32_16x16x32_bf16 v[28:31], v[208:211], v[192:195], v[28:31]
	v_mfma_f32_16x16x32_bf16 v[20:23], v[216:219], v[192:195], v[20:23]
	v_mfma_f32_16x16x32_bf16 v[12:15], v[208:211], v[200:203], v[12:15]
	v_mfma_f32_16x16x32_bf16 v[4:7], v[216:219], v[200:203], v[4:7]
	s_setprio 0
	s_add_i32 s81, 0, 0x18000
	v_add_u32_e32 v155, s81, v149
	s_barrier
	ds_read_b128 v[144:147], v155
	ds_read_b128 v[156:159], v155 offset:1024
	ds_read_b128 v[160:163], v155 offset:2048
	ds_read_b128 v[164:167], v155 offset:3072
	s_add_u32 s34, s34, 0x40000
	s_addc_u32 s35, s35, 0
	s_mov_b32 m0, s52
	v_lshl_add_u64 v[204:205], s[34:35], 0, v[128:129]
	ds_read_b128 v[168:171], v152 offset:32768
	ds_read_b128 v[176:179], v152 offset:33792
	ds_read_b128 v[180:183], v152 offset:34816
	ds_read_b128 v[184:187], v152 offset:35840
	ds_read_b128 v[188:191], v152 offset:36864
	ds_read_b128 v[192:195], v152 offset:37888
	ds_read_b128 v[196:199], v152 offset:38912
	ds_read_b128 v[200:203], v152 offset:39936
	global_load_lds_dwordx4 v[204:205], off
	v_lshl_add_u64 v[204:205], s[34:35], 0, v[132:133]
	s_mov_b32 m0, s53
	s_nop 0
	global_load_lds_dwordx4 v[204:205], off
	s_waitcnt lgkmcnt(8)
	s_barrier
	s_waitcnt lgkmcnt(0)
	s_setprio 1
	s_waitcnt lgkmcnt(0)
	v_mfma_f32_16x16x32_bf16 v[116:119], v[144:147], v[168:171], v[116:119]
	v_mfma_f32_16x16x32_bf16 v[112:115], v[160:163], v[168:171], v[112:115]
	v_mfma_f32_16x16x32_bf16 v[100:103], v[144:147], v[180:183], v[100:103]
	v_mfma_f32_16x16x32_bf16 v[96:99], v[160:163], v[180:183], v[96:99]
	v_mfma_f32_16x16x32_bf16 v[84:87], v[144:147], v[188:191], v[84:87]
	v_mfma_f32_16x16x32_bf16 v[80:83], v[160:163], v[188:191], v[80:83]
	v_mfma_f32_16x16x32_bf16 v[72:75], v[144:147], v[196:199], v[72:75]
	v_mfma_f32_16x16x32_bf16 v[64:67], v[160:163], v[196:199], v[64:67]
	v_mfma_f32_16x16x32_bf16 v[116:119], v[156:159], v[176:179], v[116:119]
	v_mfma_f32_16x16x32_bf16 v[112:115], v[164:167], v[176:179], v[112:115]
	v_mfma_f32_16x16x32_bf16 v[100:103], v[156:159], v[184:187], v[100:103]
	v_mfma_f32_16x16x32_bf16 v[96:99], v[164:167], v[184:187], v[96:99]
	v_mfma_f32_16x16x32_bf16 v[84:87], v[156:159], v[192:195], v[84:87]
	v_mfma_f32_16x16x32_bf16 v[80:83], v[164:167], v[192:195], v[80:83]
	v_mfma_f32_16x16x32_bf16 v[72:75], v[156:159], v[200:203], v[72:75]
	v_mfma_f32_16x16x32_bf16 v[64:67], v[164:167], v[200:203], v[64:67]
	s_setprio 0
	s_barrier
	s_add_i32 s34, 0, 0x1c000
	s_add_i32 s35, s81, s46
	v_add_u32_e32 v155, s34, v149
	v_lshl_add_u64 v[172:173], v[172:173], 0, s[4:5]
	s_mov_b32 m0, s35
	ds_read_b128 v[204:207], v155
	ds_read_b128 v[208:211], v155 offset:1024
	ds_read_b128 v[212:215], v155 offset:2048
	ds_read_b128 v[216:219], v155 offset:3072
	global_load_lds_dwordx4 v[172:173], off
	v_lshl_add_u64 v[172:173], v[220:221], 0, s[4:5]
	s_add_i32 m0, s35, 0x2000
	s_nop 0
	global_load_lds_dwordx4 v[172:173], off
	s_barrier
	s_waitcnt lgkmcnt(0)
	s_setprio 1
	s_waitcnt lgkmcnt(0)
	v_mfma_f32_16x16x32_bf16 v[124:127], v[204:207], v[168:171], v[124:127]
	v_mfma_f32_16x16x32_bf16 v[120:123], v[212:215], v[168:171], v[120:123]
	v_mfma_f32_16x16x32_bf16 v[108:111], v[204:207], v[180:183], v[108:111]
	v_mfma_f32_16x16x32_bf16 v[104:107], v[212:215], v[180:183], v[104:107]
	v_mfma_f32_16x16x32_bf16 v[92:95], v[204:207], v[188:191], v[92:95]
	v_mfma_f32_16x16x32_bf16 v[88:91], v[212:215], v[188:191], v[88:91]
	v_mfma_f32_16x16x32_bf16 v[76:79], v[204:207], v[196:199], v[76:79]
	v_mfma_f32_16x16x32_bf16 v[68:71], v[212:215], v[196:199], v[68:71]
	v_mfma_f32_16x16x32_bf16 v[124:127], v[208:211], v[176:179], v[124:127]
	v_mfma_f32_16x16x32_bf16 v[120:123], v[216:219], v[176:179], v[120:123]
	v_mfma_f32_16x16x32_bf16 v[108:111], v[208:211], v[184:187], v[108:111]
	v_mfma_f32_16x16x32_bf16 v[104:107], v[216:219], v[184:187], v[104:107]
	v_mfma_f32_16x16x32_bf16 v[92:95], v[208:211], v[192:195], v[92:95]
	v_mfma_f32_16x16x32_bf16 v[88:91], v[216:219], v[192:195], v[88:91]
	v_mfma_f32_16x16x32_bf16 v[76:79], v[208:211], v[200:203], v[76:79]
	v_mfma_f32_16x16x32_bf16 v[68:71], v[216:219], v[200:203], v[68:71]
	s_setprio 0
	s_mov_b32 m0, s55
	v_lshl_add_u64 v[172:173], v[222:223], 0, s[4:5]
	s_barrier
	ds_read_b128 v[168:171], v152 offset:49152
	ds_read_b128 v[176:179], v152 offset:50176
	ds_read_b128 v[180:183], v152 offset:51200
	ds_read_b128 v[184:187], v152 offset:52224
	ds_read_b128 v[188:191], v152 offset:53248
	ds_read_b128 v[192:195], v152 offset:54272
	ds_read_b128 v[196:199], v152 offset:55296
	ds_read_b128 v[200:203], v152 offset:56320
	global_load_lds_dwordx4 v[172:173], off
	v_lshl_add_u64 v[172:173], v[224:225], 0, s[4:5]
	s_mov_b32 m0, s56
	s_nop 0
	global_load_lds_dwordx4 v[172:173], off
	s_barrier
	s_waitcnt lgkmcnt(0)
	s_setprio 1
	s_waitcnt lgkmcnt(0)
	v_mfma_f32_16x16x32_bf16 v[56:59], v[144:147], v[168:171], v[56:59]
	v_mfma_f32_16x16x32_bf16 v[48:51], v[160:163], v[168:171], v[48:51]
	v_mfma_f32_16x16x32_bf16 v[40:43], v[144:147], v[180:183], v[40:43]
	v_mfma_f32_16x16x32_bf16 v[32:35], v[160:163], v[180:183], v[32:35]
	v_mfma_f32_16x16x32_bf16 v[24:27], v[144:147], v[188:191], v[24:27]
	v_mfma_f32_16x16x32_bf16 v[16:19], v[160:163], v[188:191], v[16:19]
	v_mfma_f32_16x16x32_bf16 v[8:11], v[144:147], v[196:199], v[8:11]
	v_mfma_f32_16x16x32_bf16 v[0:3], v[160:163], v[196:199], v[0:3]
	v_mfma_f32_16x16x32_bf16 v[56:59], v[156:159], v[176:179], v[56:59]
	v_mfma_f32_16x16x32_bf16 v[48:51], v[164:167], v[176:179], v[48:51]
	v_mfma_f32_16x16x32_bf16 v[40:43], v[156:159], v[184:187], v[40:43]
	v_mfma_f32_16x16x32_bf16 v[32:35], v[164:167], v[184:187], v[32:35]
	v_mfma_f32_16x16x32_bf16 v[24:27], v[156:159], v[192:195], v[24:27]
	v_mfma_f32_16x16x32_bf16 v[16:19], v[164:167], v[192:195], v[16:19]
	v_mfma_f32_16x16x32_bf16 v[8:11], v[156:159], v[200:203], v[8:11]
	v_mfma_f32_16x16x32_bf16 v[0:3], v[164:167], v[200:203], v[0:3]
	s_setprio 0
	s_barrier
	s_add_u32 s30, s30, 0x40080
	s_addc_u32 s31, s31, 0
	s_add_i32 s34, s34, s46
	v_lshl_add_u64 v[144:145], s[30:31], 0, v[130:131]
	s_mov_b32 m0, s34
	s_nop 0
	global_load_lds_dwordx4 v[144:145], off
	v_lshl_add_u64 v[144:145], s[30:31], 0, v[134:135]
	s_add_i32 m0, s34, 0x2000
	s_nop 0
	global_load_lds_dwordx4 v[144:145], off
	s_waitcnt vmcnt(6)
	s_barrier
	s_setprio 1
	v_mfma_f32_16x16x32_bf16 v[60:63], v[204:207], v[168:171], v[60:63]
	v_mfma_f32_16x16x32_bf16 v[52:55], v[212:215], v[168:171], v[52:55]
	v_mfma_f32_16x16x32_bf16 v[44:47], v[204:207], v[180:183], v[44:47]
	v_mfma_f32_16x16x32_bf16 v[36:39], v[212:215], v[180:183], v[36:39]
	v_mfma_f32_16x16x32_bf16 v[28:31], v[204:207], v[188:191], v[28:31]
	v_mfma_f32_16x16x32_bf16 v[20:23], v[212:215], v[188:191], v[20:23]
	v_mfma_f32_16x16x32_bf16 v[12:15], v[204:207], v[196:199], v[12:15]
	v_mfma_f32_16x16x32_bf16 v[4:7], v[212:215], v[196:199], v[4:7]
	v_mfma_f32_16x16x32_bf16 v[60:63], v[208:211], v[176:179], v[60:63]
	v_mfma_f32_16x16x32_bf16 v[52:55], v[216:219], v[176:179], v[52:55]
	v_mfma_f32_16x16x32_bf16 v[44:47], v[208:211], v[184:187], v[44:47]
	v_mfma_f32_16x16x32_bf16 v[36:39], v[216:219], v[184:187], v[36:39]
	v_mfma_f32_16x16x32_bf16 v[28:31], v[208:211], v[192:195], v[28:31]
	v_mfma_f32_16x16x32_bf16 v[20:23], v[216:219], v[192:195], v[20:23]
	v_mfma_f32_16x16x32_bf16 v[12:15], v[208:211], v[200:203], v[12:15]
	v_mfma_f32_16x16x32_bf16 v[4:7], v[216:219], v[200:203], v[4:7]
	s_setprio 0
	s_add_i32 s80, s80, 2
	s_add_u32 s28, s28, 0x100
	s_addc_u32 s29, s29, 0
	s_add_u32 s69, s69, 0x100
	s_addc_u32 s77, s77, 0
	s_cmp_gt_u32 s80, 13
	s_barrier
	s_cbranch_scc0 .LBB0_196
	v_lshl_add_u32 v144, s26, 8, v148
	v_ashrrev_i32_e32 v145, 31, v144
	v_lshl_add_u64 v[146:147], v[144:145], 2, s[6:7]
	global_load_dword v145, v[146:147], off
	global_load_dword v247, v[146:147], off offset:64
	global_load_dword v248, v[146:147], off offset:128
	global_load_dword v249, v[146:147], off offset:192
	global_load_dword v250, v[146:147], off offset:512
	global_load_dword v251, v[146:147], off offset:576
	global_load_dword v252, v[146:147], off offset:640
	global_load_dword v253, v[146:147], off offset:704
	v_lshl_or_b32 v156, s66, 7, v150
	v_mov_b32_e32 v161, v114
	v_mov_b32_e32 v114, v123
	v_mov_b32_e32 v158, v124
	v_mov_b32_e32 v159, v116
	v_mov_b32_e32 v116, v125
	v_mov_b32_e32 v124, v126
	v_mov_b32_e32 v125, v118
	v_mov_b32_e32 v118, v127
	v_mov_b32_e32 v126, v120
	v_mov_b32_e32 v127, v112
	v_mov_b32_e32 v112, v121
	v_mov_b32_e32 v160, v122
	v_mov_b64_e32 v[120:121], s[44:45]
	v_ashrrev_i32_e32 v157, 31, v156
	v_or_b32_e32 v164, 16, v144
	v_mad_i64_i32 v[162:163], s[28:29], v144, s65, v[120:121]
	v_lshlrev_b64 v[122:123], 1, v[156:157]
	v_ashrrev_i32_e32 v165, 31, v164
	v_lshl_add_u64 v[156:157], v[162:163], 0, v[122:123]
	v_lshl_add_u64 v[162:163], v[164:165], 2, s[6:7]
	s_mov_b32 s66, s10
	s_mov_b32 s26, s12
	s_mov_b64 s[30:31], s[24:25]
	s_waitcnt vmcnt(7)
	v_fmamk_f32 v145, v145, 0x3a800000, v154
	v_mul_f32_e32 v155, 0x4b800000, v145
	v_cmp_gt_f32_e32 vcc, s64, v145
	s_nop 1
	v_cndmask_b32_e32 v145, v145, v155, vcc
	v_rsq_f32_e32 v145, v145
	s_nop 0
	v_mul_f32_e32 v155, 0x45800000, v145
	v_cndmask_b32_e32 v166, v145, v155, vcc
	v_pk_mul_f32 v[114:115], v[114:115], v[166:167] op_sel_hi:[1,0]
	v_pk_mul_f32 v[158:159], v[158:159], v[166:167] op_sel_hi:[1,0]
	v_pk_mul_f32 v[116:117], v[116:117], v[166:167] op_sel_hi:[1,0]
	v_pk_mul_f32 v[124:125], v[124:125], v[166:167] op_sel_hi:[1,0]
	v_pk_mul_f32 v[118:119], v[118:119], v[166:167] op_sel_hi:[1,0]
	v_pk_mul_f32 v[126:127], v[126:127], v[166:167] op_sel_hi:[1,0]
	v_pk_mul_f32 v[112:113], v[112:113], v[166:167] op_sel_hi:[1,0]
	v_pk_mul_f32 v[160:161], v[160:161], v[166:167] op_sel_hi:[1,0]
	v_mul_f32_e32 v170, 0xbfb8aa3b, v115
	v_mul_f32_e32 v145, 0xbfb8aa3b, v159
	v_mul_f32_e32 v155, 0xbfb8aa3b, v117
	v_mul_f32_e32 v165, 0xbfb8aa3b, v125
	v_mul_f32_e32 v166, 0xbfb8aa3b, v119
	v_mul_f32_e32 v167, 0xbfb8aa3b, v127
	v_mul_f32_e32 v168, 0xbfb8aa3b, v113
	v_mul_f32_e32 v169, 0xbfb8aa3b, v161
	v_exp_f32_e32 v170, v170
	v_exp_f32_e32 v145, v145
	v_exp_f32_e32 v155, v155
	v_exp_f32_e32 v165, v165
	v_exp_f32_e32 v166, v166
	v_exp_f32_e32 v167, v167
	v_exp_f32_e32 v168, v168
	v_exp_f32_e32 v169, v169
	v_add_f32_e32 v170, 1.0, v170
	v_add_f32_e32 v145, 1.0, v145
	v_add_f32_e32 v155, 1.0, v155
	v_add_f32_e32 v165, 1.0, v165
	v_add_f32_e32 v166, 1.0, v166
	v_add_f32_e32 v167, 1.0, v167
	v_add_f32_e32 v168, 1.0, v168
	v_add_f32_e32 v169, 1.0, v169
	v_rcp_f32_e32 v170, v170
	v_rcp_f32_e32 v145, v145
	v_rcp_f32_e32 v155, v155
	v_rcp_f32_e32 v165, v165
	v_rcp_f32_e32 v166, v166
	v_rcp_f32_e32 v167, v167
	v_rcp_f32_e32 v168, v168
	v_rcp_f32_e32 v169, v169
	v_mul_f32_e32 v115, v115, v170
	v_mul_f32_e32 v145, v159, v145
	v_mul_f32_e32 v117, v117, v155
	v_mul_f32_e32 v125, v125, v165
	v_mul_f32_e32 v119, v119, v166
	v_mul_f32_e32 v127, v127, v167
	v_mul_f32_e32 v113, v113, v168
	v_mul_f32_e32 v155, v161, v169
	v_mul_f32_e32 v115, v114, v115
	v_mul_f32_e32 v145, v158, v145
	v_mul_f32_e32 v116, v116, v117
	v_mul_f32_e32 v117, v124, v125
	v_mul_f32_e32 v118, v118, v119
	v_mul_f32_e32 v119, v126, v127
	v_mul_f32_e32 v124, v112, v113
	v_mul_f32_e32 v125, v160, v155
	v_cvt_pk_bf16_f32 v112, v145, v116
	v_cvt_pk_bf16_f32 v113, v117, v118
	v_cvt_pk_bf16_f32 v114, v119, v124
	v_cvt_pk_bf16_f32 v115, v125, v115
	global_store_dwordx4 v[156:157], v[112:115], off
	s_nop 0
	v_mov_b32_e32 v113, v100
	v_mov_b32_e32 v100, v109
	v_mov_b32_e32 v109, v102
	v_mov_b32_e32 v102, v111
	v_mov_b32_e32 v111, v96
	v_mov_b32_e32 v96, v105
	v_mov_b32_e32 v105, v98
	v_mov_b32_e32 v98, v107
	v_mov_b32_e32 v112, v108
	v_mov_b32_e32 v108, v110
	v_mov_b32_e32 v110, v104
	v_mov_b32_e32 v104, v106
	v_or_b32_e32 v106, 32, v144
	v_mad_i64_i32 v[114:115], s[28:29], v164, s65, v[120:121]
	v_lshl_add_u64 v[114:115], v[114:115], 0, v[122:123]
	s_waitcnt vmcnt(7)
	v_mov_b32_e32 v116, v247
	v_fmamk_f32 v107, v116, 0x3a800000, v154
	v_mul_f32_e32 v116, 0x4b800000, v107
	v_cmp_gt_f32_e32 vcc, s64, v107
	s_nop 1
	v_cndmask_b32_e32 v107, v107, v116, vcc
	v_rsq_f32_e32 v118, v107
	v_ashrrev_i32_e32 v107, 31, v106
	v_lshl_add_u64 v[116:117], v[106:107], 2, s[6:7]
	v_mul_f32_e32 v107, 0x45800000, v118
	v_cndmask_b32_e32 v118, v118, v107, vcc
	v_pk_mul_f32 v[98:99], v[98:99], v[118:119] op_sel_hi:[1,0]
	v_pk_mul_f32 v[112:113], v[112:113], v[118:119] op_sel_hi:[1,0]
	v_pk_mul_f32 v[100:101], v[100:101], v[118:119] op_sel_hi:[1,0]
	v_pk_mul_f32 v[108:109], v[108:109], v[118:119] op_sel_hi:[1,0]
	v_pk_mul_f32 v[102:103], v[102:103], v[118:119] op_sel_hi:[1,0]
	v_pk_mul_f32 v[110:111], v[110:111], v[118:119] op_sel_hi:[1,0]
	v_pk_mul_f32 v[96:97], v[96:97], v[118:119] op_sel_hi:[1,0]
	v_pk_mul_f32 v[104:105], v[104:105], v[118:119] op_sel_hi:[1,0]
	v_mul_f32_e32 v145, 0xbfb8aa3b, v99
	v_mul_f32_e32 v107, 0xbfb8aa3b, v113
	v_mul_f32_e32 v118, 0xbfb8aa3b, v101
	v_mul_f32_e32 v119, 0xbfb8aa3b, v109
	v_mul_f32_e32 v124, 0xbfb8aa3b, v103
	v_mul_f32_e32 v125, 0xbfb8aa3b, v111
	v_mul_f32_e32 v126, 0xbfb8aa3b, v97
	v_mul_f32_e32 v127, 0xbfb8aa3b, v105
	v_exp_f32_e32 v145, v145
	v_exp_f32_e32 v107, v107
	v_exp_f32_e32 v118, v118
	v_exp_f32_e32 v119, v119
	v_exp_f32_e32 v124, v124
	v_exp_f32_e32 v125, v125
	v_exp_f32_e32 v126, v126
	v_exp_f32_e32 v127, v127
	v_add_f32_e32 v145, 1.0, v145
	v_add_f32_e32 v107, 1.0, v107
	v_add_f32_e32 v118, 1.0, v118
	v_add_f32_e32 v119, 1.0, v119
	v_add_f32_e32 v124, 1.0, v124
	v_add_f32_e32 v125, 1.0, v125
	v_add_f32_e32 v126, 1.0, v126
	v_add_f32_e32 v127, 1.0, v127
	v_rcp_f32_e32 v145, v145
	v_rcp_f32_e32 v107, v107
	v_rcp_f32_e32 v118, v118
	v_rcp_f32_e32 v119, v119
	v_rcp_f32_e32 v124, v124
	v_rcp_f32_e32 v125, v125
	v_rcp_f32_e32 v126, v126
	v_rcp_f32_e32 v127, v127
	v_mul_f32_e32 v99, v99, v145
	v_mul_f32_e32 v107, v113, v107
	v_mul_f32_e32 v101, v101, v118
	v_mul_f32_e32 v109, v109, v119
	v_mul_f32_e32 v103, v103, v124
	v_mul_f32_e32 v111, v111, v125
	v_mul_f32_e32 v97, v97, v126
	v_mul_f32_e32 v105, v105, v127
	v_mul_f32_e32 v99, v98, v99
	v_mul_f32_e32 v107, v112, v107
	v_mul_f32_e32 v100, v100, v101
	v_mul_f32_e32 v101, v108, v109
	v_mul_f32_e32 v102, v102, v103
	v_mul_f32_e32 v103, v110, v111
	v_mul_f32_e32 v108, v96, v97
	v_mul_f32_e32 v104, v104, v105
	v_cvt_pk_bf16_f32 v96, v107, v100
	v_cvt_pk_bf16_f32 v97, v101, v102
	v_cvt_pk_bf16_f32 v98, v103, v108
	v_cvt_pk_bf16_f32 v99, v104, v99
	global_store_dwordx4 v[114:115], v[96:99], off
	s_nop 0
	v_mov_b32_e32 v97, v84
	v_mov_b32_e32 v84, v93
	v_mov_b32_e32 v93, v86
	v_mov_b32_e32 v86, v95
	v_mov_b32_e32 v95, v80
	v_mov_b32_e32 v80, v89
	v_mov_b32_e32 v89, v82
	v_mov_b32_e32 v82, v91
	v_mov_b32_e32 v96, v92
	v_mov_b32_e32 v92, v94
	v_mov_b32_e32 v94, v88
	v_mov_b32_e32 v88, v90
	v_or_b32_e32 v90, 48, v144
	v_mad_i64_i32 v[98:99], s[28:29], v106, s65, v[120:121]
	v_lshl_add_u64 v[98:99], v[98:99], 0, v[122:123]
	s_waitcnt vmcnt(7)
	v_mov_b32_e32 v100, v248
	v_fmamk_f32 v91, v100, 0x3a800000, v154
	v_mul_f32_e32 v100, 0x4b800000, v91
	v_cmp_gt_f32_e32 vcc, s64, v91
	s_nop 1
	v_cndmask_b32_e32 v91, v91, v100, vcc
	v_rsq_f32_e32 v102, v91
	v_ashrrev_i32_e32 v91, 31, v90
	v_lshl_add_u64 v[100:101], v[90:91], 2, s[6:7]
	v_mul_f32_e32 v91, 0x45800000, v102
	v_cndmask_b32_e32 v102, v102, v91, vcc
	v_pk_mul_f32 v[82:83], v[82:83], v[102:103] op_sel_hi:[1,0]
	v_pk_mul_f32 v[96:97], v[96:97], v[102:103] op_sel_hi:[1,0]
	v_pk_mul_f32 v[84:85], v[84:85], v[102:103] op_sel_hi:[1,0]
	v_pk_mul_f32 v[92:93], v[92:93], v[102:103] op_sel_hi:[1,0]
	v_pk_mul_f32 v[86:87], v[86:87], v[102:103] op_sel_hi:[1,0]
	v_pk_mul_f32 v[94:95], v[94:95], v[102:103] op_sel_hi:[1,0]
	v_pk_mul_f32 v[80:81], v[80:81], v[102:103] op_sel_hi:[1,0]
	v_pk_mul_f32 v[88:89], v[88:89], v[102:103] op_sel_hi:[1,0]
	v_mul_f32_e32 v108, 0xbfb8aa3b, v83
	v_mul_f32_e32 v91, 0xbfb8aa3b, v97
	v_mul_f32_e32 v102, 0xbfb8aa3b, v85
	v_mul_f32_e32 v103, 0xbfb8aa3b, v93
	v_mul_f32_e32 v104, 0xbfb8aa3b, v87
	v_mul_f32_e32 v105, 0xbfb8aa3b, v95
	v_mul_f32_e32 v106, 0xbfb8aa3b, v81
	v_mul_f32_e32 v107, 0xbfb8aa3b, v89
	v_exp_f32_e32 v108, v108
	v_exp_f32_e32 v91, v91
	v_exp_f32_e32 v102, v102
	v_exp_f32_e32 v103, v103
	v_exp_f32_e32 v104, v104
	v_exp_f32_e32 v105, v105
	v_exp_f32_e32 v106, v106
	v_exp_f32_e32 v107, v107
	v_add_f32_e32 v108, 1.0, v108
	v_add_f32_e32 v91, 1.0, v91
	v_add_f32_e32 v102, 1.0, v102
	v_add_f32_e32 v103, 1.0, v103
	v_add_f32_e32 v104, 1.0, v104
	v_add_f32_e32 v105, 1.0, v105
	v_add_f32_e32 v106, 1.0, v106
	v_add_f32_e32 v107, 1.0, v107
	v_rcp_f32_e32 v108, v108
	v_rcp_f32_e32 v91, v91
	v_rcp_f32_e32 v102, v102
	v_rcp_f32_e32 v103, v103
	v_rcp_f32_e32 v104, v104
	v_rcp_f32_e32 v105, v105
	v_rcp_f32_e32 v106, v106
	v_rcp_f32_e32 v107, v107
	v_mul_f32_e32 v83, v83, v108
	v_mul_f32_e32 v91, v97, v91
	v_mul_f32_e32 v85, v85, v102
	v_mul_f32_e32 v93, v93, v103
	v_mul_f32_e32 v87, v87, v104
	v_mul_f32_e32 v95, v95, v105
	v_mul_f32_e32 v81, v81, v106
	v_mul_f32_e32 v89, v89, v107
	v_mul_f32_e32 v83, v82, v83
	v_mul_f32_e32 v91, v96, v91
	v_mul_f32_e32 v84, v84, v85
	v_mul_f32_e32 v85, v92, v93
	v_mul_f32_e32 v86, v86, v87
	v_mul_f32_e32 v87, v94, v95
	v_mul_f32_e32 v92, v80, v81
	v_mul_f32_e32 v88, v88, v89
	v_cvt_pk_bf16_f32 v80, v91, v84
	v_cvt_pk_bf16_f32 v81, v85, v86
	v_cvt_pk_bf16_f32 v82, v87, v92
	v_cvt_pk_bf16_f32 v83, v88, v83
	global_store_dwordx4 v[98:99], v[80:83], off
	s_nop 0
	v_mov_b32_e32 v80, v76
	v_mov_b32_e32 v76, v78
	v_mov_b32_e32 v78, v68
	v_mov_b32_e32 v68, v70
	v_mov_b32_e32 v81, v72
	v_mov_b32_e32 v72, v77
	v_mov_b32_e32 v77, v74
	v_mov_b32_e32 v74, v79
	v_mov_b32_e32 v79, v64
	v_mov_b32_e32 v64, v69
	v_mov_b32_e32 v69, v66
	v_mov_b32_e32 v66, v71
	s_waitcnt vmcnt(7)
	v_mov_b32_e32 v82, v249
	v_fmamk_f32 v70, v82, 0x3a800000, v154
	v_mul_f32_e32 v71, 0x4b800000, v70
	v_cmp_gt_f32_e32 vcc, s64, v70
	s_nop 1
	v_cndmask_b32_e32 v70, v70, v71, vcc
	v_rsq_f32_e32 v82, v70
	v_mad_i64_i32 v[70:71], s[28:29], v90, s65, v[120:121]
	v_lshl_add_u64 v[70:71], v[70:71], 0, v[122:123]
	v_mul_f32_e32 v83, 0x45800000, v82
	v_cndmask_b32_e32 v82, v82, v83, vcc
	v_pk_mul_f32 v[66:67], v[66:67], v[82:83] op_sel_hi:[1,0]
	v_pk_mul_f32 v[80:81], v[80:81], v[82:83] op_sel_hi:[1,0]
	v_pk_mul_f32 v[72:73], v[72:73], v[82:83] op_sel_hi:[1,0]
	v_pk_mul_f32 v[76:77], v[76:77], v[82:83] op_sel_hi:[1,0]
	v_pk_mul_f32 v[74:75], v[74:75], v[82:83] op_sel_hi:[1,0]
	v_pk_mul_f32 v[78:79], v[78:79], v[82:83] op_sel_hi:[1,0]
	v_pk_mul_f32 v[64:65], v[64:65], v[82:83] op_sel_hi:[1,0]
	v_pk_mul_f32 v[68:69], v[68:69], v[82:83] op_sel_hi:[1,0]
	v_mul_f32_e32 v89, 0xbfb8aa3b, v67
	v_mul_f32_e32 v82, 0xbfb8aa3b, v81
	v_mul_f32_e32 v83, 0xbfb8aa3b, v73
	v_mul_f32_e32 v84, 0xbfb8aa3b, v77
	v_mul_f32_e32 v85, 0xbfb8aa3b, v75
	v_mul_f32_e32 v86, 0xbfb8aa3b, v79
	v_mul_f32_e32 v87, 0xbfb8aa3b, v65
	v_mul_f32_e32 v88, 0xbfb8aa3b, v69
	v_exp_f32_e32 v89, v89
	v_exp_f32_e32 v82, v82
	v_exp_f32_e32 v83, v83
	v_exp_f32_e32 v84, v84
	v_exp_f32_e32 v85, v85
	v_exp_f32_e32 v86, v86
	v_exp_f32_e32 v87, v87
	v_exp_f32_e32 v88, v88
	v_add_f32_e32 v89, 1.0, v89
	v_add_f32_e32 v82, 1.0, v82
	v_add_f32_e32 v83, 1.0, v83
	v_add_f32_e32 v84, 1.0, v84
	v_add_f32_e32 v85, 1.0, v85
	v_add_f32_e32 v86, 1.0, v86
	v_add_f32_e32 v87, 1.0, v87
	v_add_f32_e32 v88, 1.0, v88
	v_rcp_f32_e32 v89, v89
	v_rcp_f32_e32 v82, v82
	v_rcp_f32_e32 v83, v83
	v_rcp_f32_e32 v84, v84
	v_rcp_f32_e32 v85, v85
	v_rcp_f32_e32 v86, v86
	v_rcp_f32_e32 v87, v87
	v_rcp_f32_e32 v88, v88
	v_mul_f32_e32 v67, v67, v89
	v_mul_f32_e32 v81, v81, v82
	v_mul_f32_e32 v73, v73, v83
	v_mul_f32_e32 v77, v77, v84
	v_mul_f32_e32 v75, v75, v85
	v_mul_f32_e32 v79, v79, v86
	v_mul_f32_e32 v65, v65, v87
	v_mul_f32_e32 v69, v69, v88
	v_mul_f32_e32 v67, v66, v67
	v_mul_f32_e32 v80, v80, v81
	v_mul_f32_e32 v72, v72, v73
	v_mul_f32_e32 v73, v76, v77
	v_mul_f32_e32 v74, v74, v75
	v_mul_f32_e32 v75, v78, v79
	v_mul_f32_e32 v76, v64, v65
	v_mul_f32_e32 v68, v68, v69
	v_cvt_pk_bf16_f32 v64, v80, v72
	v_cvt_pk_bf16_f32 v65, v73, v74
	v_cvt_pk_bf16_f32 v66, v75, v76
	v_cvt_pk_bf16_f32 v67, v68, v67
	global_store_dwordx4 v[70:71], v[64:67], off
	s_nop 0
	v_mov_b32_e32 v65, v56
	v_mov_b32_e32 v56, v61
	v_mov_b32_e32 v61, v58
	v_mov_b32_e32 v58, v63
	v_mov_b32_e32 v63, v48
	v_mov_b32_e32 v48, v53
	v_mov_b32_e32 v53, v50
	v_mov_b32_e32 v50, v55
	v_mov_b32_e32 v64, v60
	v_mov_b32_e32 v60, v62
	v_mov_b32_e32 v62, v52
	v_mov_b32_e32 v52, v54
	v_add_u32_e32 v54, 0x80, v144
	s_waitcnt vmcnt(7)
	v_mov_b32_e32 v66, v250
	v_fmamk_f32 v55, v66, 0x3a800000, v154
	v_mul_f32_e32 v66, 0x4b800000, v55
	v_cmp_gt_f32_e32 vcc, s64, v55
	s_nop 1
	v_cndmask_b32_e32 v55, v55, v66, vcc
	v_rsq_f32_e32 v66, v55
	v_mad_i64_i32 v[54:55], s[28:29], v54, s65, v[120:121]
	v_lshl_add_u64 v[54:55], v[54:55], 0, v[122:123]
	v_mul_f32_e32 v67, 0x45800000, v66
	v_cndmask_b32_e32 v66, v66, v67, vcc
	v_pk_mul_f32 v[50:51], v[50:51], v[66:67] op_sel_hi:[1,0]
	v_pk_mul_f32 v[64:65], v[64:65], v[66:67] op_sel_hi:[1,0]
	v_pk_mul_f32 v[56:57], v[56:57], v[66:67] op_sel_hi:[1,0]
	v_pk_mul_f32 v[60:61], v[60:61], v[66:67] op_sel_hi:[1,0]
	v_pk_mul_f32 v[58:59], v[58:59], v[66:67] op_sel_hi:[1,0]
	v_pk_mul_f32 v[62:63], v[62:63], v[66:67] op_sel_hi:[1,0]
	v_pk_mul_f32 v[48:49], v[48:49], v[66:67] op_sel_hi:[1,0]
	v_pk_mul_f32 v[52:53], v[52:53], v[66:67] op_sel_hi:[1,0]
	v_mul_f32_e32 v73, 0xbfb8aa3b, v51
	v_mul_f32_e32 v66, 0xbfb8aa3b, v65
	v_mul_f32_e32 v67, 0xbfb8aa3b, v57
	v_mul_f32_e32 v68, 0xbfb8aa3b, v61
	v_mul_f32_e32 v69, 0xbfb8aa3b, v59
	v_mul_f32_e32 v70, 0xbfb8aa3b, v63
	v_mul_f32_e32 v71, 0xbfb8aa3b, v49
	v_mul_f32_e32 v72, 0xbfb8aa3b, v53
	v_exp_f32_e32 v73, v73
	v_exp_f32_e32 v66, v66
	v_exp_f32_e32 v67, v67
	v_exp_f32_e32 v68, v68
	v_exp_f32_e32 v69, v69
	v_exp_f32_e32 v70, v70
	v_exp_f32_e32 v71, v71
	v_exp_f32_e32 v72, v72
	v_add_f32_e32 v73, 1.0, v73
	v_add_f32_e32 v66, 1.0, v66
	v_add_f32_e32 v67, 1.0, v67
	v_add_f32_e32 v68, 1.0, v68
	v_add_f32_e32 v69, 1.0, v69
	v_add_f32_e32 v70, 1.0, v70
	v_add_f32_e32 v71, 1.0, v71
	v_add_f32_e32 v72, 1.0, v72
	v_rcp_f32_e32 v73, v73
	v_rcp_f32_e32 v66, v66
	v_rcp_f32_e32 v67, v67
	v_rcp_f32_e32 v68, v68
	v_rcp_f32_e32 v69, v69
	v_rcp_f32_e32 v70, v70
	v_rcp_f32_e32 v71, v71
	v_rcp_f32_e32 v72, v72
	v_mul_f32_e32 v51, v51, v73
	v_mul_f32_e32 v65, v65, v66
	v_mul_f32_e32 v57, v57, v67
	v_mul_f32_e32 v61, v61, v68
	v_mul_f32_e32 v59, v59, v69
	v_mul_f32_e32 v63, v63, v70
	v_mul_f32_e32 v49, v49, v71
	v_mul_f32_e32 v53, v53, v72
	v_mul_f32_e32 v51, v50, v51
	v_mul_f32_e32 v64, v64, v65
	v_mul_f32_e32 v56, v56, v57
	v_mul_f32_e32 v57, v60, v61
	v_mul_f32_e32 v58, v58, v59
	v_mul_f32_e32 v59, v62, v63
	v_mul_f32_e32 v60, v48, v49
	v_mul_f32_e32 v52, v52, v53
	v_cvt_pk_bf16_f32 v48, v64, v56
	v_cvt_pk_bf16_f32 v49, v57, v58
	v_cvt_pk_bf16_f32 v50, v59, v60
	v_cvt_pk_bf16_f32 v51, v52, v51
	global_store_dwordx4 v[54:55], v[48:51], off
	s_nop 0
	v_mov_b32_e32 v49, v40
	v_mov_b32_e32 v40, v45
	v_mov_b32_e32 v45, v42
	v_mov_b32_e32 v42, v47
	v_mov_b32_e32 v47, v32
	v_mov_b32_e32 v32, v37
	v_mov_b32_e32 v37, v34
	v_mov_b32_e32 v34, v39
	v_mov_b32_e32 v48, v44
	v_mov_b32_e32 v44, v46
	v_mov_b32_e32 v46, v36
	v_mov_b32_e32 v36, v38
	v_add_u32_e32 v38, 0x90, v144
	s_waitcnt vmcnt(7)
	v_mov_b32_e32 v50, v251
	v_fmamk_f32 v39, v50, 0x3a800000, v154
	v_mul_f32_e32 v50, 0x4b800000, v39
	v_cmp_gt_f32_e32 vcc, s64, v39
	s_nop 1
	v_cndmask_b32_e32 v39, v39, v50, vcc
	v_rsq_f32_e32 v50, v39
	v_mad_i64_i32 v[38:39], s[28:29], v38, s65, v[120:121]
	v_lshl_add_u64 v[38:39], v[38:39], 0, v[122:123]
	v_mul_f32_e32 v51, 0x45800000, v50
	v_cndmask_b32_e32 v50, v50, v51, vcc
	v_pk_mul_f32 v[34:35], v[34:35], v[50:51] op_sel_hi:[1,0]
	v_pk_mul_f32 v[48:49], v[48:49], v[50:51] op_sel_hi:[1,0]
	v_pk_mul_f32 v[40:41], v[40:41], v[50:51] op_sel_hi:[1,0]
	v_pk_mul_f32 v[44:45], v[44:45], v[50:51] op_sel_hi:[1,0]
	v_pk_mul_f32 v[42:43], v[42:43], v[50:51] op_sel_hi:[1,0]
	v_pk_mul_f32 v[46:47], v[46:47], v[50:51] op_sel_hi:[1,0]
	v_pk_mul_f32 v[32:33], v[32:33], v[50:51] op_sel_hi:[1,0]
	v_pk_mul_f32 v[36:37], v[36:37], v[50:51] op_sel_hi:[1,0]
	v_mul_f32_e32 v57, 0xbfb8aa3b, v35
	v_mul_f32_e32 v50, 0xbfb8aa3b, v49
	v_mul_f32_e32 v51, 0xbfb8aa3b, v41
	v_mul_f32_e32 v52, 0xbfb8aa3b, v45
	v_mul_f32_e32 v53, 0xbfb8aa3b, v43
	v_mul_f32_e32 v54, 0xbfb8aa3b, v47
	v_mul_f32_e32 v55, 0xbfb8aa3b, v33
	v_mul_f32_e32 v56, 0xbfb8aa3b, v37
	v_exp_f32_e32 v57, v57
	v_exp_f32_e32 v50, v50
	v_exp_f32_e32 v51, v51
	v_exp_f32_e32 v52, v52
	v_exp_f32_e32 v53, v53
	v_exp_f32_e32 v54, v54
	v_exp_f32_e32 v55, v55
	v_exp_f32_e32 v56, v56
	v_add_f32_e32 v57, 1.0, v57
	v_add_f32_e32 v50, 1.0, v50
	v_add_f32_e32 v51, 1.0, v51
	v_add_f32_e32 v52, 1.0, v52
	v_add_f32_e32 v53, 1.0, v53
	v_add_f32_e32 v54, 1.0, v54
	v_add_f32_e32 v55, 1.0, v55
	v_add_f32_e32 v56, 1.0, v56
	v_rcp_f32_e32 v57, v57
	v_rcp_f32_e32 v50, v50
	v_rcp_f32_e32 v51, v51
	v_rcp_f32_e32 v52, v52
	v_rcp_f32_e32 v53, v53
	v_rcp_f32_e32 v54, v54
	v_rcp_f32_e32 v55, v55
	v_rcp_f32_e32 v56, v56
	v_mul_f32_e32 v35, v35, v57
	v_mul_f32_e32 v49, v49, v50
	v_mul_f32_e32 v41, v41, v51
	v_mul_f32_e32 v45, v45, v52
	v_mul_f32_e32 v43, v43, v53
	v_mul_f32_e32 v47, v47, v54
	v_mul_f32_e32 v33, v33, v55
	v_mul_f32_e32 v37, v37, v56
	v_mul_f32_e32 v35, v34, v35
	v_mul_f32_e32 v48, v48, v49
	v_mul_f32_e32 v40, v40, v41
	v_mul_f32_e32 v41, v44, v45
	v_mul_f32_e32 v42, v42, v43
	v_mul_f32_e32 v43, v46, v47
	v_mul_f32_e32 v44, v32, v33
	v_mul_f32_e32 v36, v36, v37
	v_cvt_pk_bf16_f32 v32, v48, v40
	v_cvt_pk_bf16_f32 v33, v41, v42
	v_cvt_pk_bf16_f32 v34, v43, v44
	v_cvt_pk_bf16_f32 v35, v36, v35
	global_store_dwordx4 v[38:39], v[32:35], off
	s_nop 0
	v_mov_b32_e32 v33, v24
	v_mov_b32_e32 v24, v29
	v_mov_b32_e32 v29, v26
	v_mov_b32_e32 v26, v31
	v_mov_b32_e32 v31, v16
	v_mov_b32_e32 v16, v21
	v_mov_b32_e32 v21, v18
	v_mov_b32_e32 v18, v23
	v_mov_b32_e32 v32, v28
	v_mov_b32_e32 v28, v30
	v_mov_b32_e32 v30, v20
	v_mov_b32_e32 v20, v22
	v_add_u32_e32 v22, 0xa0, v144
	s_waitcnt vmcnt(7)
	v_mov_b32_e32 v34, v252
	v_fmamk_f32 v23, v34, 0x3a800000, v154
	v_mul_f32_e32 v34, 0x4b800000, v23
	v_cmp_gt_f32_e32 vcc, s64, v23
	s_nop 1
	v_cndmask_b32_e32 v23, v23, v34, vcc
	v_rsq_f32_e32 v34, v23
	v_mad_i64_i32 v[22:23], s[28:29], v22, s65, v[120:121]
	v_lshl_add_u64 v[22:23], v[22:23], 0, v[122:123]
	v_mul_f32_e32 v35, 0x45800000, v34
	v_cndmask_b32_e32 v34, v34, v35, vcc
	v_pk_mul_f32 v[18:19], v[18:19], v[34:35] op_sel_hi:[1,0]
	v_pk_mul_f32 v[32:33], v[32:33], v[34:35] op_sel_hi:[1,0]
	v_pk_mul_f32 v[24:25], v[24:25], v[34:35] op_sel_hi:[1,0]
	v_pk_mul_f32 v[28:29], v[28:29], v[34:35] op_sel_hi:[1,0]
	v_pk_mul_f32 v[26:27], v[26:27], v[34:35] op_sel_hi:[1,0]
	v_pk_mul_f32 v[30:31], v[30:31], v[34:35] op_sel_hi:[1,0]
	v_pk_mul_f32 v[16:17], v[16:17], v[34:35] op_sel_hi:[1,0]
	v_pk_mul_f32 v[20:21], v[20:21], v[34:35] op_sel_hi:[1,0]
	v_mul_f32_e32 v41, 0xbfb8aa3b, v19
	v_mul_f32_e32 v34, 0xbfb8aa3b, v33
	v_mul_f32_e32 v35, 0xbfb8aa3b, v25
	v_mul_f32_e32 v36, 0xbfb8aa3b, v29
	v_mul_f32_e32 v37, 0xbfb8aa3b, v27
	v_mul_f32_e32 v38, 0xbfb8aa3b, v31
	v_mul_f32_e32 v39, 0xbfb8aa3b, v17
	v_mul_f32_e32 v40, 0xbfb8aa3b, v21
	v_exp_f32_e32 v41, v41
	v_exp_f32_e32 v34, v34
	v_exp_f32_e32 v35, v35
	v_exp_f32_e32 v36, v36
	v_exp_f32_e32 v37, v37
	v_exp_f32_e32 v38, v38
	v_exp_f32_e32 v39, v39
	v_exp_f32_e32 v40, v40
	v_add_f32_e32 v41, 1.0, v41
	v_add_f32_e32 v34, 1.0, v34
	v_add_f32_e32 v35, 1.0, v35
	v_add_f32_e32 v36, 1.0, v36
	v_add_f32_e32 v37, 1.0, v37
	v_add_f32_e32 v38, 1.0, v38
	v_add_f32_e32 v39, 1.0, v39
	v_add_f32_e32 v40, 1.0, v40
	v_rcp_f32_e32 v41, v41
	v_rcp_f32_e32 v34, v34
	v_rcp_f32_e32 v35, v35
	v_rcp_f32_e32 v36, v36
	v_rcp_f32_e32 v37, v37
	v_rcp_f32_e32 v38, v38
	v_rcp_f32_e32 v39, v39
	v_rcp_f32_e32 v40, v40
	v_mul_f32_e32 v19, v19, v41
	v_mul_f32_e32 v33, v33, v34
	v_mul_f32_e32 v25, v25, v35
	v_mul_f32_e32 v29, v29, v36
	v_mul_f32_e32 v27, v27, v37
	v_mul_f32_e32 v31, v31, v38
	v_mul_f32_e32 v17, v17, v39
	v_mul_f32_e32 v21, v21, v40
	v_mul_f32_e32 v19, v18, v19
	v_mul_f32_e32 v32, v32, v33
	v_mul_f32_e32 v24, v24, v25
	v_mul_f32_e32 v25, v28, v29
	v_mul_f32_e32 v26, v26, v27
	v_mul_f32_e32 v27, v30, v31
	v_mul_f32_e32 v28, v16, v17
	v_mul_f32_e32 v20, v20, v21
	v_cvt_pk_bf16_f32 v16, v32, v24
	v_cvt_pk_bf16_f32 v17, v25, v26
	v_cvt_pk_bf16_f32 v18, v27, v28
	v_cvt_pk_bf16_f32 v19, v20, v19
	global_store_dwordx4 v[22:23], v[16:19], off
	s_and_b64 vcc, exec, s[0:1]
	v_mov_b32_e32 v17, v8
	v_mov_b32_e32 v8, v13
	v_mov_b32_e32 v13, v10
	v_mov_b32_e32 v10, v15
	v_mov_b32_e32 v15, v0
	v_mov_b32_e32 v0, v5
	v_mov_b32_e32 v5, v2
	v_mov_b32_e32 v2, v7
	v_mov_b32_e32 v16, v12
	v_mov_b32_e32 v12, v14
	v_mov_b32_e32 v14, v4
	v_mov_b32_e32 v4, v6
	v_add_u32_e32 v6, 0xb0, v144
	s_mov_b64 s[28:29], s[22:23]
	s_waitcnt vmcnt(7)
	v_mov_b32_e32 v18, v253
	v_fmamk_f32 v7, v18, 0x3a800000, v154
	v_mul_f32_e32 v18, 0x4b800000, v7
	v_cmp_gt_f32_e64 s[0:1], s64, v7
	s_nop 1
	v_cndmask_b32_e64 v7, v7, v18, s[0:1]
	v_rsq_f32_e32 v18, v7
	v_mad_i64_i32 v[6:7], s[22:23], v6, s65, v[120:121]
	v_lshl_add_u64 v[6:7], v[6:7], 0, v[122:123]
	v_mul_f32_e32 v19, 0x45800000, v18
	v_cndmask_b32_e64 v18, v18, v19, s[0:1]
	v_pk_mul_f32 v[2:3], v[2:3], v[18:19] op_sel_hi:[1,0]
	v_pk_mul_f32 v[16:17], v[16:17], v[18:19] op_sel_hi:[1,0]
	v_pk_mul_f32 v[8:9], v[8:9], v[18:19] op_sel_hi:[1,0]
	v_pk_mul_f32 v[12:13], v[12:13], v[18:19] op_sel_hi:[1,0]
	v_pk_mul_f32 v[10:11], v[10:11], v[18:19] op_sel_hi:[1,0]
	v_pk_mul_f32 v[14:15], v[14:15], v[18:19] op_sel_hi:[1,0]
	v_pk_mul_f32 v[0:1], v[0:1], v[18:19] op_sel_hi:[1,0]
	v_pk_mul_f32 v[4:5], v[4:5], v[18:19] op_sel_hi:[1,0]
	v_mul_f32_e32 v25, 0xbfb8aa3b, v3
	v_mul_f32_e32 v18, 0xbfb8aa3b, v17
	v_mul_f32_e32 v19, 0xbfb8aa3b, v9
	v_mul_f32_e32 v20, 0xbfb8aa3b, v13
	v_mul_f32_e32 v21, 0xbfb8aa3b, v11
	v_mul_f32_e32 v22, 0xbfb8aa3b, v15
	v_mul_f32_e32 v23, 0xbfb8aa3b, v1
	v_mul_f32_e32 v24, 0xbfb8aa3b, v5
	v_exp_f32_e32 v25, v25
	v_exp_f32_e32 v18, v18
	v_exp_f32_e32 v19, v19
	v_exp_f32_e32 v20, v20
	v_exp_f32_e32 v21, v21
	v_exp_f32_e32 v22, v22
	v_exp_f32_e32 v23, v23
	v_exp_f32_e32 v24, v24
	v_add_f32_e32 v25, 1.0, v25
	v_add_f32_e32 v18, 1.0, v18
	v_add_f32_e32 v19, 1.0, v19
	v_add_f32_e32 v20, 1.0, v20
	v_add_f32_e32 v21, 1.0, v21
	v_add_f32_e32 v22, 1.0, v22
	v_add_f32_e32 v23, 1.0, v23
	v_add_f32_e32 v24, 1.0, v24
	v_rcp_f32_e32 v25, v25
	v_rcp_f32_e32 v18, v18
	v_rcp_f32_e32 v19, v19
	v_rcp_f32_e32 v20, v20
	v_rcp_f32_e32 v21, v21
	v_rcp_f32_e32 v22, v22
	v_rcp_f32_e32 v23, v23
	v_rcp_f32_e32 v24, v24
	v_mul_f32_e32 v3, v3, v25
	v_mul_f32_e32 v17, v17, v18
	v_mul_f32_e32 v9, v9, v19
	v_mul_f32_e32 v13, v13, v20
	v_mul_f32_e32 v11, v11, v21
	v_mul_f32_e32 v15, v15, v22
	v_mul_f32_e32 v1, v1, v23
	v_mul_f32_e32 v5, v5, v24
	v_mul_f32_e32 v3, v2, v3
	v_mul_f32_e32 v16, v16, v17
	v_mul_f32_e32 v8, v8, v9
	v_mul_f32_e32 v9, v12, v13
	v_mul_f32_e32 v10, v10, v11
	v_mul_f32_e32 v11, v14, v15
	v_mul_f32_e32 v12, v0, v1
	v_mul_f32_e32 v4, v4, v5
	v_cvt_pk_bf16_f32 v0, v16, v8
	v_cvt_pk_bf16_f32 v1, v9, v10
	v_cvt_pk_bf16_f32 v2, v11, v12
	v_cvt_pk_bf16_f32 v3, v4, v3
	global_store_dwordx4 v[6:7], v[0:3], off
	s_cbranch_vccz .LBB0_189
	s_waitcnt vmcnt(0)
	s_cmpk_gt_u32 s36, 0xff
	s_cbranch_scc1 .LBB0_200
	s_barrier

.LBB0_447:
	ds_read_b128 v[144:147], v151
	ds_read_b128 v[156:159], v151 offset:1024
	ds_read_b128 v[160:163], v151 offset:2048
	ds_read_b128 v[164:167], v151 offset:3072
	s_add_u32 s28, s26, 0xfffc0080
	s_addc_u32 s29, s27, -1
	s_cmp_eq_u32 s63, 12
	s_cselect_b32 s31, s19, s29
	s_cselect_b32 s30, s57, s28
	s_cselect_b32 s29, s17, s62
	s_cselect_b32 s28, s58, s59
	v_lshl_add_u64 v[172:173], s[26:27], 0, v[136:137]
	s_add_i32 m0, s25, 0xc000
	ds_read_b128 v[168:171], v152
	ds_read_b128 v[178:181], v152 offset:1024
	ds_read_b128 v[182:185], v152 offset:2048
	ds_read_b128 v[186:189], v152 offset:3072
	ds_read_b128 v[190:193], v152 offset:4096
	ds_read_b128 v[194:197], v152 offset:5120
	ds_read_b128 v[198:201], v152 offset:6144
	ds_read_b128 v[202:205], v152 offset:7168
	global_load_lds_dwordx4 v[172:173], off
	v_lshl_add_u64 v[172:173], s[26:27], 0, v[138:139]
	s_add_i32 m0, s25, 0xe000
	s_nop 0
	global_load_lds_dwordx4 v[172:173], off
	s_waitcnt lgkmcnt(8)
	s_barrier
	s_waitcnt lgkmcnt(0)
	s_setprio 1
	s_waitcnt lgkmcnt(0)
	v_mfma_f32_16x16x32_bf16 v[116:119], v[144:147], v[168:171], v[116:119]
	v_mfma_f32_16x16x32_bf16 v[112:115], v[160:163], v[168:171], v[112:115]
	v_mfma_f32_16x16x32_bf16 v[100:103], v[144:147], v[182:185], v[100:103]
	v_mfma_f32_16x16x32_bf16 v[96:99], v[160:163], v[182:185], v[96:99]
	v_mfma_f32_16x16x32_bf16 v[84:87], v[144:147], v[190:193], v[84:87]
	v_mfma_f32_16x16x32_bf16 v[80:83], v[160:163], v[190:193], v[80:83]
	v_mfma_f32_16x16x32_bf16 v[72:75], v[144:147], v[198:201], v[72:75]
	v_mfma_f32_16x16x32_bf16 v[64:67], v[160:163], v[198:201], v[64:67]
	v_mfma_f32_16x16x32_bf16 v[116:119], v[156:159], v[178:181], v[116:119]
	v_mfma_f32_16x16x32_bf16 v[112:115], v[164:167], v[178:181], v[112:115]
	v_mfma_f32_16x16x32_bf16 v[100:103], v[156:159], v[186:189], v[100:103]
	v_mfma_f32_16x16x32_bf16 v[96:99], v[164:167], v[186:189], v[96:99]
	v_mfma_f32_16x16x32_bf16 v[84:87], v[156:159], v[194:197], v[84:87]
	v_mfma_f32_16x16x32_bf16 v[80:83], v[164:167], v[194:197], v[80:83]
	v_mfma_f32_16x16x32_bf16 v[72:75], v[156:159], v[202:205], v[72:75]
	v_mfma_f32_16x16x32_bf16 v[64:67], v[164:167], v[202:205], v[64:67]
	s_setprio 0
	s_barrier
	s_add_i32 s64, s52, s34
	v_lshl_add_u64 v[172:173], s[28:29], 0, v[130:131]
	s_mov_b32 m0, s64
	ds_read_b128 v[206:209], v153
	ds_read_b128 v[210:213], v153 offset:1024
	ds_read_b128 v[214:217], v153 offset:2048
	ds_read_b128 v[218:221], v153 offset:3072
	global_load_lds_dwordx4 v[172:173], off
	v_lshl_add_u64 v[222:223], s[28:29], 0, v[134:135]
	s_add_i32 m0, s64, 0x2000
	s_nop 0
	global_load_lds_dwordx4 v[222:223], off
	s_barrier
	s_waitcnt lgkmcnt(0)
	s_setprio 1
	s_waitcnt lgkmcnt(0)
	v_mfma_f32_16x16x32_bf16 v[124:127], v[206:209], v[168:171], v[124:127]
	v_mfma_f32_16x16x32_bf16 v[120:123], v[214:217], v[168:171], v[120:123]
	v_mfma_f32_16x16x32_bf16 v[108:111], v[206:209], v[182:185], v[108:111]
	v_mfma_f32_16x16x32_bf16 v[104:107], v[214:217], v[182:185], v[104:107]
	v_mfma_f32_16x16x32_bf16 v[92:95], v[206:209], v[190:193], v[92:95]
	v_mfma_f32_16x16x32_bf16 v[88:91], v[214:217], v[190:193], v[88:91]
	v_mfma_f32_16x16x32_bf16 v[76:79], v[206:209], v[198:201], v[76:79]
	v_mfma_f32_16x16x32_bf16 v[68:71], v[214:217], v[198:201], v[68:71]
	v_mfma_f32_16x16x32_bf16 v[124:127], v[210:213], v[178:181], v[124:127]
	v_mfma_f32_16x16x32_bf16 v[120:123], v[218:221], v[178:181], v[120:123]
	v_mfma_f32_16x16x32_bf16 v[108:111], v[210:213], v[186:189], v[108:111]
	v_mfma_f32_16x16x32_bf16 v[104:107], v[218:221], v[186:189], v[104:107]
	v_mfma_f32_16x16x32_bf16 v[92:95], v[210:213], v[194:197], v[92:95]
	v_mfma_f32_16x16x32_bf16 v[88:91], v[218:221], v[194:197], v[88:91]
	v_mfma_f32_16x16x32_bf16 v[76:79], v[210:213], v[202:205], v[76:79]
	v_mfma_f32_16x16x32_bf16 v[68:71], v[218:221], v[202:205], v[68:71]
	s_setprio 0
	s_mov_b32 m0, s25
	v_lshl_add_u64 v[224:225], s[30:31], 0, v[128:129]
	s_barrier
	ds_read_b128 v[168:171], v152 offset:16384
	ds_read_b128 v[178:181], v152 offset:17408
	ds_read_b128 v[182:185], v152 offset:18432
	ds_read_b128 v[186:189], v152 offset:19456
	ds_read_b128 v[190:193], v152 offset:20480
	ds_read_b128 v[194:197], v152 offset:21504
	ds_read_b128 v[198:201], v152 offset:22528
	ds_read_b128 v[202:205], v152 offset:23552
	global_load_lds_dwordx4 v[224:225], off
	v_lshl_add_u64 v[226:227], s[30:31], 0, v[132:133]
	s_mov_b32 m0, s35
	s_nop 0
	global_load_lds_dwordx4 v[226:227], off
	s_barrier
	s_waitcnt lgkmcnt(0)
	s_setprio 1
	s_waitcnt lgkmcnt(0)
	v_mfma_f32_16x16x32_bf16 v[56:59], v[144:147], v[168:171], v[56:59]
	v_mfma_f32_16x16x32_bf16 v[48:51], v[160:163], v[168:171], v[48:51]
	v_mfma_f32_16x16x32_bf16 v[40:43], v[144:147], v[182:185], v[40:43]
	v_mfma_f32_16x16x32_bf16 v[32:35], v[160:163], v[182:185], v[32:35]
	v_mfma_f32_16x16x32_bf16 v[24:27], v[144:147], v[190:193], v[24:27]
	v_mfma_f32_16x16x32_bf16 v[16:19], v[160:163], v[190:193], v[16:19]
	v_mfma_f32_16x16x32_bf16 v[8:11], v[144:147], v[198:201], v[8:11]
	v_mfma_f32_16x16x32_bf16 v[0:3], v[160:163], v[198:201], v[0:3]
	v_mfma_f32_16x16x32_bf16 v[56:59], v[156:159], v[178:181], v[56:59]
	v_mfma_f32_16x16x32_bf16 v[48:51], v[164:167], v[178:181], v[48:51]
	v_mfma_f32_16x16x32_bf16 v[40:43], v[156:159], v[186:189], v[40:43]
	v_mfma_f32_16x16x32_bf16 v[32:35], v[164:167], v[186:189], v[32:35]
	v_mfma_f32_16x16x32_bf16 v[24:27], v[156:159], v[194:197], v[24:27]
	v_mfma_f32_16x16x32_bf16 v[16:19], v[164:167], v[194:197], v[16:19]
	v_mfma_f32_16x16x32_bf16 v[8:11], v[156:159], v[202:205], v[8:11]
	v_mfma_f32_16x16x32_bf16 v[0:3], v[164:167], v[202:205], v[0:3]
	s_setprio 0
	s_barrier
	s_add_u32 s64, s28, 0x40000
	s_addc_u32 s65, s29, 0
	s_add_i32 s66, s53, s34
	v_lshl_add_u64 v[144:145], s[64:65], 0, v[130:131]
	s_mov_b32 m0, s66
	s_nop 0
	global_load_lds_dwordx4 v[144:145], off
	v_lshl_add_u64 v[144:145], s[64:65], 0, v[134:135]
	s_add_i32 m0, s66, 0x2000
	s_nop 0
	global_load_lds_dwordx4 v[144:145], off
	s_waitcnt vmcnt(6)
	s_barrier
	s_setprio 1
	v_mfma_f32_16x16x32_bf16 v[60:63], v[206:209], v[168:171], v[60:63]
	v_mfma_f32_16x16x32_bf16 v[52:55], v[214:217], v[168:171], v[52:55]
	v_mfma_f32_16x16x32_bf16 v[44:47], v[206:209], v[182:185], v[44:47]
	v_mfma_f32_16x16x32_bf16 v[36:39], v[214:217], v[182:185], v[36:39]
	v_mfma_f32_16x16x32_bf16 v[28:31], v[206:209], v[190:193], v[28:31]
	v_mfma_f32_16x16x32_bf16 v[20:23], v[214:217], v[190:193], v[20:23]
	v_mfma_f32_16x16x32_bf16 v[12:15], v[206:209], v[198:201], v[12:15]
	v_mfma_f32_16x16x32_bf16 v[4:7], v[214:217], v[198:201], v[4:7]
	v_mfma_f32_16x16x32_bf16 v[60:63], v[210:213], v[178:181], v[60:63]
	v_mfma_f32_16x16x32_bf16 v[52:55], v[218:221], v[178:181], v[52:55]
	v_mfma_f32_16x16x32_bf16 v[44:47], v[210:213], v[186:189], v[44:47]
	v_mfma_f32_16x16x32_bf16 v[36:39], v[218:221], v[186:189], v[36:39]
	v_mfma_f32_16x16x32_bf16 v[28:31], v[210:213], v[194:197], v[28:31]
	v_mfma_f32_16x16x32_bf16 v[20:23], v[218:221], v[194:197], v[20:23]
	v_mfma_f32_16x16x32_bf16 v[12:15], v[210:213], v[202:205], v[12:15]
	v_mfma_f32_16x16x32_bf16 v[4:7], v[218:221], v[202:205], v[4:7]
	s_setprio 0
	s_add_i32 s64, 0, 0x18000
	v_add_u32_e32 v155, s64, v149
	s_barrier
	ds_read_b128 v[144:147], v155
	ds_read_b128 v[156:159], v155 offset:1024
	ds_read_b128 v[160:163], v155 offset:2048
	ds_read_b128 v[164:167], v155 offset:3072
	s_add_u32 s30, s30, 0x40000
	s_addc_u32 s31, s31, 0
	s_mov_b32 m0, s36
	v_lshl_add_u64 v[206:207], s[30:31], 0, v[128:129]
	ds_read_b128 v[168:171], v152 offset:32768
	ds_read_b128 v[178:181], v152 offset:33792
	ds_read_b128 v[182:185], v152 offset:34816
	ds_read_b128 v[186:189], v152 offset:35840
	ds_read_b128 v[190:193], v152 offset:36864
	ds_read_b128 v[194:197], v152 offset:37888
	ds_read_b128 v[198:201], v152 offset:38912
	ds_read_b128 v[202:205], v152 offset:39936
	global_load_lds_dwordx4 v[206:207], off
	v_lshl_add_u64 v[206:207], s[30:31], 0, v[132:133]
	s_mov_b32 m0, s37
	s_nop 0
	global_load_lds_dwordx4 v[206:207], off
	s_waitcnt lgkmcnt(8)
	s_barrier
	s_waitcnt lgkmcnt(0)
	s_setprio 1
	s_waitcnt lgkmcnt(0)
	v_mfma_f32_16x16x32_bf16 v[116:119], v[144:147], v[168:171], v[116:119]
	v_mfma_f32_16x16x32_bf16 v[112:115], v[160:163], v[168:171], v[112:115]
	v_mfma_f32_16x16x32_bf16 v[100:103], v[144:147], v[182:185], v[100:103]
	v_mfma_f32_16x16x32_bf16 v[96:99], v[160:163], v[182:185], v[96:99]
	v_mfma_f32_16x16x32_bf16 v[84:87], v[144:147], v[190:193], v[84:87]
	v_mfma_f32_16x16x32_bf16 v[80:83], v[160:163], v[190:193], v[80:83]
	v_mfma_f32_16x16x32_bf16 v[72:75], v[144:147], v[198:201], v[72:75]
	v_mfma_f32_16x16x32_bf16 v[64:67], v[160:163], v[198:201], v[64:67]
	v_mfma_f32_16x16x32_bf16 v[116:119], v[156:159], v[178:181], v[116:119]
	v_mfma_f32_16x16x32_bf16 v[112:115], v[164:167], v[178:181], v[112:115]
	v_mfma_f32_16x16x32_bf16 v[100:103], v[156:159], v[186:189], v[100:103]
	v_mfma_f32_16x16x32_bf16 v[96:99], v[164:167], v[186:189], v[96:99]
	v_mfma_f32_16x16x32_bf16 v[84:87], v[156:159], v[194:197], v[84:87]
	v_mfma_f32_16x16x32_bf16 v[80:83], v[164:167], v[194:197], v[80:83]
	v_mfma_f32_16x16x32_bf16 v[72:75], v[156:159], v[202:205], v[72:75]
	v_mfma_f32_16x16x32_bf16 v[64:67], v[164:167], v[202:205], v[64:67]
	s_setprio 0
	s_barrier
	s_add_i32 s30, 0, 0x1c000
	s_add_i32 s31, s64, s34
	v_add_u32_e32 v155, s30, v149
	v_lshl_add_u64 v[172:173], v[172:173], 0, s[12:13]
	s_mov_b32 m0, s31
	ds_read_b128 v[206:209], v155
	ds_read_b128 v[210:213], v155 offset:1024
	ds_read_b128 v[214:217], v155 offset:2048
	ds_read_b128 v[218:221], v155 offset:3072
	global_load_lds_dwordx4 v[172:173], off
	v_lshl_add_u64 v[172:173], v[222:223], 0, s[12:13]
	s_add_i32 m0, s31, 0x2000
	s_nop 0
	global_load_lds_dwordx4 v[172:173], off
	s_barrier
	s_waitcnt lgkmcnt(0)
	s_setprio 1
	s_waitcnt lgkmcnt(0)
	v_mfma_f32_16x16x32_bf16 v[124:127], v[206:209], v[168:171], v[124:127]
	v_mfma_f32_16x16x32_bf16 v[120:123], v[214:217], v[168:171], v[120:123]
	v_mfma_f32_16x16x32_bf16 v[108:111], v[206:209], v[182:185], v[108:111]
	v_mfma_f32_16x16x32_bf16 v[104:107], v[214:217], v[182:185], v[104:107]
	v_mfma_f32_16x16x32_bf16 v[92:95], v[206:209], v[190:193], v[92:95]
	v_mfma_f32_16x16x32_bf16 v[88:91], v[214:217], v[190:193], v[88:91]
	v_mfma_f32_16x16x32_bf16 v[76:79], v[206:209], v[198:201], v[76:79]
	v_mfma_f32_16x16x32_bf16 v[68:71], v[214:217], v[198:201], v[68:71]
	v_mfma_f32_16x16x32_bf16 v[124:127], v[210:213], v[178:181], v[124:127]
	v_mfma_f32_16x16x32_bf16 v[120:123], v[218:221], v[178:181], v[120:123]
	v_mfma_f32_16x16x32_bf16 v[108:111], v[210:213], v[186:189], v[108:111]
	v_mfma_f32_16x16x32_bf16 v[104:107], v[218:221], v[186:189], v[104:107]
	v_mfma_f32_16x16x32_bf16 v[92:95], v[210:213], v[194:197], v[92:95]
	v_mfma_f32_16x16x32_bf16 v[88:91], v[218:221], v[194:197], v[88:91]
	v_mfma_f32_16x16x32_bf16 v[76:79], v[210:213], v[202:205], v[76:79]
	v_mfma_f32_16x16x32_bf16 v[68:71], v[218:221], v[202:205], v[68:71]
	s_setprio 0
	s_mov_b32 m0, s43
	v_lshl_add_u64 v[172:173], v[224:225], 0, s[12:13]
	s_barrier
	ds_read_b128 v[168:171], v152 offset:49152
	ds_read_b128 v[178:181], v152 offset:50176
	ds_read_b128 v[182:185], v152 offset:51200
	ds_read_b128 v[186:189], v152 offset:52224
	ds_read_b128 v[190:193], v152 offset:53248
	ds_read_b128 v[194:197], v152 offset:54272
	ds_read_b128 v[198:201], v152 offset:55296
	ds_read_b128 v[202:205], v152 offset:56320
	global_load_lds_dwordx4 v[172:173], off
	v_lshl_add_u64 v[172:173], v[226:227], 0, s[12:13]
	s_mov_b32 m0, s46
	s_nop 0
	global_load_lds_dwordx4 v[172:173], off
	s_barrier
	s_waitcnt lgkmcnt(0)
	s_setprio 1
	s_waitcnt lgkmcnt(0)
	v_mfma_f32_16x16x32_bf16 v[56:59], v[144:147], v[168:171], v[56:59]
	v_mfma_f32_16x16x32_bf16 v[48:51], v[160:163], v[168:171], v[48:51]
	v_mfma_f32_16x16x32_bf16 v[40:43], v[144:147], v[182:185], v[40:43]
	v_mfma_f32_16x16x32_bf16 v[32:35], v[160:163], v[182:185], v[32:35]
	v_mfma_f32_16x16x32_bf16 v[24:27], v[144:147], v[190:193], v[24:27]
	v_mfma_f32_16x16x32_bf16 v[16:19], v[160:163], v[190:193], v[16:19]
	v_mfma_f32_16x16x32_bf16 v[8:11], v[144:147], v[198:201], v[8:11]
	v_mfma_f32_16x16x32_bf16 v[0:3], v[160:163], v[198:201], v[0:3]
	v_mfma_f32_16x16x32_bf16 v[56:59], v[156:159], v[178:181], v[56:59]
	v_mfma_f32_16x16x32_bf16 v[48:51], v[164:167], v[178:181], v[48:51]
	v_mfma_f32_16x16x32_bf16 v[40:43], v[156:159], v[186:189], v[40:43]
	v_mfma_f32_16x16x32_bf16 v[32:35], v[164:167], v[186:189], v[32:35]
	v_mfma_f32_16x16x32_bf16 v[24:27], v[156:159], v[194:197], v[24:27]
	v_mfma_f32_16x16x32_bf16 v[16:19], v[164:167], v[194:197], v[16:19]
	v_mfma_f32_16x16x32_bf16 v[8:11], v[156:159], v[202:205], v[8:11]
	v_mfma_f32_16x16x32_bf16 v[0:3], v[164:167], v[202:205], v[0:3]
	s_setprio 0
	s_barrier
	s_add_u32 s28, s28, 0x40080
	s_addc_u32 s29, s29, 0
	s_add_i32 s30, s30, s34
	v_lshl_add_u64 v[144:145], s[28:29], 0, v[130:131]
	s_mov_b32 m0, s30
	s_nop 0
	global_load_lds_dwordx4 v[144:145], off
	v_lshl_add_u64 v[144:145], s[28:29], 0, v[134:135]
	s_add_i32 m0, s30, 0x2000
	s_nop 0
	global_load_lds_dwordx4 v[144:145], off
	s_waitcnt vmcnt(6)
	s_barrier
	s_setprio 1
	v_mfma_f32_16x16x32_bf16 v[60:63], v[206:209], v[168:171], v[60:63]
	v_mfma_f32_16x16x32_bf16 v[52:55], v[214:217], v[168:171], v[52:55]
	v_mfma_f32_16x16x32_bf16 v[44:47], v[206:209], v[182:185], v[44:47]
	v_mfma_f32_16x16x32_bf16 v[36:39], v[214:217], v[182:185], v[36:39]
	v_mfma_f32_16x16x32_bf16 v[28:31], v[206:209], v[190:193], v[28:31]
	v_mfma_f32_16x16x32_bf16 v[20:23], v[214:217], v[190:193], v[20:23]
	v_mfma_f32_16x16x32_bf16 v[12:15], v[206:209], v[198:201], v[12:15]
	v_mfma_f32_16x16x32_bf16 v[4:7], v[214:217], v[198:201], v[4:7]
	v_mfma_f32_16x16x32_bf16 v[60:63], v[210:213], v[178:181], v[60:63]
	v_mfma_f32_16x16x32_bf16 v[52:55], v[218:221], v[178:181], v[52:55]
	v_mfma_f32_16x16x32_bf16 v[44:47], v[210:213], v[186:189], v[44:47]
	v_mfma_f32_16x16x32_bf16 v[36:39], v[218:221], v[186:189], v[36:39]
	v_mfma_f32_16x16x32_bf16 v[28:31], v[210:213], v[194:197], v[28:31]
	v_mfma_f32_16x16x32_bf16 v[20:23], v[218:221], v[194:197], v[20:23]
	v_mfma_f32_16x16x32_bf16 v[12:15], v[210:213], v[202:205], v[12:15]
	v_mfma_f32_16x16x32_bf16 v[4:7], v[218:221], v[202:205], v[4:7]
	s_setprio 0
	s_add_i32 s63, s63, 2
	s_add_u32 s26, s26, 0x100
	s_addc_u32 s27, s27, 0
	s_add_u32 s59, s59, 0x100
	s_addc_u32 s62, s62, 0
	s_cmp_gt_u32 s63, 13
	s_barrier
	s_cbranch_scc0 .LBB0_447
	v_lshl_add_u32 v144, s24, 8, v148
	v_ashrrev_i32_e32 v145, 31, v144
	v_lshl_add_u64 v[146:147], v[144:145], 2, s[10:11]
	global_load_dword v145, v[146:147], off
	global_load_dword v247, v[146:147], off offset:64
	global_load_dword v248, v[146:147], off offset:128
	global_load_dword v249, v[146:147], off offset:192
	global_load_dword v250, v[146:147], off offset:512
	global_load_dword v251, v[146:147], off offset:576
	global_load_dword v252, v[146:147], off offset:640
	global_load_dword v253, v[146:147], off offset:704
	v_lshl_or_b32 v156, s56, 7, v150
	v_mov_b32_e32 v161, v114
	v_mov_b32_e32 v114, v123
	v_mov_b32_e32 v158, v124
	v_mov_b32_e32 v159, v116
	v_mov_b32_e32 v116, v125
	v_mov_b32_e32 v124, v126
	v_mov_b32_e32 v125, v118
	v_mov_b32_e32 v118, v127
	v_mov_b32_e32 v126, v120
	v_mov_b32_e32 v127, v112
	v_mov_b32_e32 v112, v121
	v_mov_b32_e32 v160, v122
	v_mov_b64_e32 v[120:121], s[44:45]
	v_ashrrev_i32_e32 v157, 31, v156
	v_or_b32_e32 v164, 16, v144
	v_mad_i64_i32 v[162:163], s[26:27], v144, s55, v[120:121]
	v_lshlrev_b64 v[122:123], 1, v[156:157]
	v_ashrrev_i32_e32 v165, 31, v164
	v_lshl_add_u64 v[156:157], v[162:163], 0, v[122:123]
	v_lshl_add_u64 v[162:163], v[164:165], 2, s[10:11]
	s_mov_b32 s56, s16
	s_mov_b32 s24, s18
	s_mov_b64 s[28:29], s[22:23]
	s_waitcnt vmcnt(7)
	v_fmamk_f32 v145, v145, 0x3a800000, v154
	v_mul_f32_e32 v155, 0x4b800000, v145
	v_cmp_gt_f32_e32 vcc, s54, v145
	s_nop 1
	v_cndmask_b32_e32 v145, v145, v155, vcc
	v_rsq_f32_e32 v145, v145
	s_nop 0
	v_mul_f32_e32 v155, 0x45800000, v145
	v_cndmask_b32_e32 v166, v145, v155, vcc
	v_pk_mul_f32 v[114:115], v[114:115], v[166:167] op_sel_hi:[1,0]
	v_pk_mul_f32 v[158:159], v[158:159], v[166:167] op_sel_hi:[1,0]
	v_pk_mul_f32 v[116:117], v[116:117], v[166:167] op_sel_hi:[1,0]
	v_pk_mul_f32 v[124:125], v[124:125], v[166:167] op_sel_hi:[1,0]
	v_pk_mul_f32 v[118:119], v[118:119], v[166:167] op_sel_hi:[1,0]
	v_pk_mul_f32 v[126:127], v[126:127], v[166:167] op_sel_hi:[1,0]
	v_pk_mul_f32 v[112:113], v[112:113], v[166:167] op_sel_hi:[1,0]
	v_pk_mul_f32 v[160:161], v[160:161], v[166:167] op_sel_hi:[1,0]
	v_mul_f32_e32 v170, 0xbfb8aa3b, v115
	v_mul_f32_e32 v145, 0xbfb8aa3b, v159
	v_mul_f32_e32 v155, 0xbfb8aa3b, v117
	v_mul_f32_e32 v165, 0xbfb8aa3b, v125
	v_mul_f32_e32 v166, 0xbfb8aa3b, v119
	v_mul_f32_e32 v167, 0xbfb8aa3b, v127
	v_mul_f32_e32 v168, 0xbfb8aa3b, v113
	v_mul_f32_e32 v169, 0xbfb8aa3b, v161
	v_exp_f32_e32 v170, v170
	v_exp_f32_e32 v145, v145
	v_exp_f32_e32 v155, v155
	v_exp_f32_e32 v165, v165
	v_exp_f32_e32 v166, v166
	v_exp_f32_e32 v167, v167
	v_exp_f32_e32 v168, v168
	v_exp_f32_e32 v169, v169
	v_add_f32_e32 v170, 1.0, v170
	v_add_f32_e32 v145, 1.0, v145
	v_add_f32_e32 v155, 1.0, v155
	v_add_f32_e32 v165, 1.0, v165
	v_add_f32_e32 v166, 1.0, v166
	v_add_f32_e32 v167, 1.0, v167
	v_add_f32_e32 v168, 1.0, v168
	v_add_f32_e32 v169, 1.0, v169
	v_rcp_f32_e32 v170, v170
	v_rcp_f32_e32 v145, v145
	v_rcp_f32_e32 v155, v155
	v_rcp_f32_e32 v165, v165
	v_rcp_f32_e32 v166, v166
	v_rcp_f32_e32 v167, v167
	v_rcp_f32_e32 v168, v168
	v_rcp_f32_e32 v169, v169
	v_mul_f32_e32 v115, v115, v170
	v_mul_f32_e32 v145, v159, v145
	v_mul_f32_e32 v117, v117, v155
	v_mul_f32_e32 v125, v125, v165
	v_mul_f32_e32 v119, v119, v166
	v_mul_f32_e32 v127, v127, v167
	v_mul_f32_e32 v113, v113, v168
	v_mul_f32_e32 v155, v161, v169
	v_mul_f32_e32 v115, v114, v115
	v_mul_f32_e32 v145, v158, v145
	v_mul_f32_e32 v116, v116, v117
	v_mul_f32_e32 v117, v124, v125
	v_mul_f32_e32 v118, v118, v119
	v_mul_f32_e32 v119, v126, v127
	v_mul_f32_e32 v124, v112, v113
	v_mul_f32_e32 v125, v160, v155
	v_cvt_pk_bf16_f32 v112, v145, v116
	v_cvt_pk_bf16_f32 v113, v117, v118
	v_cvt_pk_bf16_f32 v114, v119, v124
	v_cvt_pk_bf16_f32 v115, v125, v115
	global_store_dwordx4 v[156:157], v[112:115], off
	s_nop 0
	v_mov_b32_e32 v113, v100
	v_mov_b32_e32 v100, v109
	v_mov_b32_e32 v109, v102
	v_mov_b32_e32 v102, v111
	v_mov_b32_e32 v111, v96
	v_mov_b32_e32 v96, v105
	v_mov_b32_e32 v105, v98
	v_mov_b32_e32 v98, v107
	v_mov_b32_e32 v112, v108
	v_mov_b32_e32 v108, v110
	v_mov_b32_e32 v110, v104
	v_mov_b32_e32 v104, v106
	v_or_b32_e32 v106, 32, v144
	v_mad_i64_i32 v[114:115], s[26:27], v164, s55, v[120:121]
	v_lshl_add_u64 v[114:115], v[114:115], 0, v[122:123]
	s_waitcnt vmcnt(7)
	v_mov_b32_e32 v116, v247
	v_fmamk_f32 v107, v116, 0x3a800000, v154
	v_mul_f32_e32 v116, 0x4b800000, v107
	v_cmp_gt_f32_e32 vcc, s54, v107
	s_nop 1
	v_cndmask_b32_e32 v107, v107, v116, vcc
	v_rsq_f32_e32 v118, v107
	v_ashrrev_i32_e32 v107, 31, v106
	v_lshl_add_u64 v[116:117], v[106:107], 2, s[10:11]
	v_mul_f32_e32 v107, 0x45800000, v118
	v_cndmask_b32_e32 v118, v118, v107, vcc
	v_pk_mul_f32 v[98:99], v[98:99], v[118:119] op_sel_hi:[1,0]
	v_pk_mul_f32 v[112:113], v[112:113], v[118:119] op_sel_hi:[1,0]
	v_pk_mul_f32 v[100:101], v[100:101], v[118:119] op_sel_hi:[1,0]
	v_pk_mul_f32 v[108:109], v[108:109], v[118:119] op_sel_hi:[1,0]
	v_pk_mul_f32 v[102:103], v[102:103], v[118:119] op_sel_hi:[1,0]
	v_pk_mul_f32 v[110:111], v[110:111], v[118:119] op_sel_hi:[1,0]
	v_pk_mul_f32 v[96:97], v[96:97], v[118:119] op_sel_hi:[1,0]
	v_pk_mul_f32 v[104:105], v[104:105], v[118:119] op_sel_hi:[1,0]
	v_mul_f32_e32 v145, 0xbfb8aa3b, v99
	v_mul_f32_e32 v107, 0xbfb8aa3b, v113
	v_mul_f32_e32 v118, 0xbfb8aa3b, v101
	v_mul_f32_e32 v119, 0xbfb8aa3b, v109
	v_mul_f32_e32 v124, 0xbfb8aa3b, v103
	v_mul_f32_e32 v125, 0xbfb8aa3b, v111
	v_mul_f32_e32 v126, 0xbfb8aa3b, v97
	v_mul_f32_e32 v127, 0xbfb8aa3b, v105
	v_exp_f32_e32 v145, v145
	v_exp_f32_e32 v107, v107
	v_exp_f32_e32 v118, v118
	v_exp_f32_e32 v119, v119
	v_exp_f32_e32 v124, v124
	v_exp_f32_e32 v125, v125
	v_exp_f32_e32 v126, v126
	v_exp_f32_e32 v127, v127
	v_add_f32_e32 v145, 1.0, v145
	v_add_f32_e32 v107, 1.0, v107
	v_add_f32_e32 v118, 1.0, v118
	v_add_f32_e32 v119, 1.0, v119
	v_add_f32_e32 v124, 1.0, v124
	v_add_f32_e32 v125, 1.0, v125
	v_add_f32_e32 v126, 1.0, v126
	v_add_f32_e32 v127, 1.0, v127
	v_rcp_f32_e32 v145, v145
	v_rcp_f32_e32 v107, v107
	v_rcp_f32_e32 v118, v118
	v_rcp_f32_e32 v119, v119
	v_rcp_f32_e32 v124, v124
	v_rcp_f32_e32 v125, v125
	v_rcp_f32_e32 v126, v126
	v_rcp_f32_e32 v127, v127
	v_mul_f32_e32 v99, v99, v145
	v_mul_f32_e32 v107, v113, v107
	v_mul_f32_e32 v101, v101, v118
	v_mul_f32_e32 v109, v109, v119
	v_mul_f32_e32 v103, v103, v124
	v_mul_f32_e32 v111, v111, v125
	v_mul_f32_e32 v97, v97, v126
	v_mul_f32_e32 v105, v105, v127
	v_mul_f32_e32 v99, v98, v99
	v_mul_f32_e32 v107, v112, v107
	v_mul_f32_e32 v100, v100, v101
	v_mul_f32_e32 v101, v108, v109
	v_mul_f32_e32 v102, v102, v103
	v_mul_f32_e32 v103, v110, v111
	v_mul_f32_e32 v108, v96, v97
	v_mul_f32_e32 v104, v104, v105
	v_cvt_pk_bf16_f32 v96, v107, v100
	v_cvt_pk_bf16_f32 v97, v101, v102
	v_cvt_pk_bf16_f32 v98, v103, v108
	v_cvt_pk_bf16_f32 v99, v104, v99
	global_store_dwordx4 v[114:115], v[96:99], off
	s_nop 0
	v_mov_b32_e32 v97, v84
	v_mov_b32_e32 v84, v93
	v_mov_b32_e32 v93, v86
	v_mov_b32_e32 v86, v95
	v_mov_b32_e32 v95, v80
	v_mov_b32_e32 v80, v89
	v_mov_b32_e32 v89, v82
	v_mov_b32_e32 v82, v91
	v_mov_b32_e32 v96, v92
	v_mov_b32_e32 v92, v94
	v_mov_b32_e32 v94, v88
	v_mov_b32_e32 v88, v90
	v_or_b32_e32 v90, 48, v144
	v_mad_i64_i32 v[98:99], s[26:27], v106, s55, v[120:121]
	v_lshl_add_u64 v[98:99], v[98:99], 0, v[122:123]
	s_waitcnt vmcnt(7)
	v_mov_b32_e32 v100, v248
	v_fmamk_f32 v91, v100, 0x3a800000, v154
	v_mul_f32_e32 v100, 0x4b800000, v91
	v_cmp_gt_f32_e32 vcc, s54, v91
	s_nop 1
	v_cndmask_b32_e32 v91, v91, v100, vcc
	v_rsq_f32_e32 v102, v91
	v_ashrrev_i32_e32 v91, 31, v90
	v_lshl_add_u64 v[100:101], v[90:91], 2, s[10:11]
	v_mul_f32_e32 v91, 0x45800000, v102
	v_cndmask_b32_e32 v102, v102, v91, vcc
	v_pk_mul_f32 v[82:83], v[82:83], v[102:103] op_sel_hi:[1,0]
	v_pk_mul_f32 v[96:97], v[96:97], v[102:103] op_sel_hi:[1,0]
	v_pk_mul_f32 v[84:85], v[84:85], v[102:103] op_sel_hi:[1,0]
	v_pk_mul_f32 v[92:93], v[92:93], v[102:103] op_sel_hi:[1,0]
	v_pk_mul_f32 v[86:87], v[86:87], v[102:103] op_sel_hi:[1,0]
	v_pk_mul_f32 v[94:95], v[94:95], v[102:103] op_sel_hi:[1,0]
	v_pk_mul_f32 v[80:81], v[80:81], v[102:103] op_sel_hi:[1,0]
	v_pk_mul_f32 v[88:89], v[88:89], v[102:103] op_sel_hi:[1,0]
	v_mul_f32_e32 v108, 0xbfb8aa3b, v83
	v_mul_f32_e32 v91, 0xbfb8aa3b, v97
	v_mul_f32_e32 v102, 0xbfb8aa3b, v85
	v_mul_f32_e32 v103, 0xbfb8aa3b, v93
	v_mul_f32_e32 v104, 0xbfb8aa3b, v87
	v_mul_f32_e32 v105, 0xbfb8aa3b, v95
	v_mul_f32_e32 v106, 0xbfb8aa3b, v81
	v_mul_f32_e32 v107, 0xbfb8aa3b, v89
	v_exp_f32_e32 v108, v108
	v_exp_f32_e32 v91, v91
	v_exp_f32_e32 v102, v102
	v_exp_f32_e32 v103, v103
	v_exp_f32_e32 v104, v104
	v_exp_f32_e32 v105, v105
	v_exp_f32_e32 v106, v106
	v_exp_f32_e32 v107, v107
	v_add_f32_e32 v108, 1.0, v108
	v_add_f32_e32 v91, 1.0, v91
	v_add_f32_e32 v102, 1.0, v102
	v_add_f32_e32 v103, 1.0, v103
	v_add_f32_e32 v104, 1.0, v104
	v_add_f32_e32 v105, 1.0, v105
	v_add_f32_e32 v106, 1.0, v106
	v_add_f32_e32 v107, 1.0, v107
	v_rcp_f32_e32 v108, v108
	v_rcp_f32_e32 v91, v91
	v_rcp_f32_e32 v102, v102
	v_rcp_f32_e32 v103, v103
	v_rcp_f32_e32 v104, v104
	v_rcp_f32_e32 v105, v105
	v_rcp_f32_e32 v106, v106
	v_rcp_f32_e32 v107, v107
	v_mul_f32_e32 v83, v83, v108
	v_mul_f32_e32 v91, v97, v91
	v_mul_f32_e32 v85, v85, v102
	v_mul_f32_e32 v93, v93, v103
	v_mul_f32_e32 v87, v87, v104
	v_mul_f32_e32 v95, v95, v105
	v_mul_f32_e32 v81, v81, v106
	v_mul_f32_e32 v89, v89, v107
	v_mul_f32_e32 v83, v82, v83
	v_mul_f32_e32 v91, v96, v91
	v_mul_f32_e32 v84, v84, v85
	v_mul_f32_e32 v85, v92, v93
	v_mul_f32_e32 v86, v86, v87
	v_mul_f32_e32 v87, v94, v95
	v_mul_f32_e32 v92, v80, v81
	v_mul_f32_e32 v88, v88, v89
	v_cvt_pk_bf16_f32 v80, v91, v84
	v_cvt_pk_bf16_f32 v81, v85, v86
	v_cvt_pk_bf16_f32 v82, v87, v92
	v_cvt_pk_bf16_f32 v83, v88, v83
	global_store_dwordx4 v[98:99], v[80:83], off
	s_nop 0
	v_mov_b32_e32 v80, v76
	v_mov_b32_e32 v76, v78
	v_mov_b32_e32 v78, v68
	v_mov_b32_e32 v68, v70
	v_mov_b32_e32 v81, v72
	v_mov_b32_e32 v72, v77
	v_mov_b32_e32 v77, v74
	v_mov_b32_e32 v74, v79
	v_mov_b32_e32 v79, v64
	v_mov_b32_e32 v64, v69
	v_mov_b32_e32 v69, v66
	v_mov_b32_e32 v66, v71
	s_waitcnt vmcnt(7)
	v_mov_b32_e32 v82, v249
	v_fmamk_f32 v70, v82, 0x3a800000, v154
	v_mul_f32_e32 v71, 0x4b800000, v70
	v_cmp_gt_f32_e32 vcc, s54, v70
	s_nop 1
	v_cndmask_b32_e32 v70, v70, v71, vcc
	v_rsq_f32_e32 v82, v70
	v_mad_i64_i32 v[70:71], s[26:27], v90, s55, v[120:121]
	v_lshl_add_u64 v[70:71], v[70:71], 0, v[122:123]
	v_mul_f32_e32 v83, 0x45800000, v82
	v_cndmask_b32_e32 v82, v82, v83, vcc
	v_pk_mul_f32 v[66:67], v[66:67], v[82:83] op_sel_hi:[1,0]
	v_pk_mul_f32 v[80:81], v[80:81], v[82:83] op_sel_hi:[1,0]
	v_pk_mul_f32 v[72:73], v[72:73], v[82:83] op_sel_hi:[1,0]
	v_pk_mul_f32 v[76:77], v[76:77], v[82:83] op_sel_hi:[1,0]
	v_pk_mul_f32 v[74:75], v[74:75], v[82:83] op_sel_hi:[1,0]
	v_pk_mul_f32 v[78:79], v[78:79], v[82:83] op_sel_hi:[1,0]
	v_pk_mul_f32 v[64:65], v[64:65], v[82:83] op_sel_hi:[1,0]
	v_pk_mul_f32 v[68:69], v[68:69], v[82:83] op_sel_hi:[1,0]
	v_mul_f32_e32 v89, 0xbfb8aa3b, v67
	v_mul_f32_e32 v82, 0xbfb8aa3b, v81
	v_mul_f32_e32 v83, 0xbfb8aa3b, v73
	v_mul_f32_e32 v84, 0xbfb8aa3b, v77
	v_mul_f32_e32 v85, 0xbfb8aa3b, v75
	v_mul_f32_e32 v86, 0xbfb8aa3b, v79
	v_mul_f32_e32 v87, 0xbfb8aa3b, v65
	v_mul_f32_e32 v88, 0xbfb8aa3b, v69
	v_exp_f32_e32 v89, v89
	v_exp_f32_e32 v82, v82
	v_exp_f32_e32 v83, v83
	v_exp_f32_e32 v84, v84
	v_exp_f32_e32 v85, v85
	v_exp_f32_e32 v86, v86
	v_exp_f32_e32 v87, v87
	v_exp_f32_e32 v88, v88
	v_add_f32_e32 v89, 1.0, v89
	v_add_f32_e32 v82, 1.0, v82
	v_add_f32_e32 v83, 1.0, v83
	v_add_f32_e32 v84, 1.0, v84
	v_add_f32_e32 v85, 1.0, v85
	v_add_f32_e32 v86, 1.0, v86
	v_add_f32_e32 v87, 1.0, v87
	v_add_f32_e32 v88, 1.0, v88
	v_rcp_f32_e32 v89, v89
	v_rcp_f32_e32 v82, v82
	v_rcp_f32_e32 v83, v83
	v_rcp_f32_e32 v84, v84
	v_rcp_f32_e32 v85, v85
	v_rcp_f32_e32 v86, v86
	v_rcp_f32_e32 v87, v87
	v_rcp_f32_e32 v88, v88
	v_mul_f32_e32 v67, v67, v89
	v_mul_f32_e32 v81, v81, v82
	v_mul_f32_e32 v73, v73, v83
	v_mul_f32_e32 v77, v77, v84
	v_mul_f32_e32 v75, v75, v85
	v_mul_f32_e32 v79, v79, v86
	v_mul_f32_e32 v65, v65, v87
	v_mul_f32_e32 v69, v69, v88
	v_mul_f32_e32 v67, v66, v67
	v_mul_f32_e32 v80, v80, v81
	v_mul_f32_e32 v72, v72, v73
	v_mul_f32_e32 v73, v76, v77
	v_mul_f32_e32 v74, v74, v75
	v_mul_f32_e32 v75, v78, v79
	v_mul_f32_e32 v76, v64, v65
	v_mul_f32_e32 v68, v68, v69
	v_cvt_pk_bf16_f32 v64, v80, v72
	v_cvt_pk_bf16_f32 v65, v73, v74
	v_cvt_pk_bf16_f32 v66, v75, v76
	v_cvt_pk_bf16_f32 v67, v68, v67
	global_store_dwordx4 v[70:71], v[64:67], off
	s_nop 0
	v_mov_b32_e32 v65, v56
	v_mov_b32_e32 v56, v61
	v_mov_b32_e32 v61, v58
	v_mov_b32_e32 v58, v63
	v_mov_b32_e32 v63, v48
	v_mov_b32_e32 v48, v53
	v_mov_b32_e32 v53, v50
	v_mov_b32_e32 v50, v55
	v_mov_b32_e32 v64, v60
	v_mov_b32_e32 v60, v62
	v_mov_b32_e32 v62, v52
	v_mov_b32_e32 v52, v54
	v_add_u32_e32 v54, 0x80, v144
	s_waitcnt vmcnt(7)
	v_mov_b32_e32 v66, v250
	v_fmamk_f32 v55, v66, 0x3a800000, v154
	v_mul_f32_e32 v66, 0x4b800000, v55
	v_cmp_gt_f32_e32 vcc, s54, v55
	s_nop 1
	v_cndmask_b32_e32 v55, v55, v66, vcc
	v_rsq_f32_e32 v66, v55
	v_mad_i64_i32 v[54:55], s[26:27], v54, s55, v[120:121]
	v_lshl_add_u64 v[54:55], v[54:55], 0, v[122:123]
	v_mul_f32_e32 v67, 0x45800000, v66
	v_cndmask_b32_e32 v66, v66, v67, vcc
	v_pk_mul_f32 v[50:51], v[50:51], v[66:67] op_sel_hi:[1,0]
	v_pk_mul_f32 v[64:65], v[64:65], v[66:67] op_sel_hi:[1,0]
	v_pk_mul_f32 v[56:57], v[56:57], v[66:67] op_sel_hi:[1,0]
	v_pk_mul_f32 v[60:61], v[60:61], v[66:67] op_sel_hi:[1,0]
	v_pk_mul_f32 v[58:59], v[58:59], v[66:67] op_sel_hi:[1,0]
	v_pk_mul_f32 v[62:63], v[62:63], v[66:67] op_sel_hi:[1,0]
	v_pk_mul_f32 v[48:49], v[48:49], v[66:67] op_sel_hi:[1,0]
	v_pk_mul_f32 v[52:53], v[52:53], v[66:67] op_sel_hi:[1,0]
	v_mul_f32_e32 v73, 0xbfb8aa3b, v51
	v_mul_f32_e32 v66, 0xbfb8aa3b, v65
	v_mul_f32_e32 v67, 0xbfb8aa3b, v57
	v_mul_f32_e32 v68, 0xbfb8aa3b, v61
	v_mul_f32_e32 v69, 0xbfb8aa3b, v59
	v_mul_f32_e32 v70, 0xbfb8aa3b, v63
	v_mul_f32_e32 v71, 0xbfb8aa3b, v49
	v_mul_f32_e32 v72, 0xbfb8aa3b, v53
	v_exp_f32_e32 v73, v73
	v_exp_f32_e32 v66, v66
	v_exp_f32_e32 v67, v67
	v_exp_f32_e32 v68, v68
	v_exp_f32_e32 v69, v69
	v_exp_f32_e32 v70, v70
	v_exp_f32_e32 v71, v71
	v_exp_f32_e32 v72, v72
	v_add_f32_e32 v73, 1.0, v73
	v_add_f32_e32 v66, 1.0, v66
	v_add_f32_e32 v67, 1.0, v67
	v_add_f32_e32 v68, 1.0, v68
	v_add_f32_e32 v69, 1.0, v69
	v_add_f32_e32 v70, 1.0, v70
	v_add_f32_e32 v71, 1.0, v71
	v_add_f32_e32 v72, 1.0, v72
	v_rcp_f32_e32 v73, v73
	v_rcp_f32_e32 v66, v66
	v_rcp_f32_e32 v67, v67
	v_rcp_f32_e32 v68, v68
	v_rcp_f32_e32 v69, v69
	v_rcp_f32_e32 v70, v70
	v_rcp_f32_e32 v71, v71
	v_rcp_f32_e32 v72, v72
	v_mul_f32_e32 v51, v51, v73
	v_mul_f32_e32 v65, v65, v66
	v_mul_f32_e32 v57, v57, v67
	v_mul_f32_e32 v61, v61, v68
	v_mul_f32_e32 v59, v59, v69
	v_mul_f32_e32 v63, v63, v70
	v_mul_f32_e32 v49, v49, v71
	v_mul_f32_e32 v53, v53, v72
	v_mul_f32_e32 v51, v50, v51
	v_mul_f32_e32 v64, v64, v65
	v_mul_f32_e32 v56, v56, v57
	v_mul_f32_e32 v57, v60, v61
	v_mul_f32_e32 v58, v58, v59
	v_mul_f32_e32 v59, v62, v63
	v_mul_f32_e32 v60, v48, v49
	v_mul_f32_e32 v52, v52, v53
	v_cvt_pk_bf16_f32 v48, v64, v56
	v_cvt_pk_bf16_f32 v49, v57, v58
	v_cvt_pk_bf16_f32 v50, v59, v60
	v_cvt_pk_bf16_f32 v51, v52, v51
	global_store_dwordx4 v[54:55], v[48:51], off
	s_nop 0
	v_mov_b32_e32 v49, v40
	v_mov_b32_e32 v40, v45
	v_mov_b32_e32 v45, v42
	v_mov_b32_e32 v42, v47
	v_mov_b32_e32 v47, v32
	v_mov_b32_e32 v32, v37
	v_mov_b32_e32 v37, v34
	v_mov_b32_e32 v34, v39
	v_mov_b32_e32 v48, v44
	v_mov_b32_e32 v44, v46
	v_mov_b32_e32 v46, v36
	v_mov_b32_e32 v36, v38
	v_add_u32_e32 v38, 0x90, v144
	s_waitcnt vmcnt(7)
	v_mov_b32_e32 v50, v251
	v_fmamk_f32 v39, v50, 0x3a800000, v154
	v_mul_f32_e32 v50, 0x4b800000, v39
	v_cmp_gt_f32_e32 vcc, s54, v39
	s_nop 1
	v_cndmask_b32_e32 v39, v39, v50, vcc
	v_rsq_f32_e32 v50, v39
	v_mad_i64_i32 v[38:39], s[26:27], v38, s55, v[120:121]
	v_lshl_add_u64 v[38:39], v[38:39], 0, v[122:123]
	v_mul_f32_e32 v51, 0x45800000, v50
	v_cndmask_b32_e32 v50, v50, v51, vcc
	v_pk_mul_f32 v[34:35], v[34:35], v[50:51] op_sel_hi:[1,0]
	v_pk_mul_f32 v[48:49], v[48:49], v[50:51] op_sel_hi:[1,0]
	v_pk_mul_f32 v[40:41], v[40:41], v[50:51] op_sel_hi:[1,0]
	v_pk_mul_f32 v[44:45], v[44:45], v[50:51] op_sel_hi:[1,0]
	v_pk_mul_f32 v[42:43], v[42:43], v[50:51] op_sel_hi:[1,0]
	v_pk_mul_f32 v[46:47], v[46:47], v[50:51] op_sel_hi:[1,0]
	v_pk_mul_f32 v[32:33], v[32:33], v[50:51] op_sel_hi:[1,0]
	v_pk_mul_f32 v[36:37], v[36:37], v[50:51] op_sel_hi:[1,0]
	v_mul_f32_e32 v57, 0xbfb8aa3b, v35
	v_mul_f32_e32 v50, 0xbfb8aa3b, v49
	v_mul_f32_e32 v51, 0xbfb8aa3b, v41
	v_mul_f32_e32 v52, 0xbfb8aa3b, v45
	v_mul_f32_e32 v53, 0xbfb8aa3b, v43
	v_mul_f32_e32 v54, 0xbfb8aa3b, v47
	v_mul_f32_e32 v55, 0xbfb8aa3b, v33
	v_mul_f32_e32 v56, 0xbfb8aa3b, v37
	v_exp_f32_e32 v57, v57
	v_exp_f32_e32 v50, v50
	v_exp_f32_e32 v51, v51
	v_exp_f32_e32 v52, v52
	v_exp_f32_e32 v53, v53
	v_exp_f32_e32 v54, v54
	v_exp_f32_e32 v55, v55
	v_exp_f32_e32 v56, v56
	v_add_f32_e32 v57, 1.0, v57
	v_add_f32_e32 v50, 1.0, v50
	v_add_f32_e32 v51, 1.0, v51
	v_add_f32_e32 v52, 1.0, v52
	v_add_f32_e32 v53, 1.0, v53
	v_add_f32_e32 v54, 1.0, v54
	v_add_f32_e32 v55, 1.0, v55
	v_add_f32_e32 v56, 1.0, v56
	v_rcp_f32_e32 v57, v57
	v_rcp_f32_e32 v50, v50
	v_rcp_f32_e32 v51, v51
	v_rcp_f32_e32 v52, v52
	v_rcp_f32_e32 v53, v53
	v_rcp_f32_e32 v54, v54
	v_rcp_f32_e32 v55, v55
	v_rcp_f32_e32 v56, v56
	v_mul_f32_e32 v35, v35, v57
	v_mul_f32_e32 v49, v49, v50
	v_mul_f32_e32 v41, v41, v51
	v_mul_f32_e32 v45, v45, v52
	v_mul_f32_e32 v43, v43, v53
	v_mul_f32_e32 v47, v47, v54
	v_mul_f32_e32 v33, v33, v55
	v_mul_f32_e32 v37, v37, v56
	v_mul_f32_e32 v35, v34, v35
	v_mul_f32_e32 v48, v48, v49
	v_mul_f32_e32 v40, v40, v41
	v_mul_f32_e32 v41, v44, v45
	v_mul_f32_e32 v42, v42, v43
	v_mul_f32_e32 v43, v46, v47
	v_mul_f32_e32 v44, v32, v33
	v_mul_f32_e32 v36, v36, v37
	v_cvt_pk_bf16_f32 v32, v48, v40
	v_cvt_pk_bf16_f32 v33, v41, v42
	v_cvt_pk_bf16_f32 v34, v43, v44
	v_cvt_pk_bf16_f32 v35, v36, v35
	global_store_dwordx4 v[38:39], v[32:35], off
	s_nop 0
	v_mov_b32_e32 v33, v24
	v_mov_b32_e32 v24, v29
	v_mov_b32_e32 v29, v26
	v_mov_b32_e32 v26, v31
	v_mov_b32_e32 v31, v16
	v_mov_b32_e32 v16, v21
	v_mov_b32_e32 v21, v18
	v_mov_b32_e32 v18, v23
	v_mov_b32_e32 v32, v28
	v_mov_b32_e32 v28, v30
	v_mov_b32_e32 v30, v20
	v_mov_b32_e32 v20, v22
	v_add_u32_e32 v22, 0xa0, v144
	s_waitcnt vmcnt(7)
	v_mov_b32_e32 v34, v252
	v_fmamk_f32 v23, v34, 0x3a800000, v154
	v_mul_f32_e32 v34, 0x4b800000, v23
	v_cmp_gt_f32_e32 vcc, s54, v23
	s_nop 1
	v_cndmask_b32_e32 v23, v23, v34, vcc
	v_rsq_f32_e32 v34, v23
	v_mad_i64_i32 v[22:23], s[26:27], v22, s55, v[120:121]
	v_lshl_add_u64 v[22:23], v[22:23], 0, v[122:123]
	v_mul_f32_e32 v35, 0x45800000, v34
	v_cndmask_b32_e32 v34, v34, v35, vcc
	v_pk_mul_f32 v[18:19], v[18:19], v[34:35] op_sel_hi:[1,0]
	v_pk_mul_f32 v[32:33], v[32:33], v[34:35] op_sel_hi:[1,0]
	v_pk_mul_f32 v[24:25], v[24:25], v[34:35] op_sel_hi:[1,0]
	v_pk_mul_f32 v[28:29], v[28:29], v[34:35] op_sel_hi:[1,0]
	v_pk_mul_f32 v[26:27], v[26:27], v[34:35] op_sel_hi:[1,0]
	v_pk_mul_f32 v[30:31], v[30:31], v[34:35] op_sel_hi:[1,0]
	v_pk_mul_f32 v[16:17], v[16:17], v[34:35] op_sel_hi:[1,0]
	v_pk_mul_f32 v[20:21], v[20:21], v[34:35] op_sel_hi:[1,0]
	v_mul_f32_e32 v41, 0xbfb8aa3b, v19
	v_mul_f32_e32 v34, 0xbfb8aa3b, v33
	v_mul_f32_e32 v35, 0xbfb8aa3b, v25
	v_mul_f32_e32 v36, 0xbfb8aa3b, v29
	v_mul_f32_e32 v37, 0xbfb8aa3b, v27
	v_mul_f32_e32 v38, 0xbfb8aa3b, v31
	v_mul_f32_e32 v39, 0xbfb8aa3b, v17
	v_mul_f32_e32 v40, 0xbfb8aa3b, v21
	v_exp_f32_e32 v41, v41
	v_exp_f32_e32 v34, v34
	v_exp_f32_e32 v35, v35
	v_exp_f32_e32 v36, v36
	v_exp_f32_e32 v37, v37
	v_exp_f32_e32 v38, v38
	v_exp_f32_e32 v39, v39
	v_exp_f32_e32 v40, v40
	v_add_f32_e32 v41, 1.0, v41
	v_add_f32_e32 v34, 1.0, v34
	v_add_f32_e32 v35, 1.0, v35
	v_add_f32_e32 v36, 1.0, v36
	v_add_f32_e32 v37, 1.0, v37
	v_add_f32_e32 v38, 1.0, v38
	v_add_f32_e32 v39, 1.0, v39
	v_add_f32_e32 v40, 1.0, v40
	v_rcp_f32_e32 v41, v41
	v_rcp_f32_e32 v34, v34
	v_rcp_f32_e32 v35, v35
	v_rcp_f32_e32 v36, v36
	v_rcp_f32_e32 v37, v37
	v_rcp_f32_e32 v38, v38
	v_rcp_f32_e32 v39, v39
	v_rcp_f32_e32 v40, v40
	v_mul_f32_e32 v19, v19, v41
	v_mul_f32_e32 v33, v33, v34
	v_mul_f32_e32 v25, v25, v35
	v_mul_f32_e32 v29, v29, v36
	v_mul_f32_e32 v27, v27, v37
	v_mul_f32_e32 v31, v31, v38
	v_mul_f32_e32 v17, v17, v39
	v_mul_f32_e32 v21, v21, v40
	v_mul_f32_e32 v19, v18, v19
	v_mul_f32_e32 v32, v32, v33
	v_mul_f32_e32 v24, v24, v25
	v_mul_f32_e32 v25, v28, v29
	v_mul_f32_e32 v26, v26, v27
	v_mul_f32_e32 v27, v30, v31
	v_mul_f32_e32 v28, v16, v17
	v_mul_f32_e32 v20, v20, v21
	v_cvt_pk_bf16_f32 v16, v32, v24
	v_cvt_pk_bf16_f32 v17, v25, v26
	v_cvt_pk_bf16_f32 v18, v27, v28
	v_cvt_pk_bf16_f32 v19, v20, v19
	global_store_dwordx4 v[22:23], v[16:19], off
	s_and_b64 vcc, exec, s[8:9]
	v_mov_b32_e32 v17, v8
	v_mov_b32_e32 v8, v13
	v_mov_b32_e32 v13, v10
	v_mov_b32_e32 v10, v15
	v_mov_b32_e32 v15, v0
	v_mov_b32_e32 v0, v5
	v_mov_b32_e32 v5, v2
	v_mov_b32_e32 v2, v7
	v_mov_b32_e32 v16, v12
	v_mov_b32_e32 v12, v14
	v_mov_b32_e32 v14, v4
	v_mov_b32_e32 v4, v6
	v_add_u32_e32 v6, 0xb0, v144
	s_mov_b64 s[26:27], s[20:21]
	s_waitcnt vmcnt(7)
	v_mov_b32_e32 v18, v253
	v_fmamk_f32 v7, v18, 0x3a800000, v154
	v_mul_f32_e32 v18, 0x4b800000, v7
	v_cmp_gt_f32_e64 s[8:9], s54, v7
	s_nop 1
	v_cndmask_b32_e64 v7, v7, v18, s[8:9]
	v_rsq_f32_e32 v18, v7
	v_mad_i64_i32 v[6:7], s[20:21], v6, s55, v[120:121]
	v_lshl_add_u64 v[6:7], v[6:7], 0, v[122:123]
	v_mul_f32_e32 v19, 0x45800000, v18
	v_cndmask_b32_e64 v18, v18, v19, s[8:9]
	v_pk_mul_f32 v[2:3], v[2:3], v[18:19] op_sel_hi:[1,0]
	v_pk_mul_f32 v[16:17], v[16:17], v[18:19] op_sel_hi:[1,0]
	v_pk_mul_f32 v[8:9], v[8:9], v[18:19] op_sel_hi:[1,0]
	v_pk_mul_f32 v[12:13], v[12:13], v[18:19] op_sel_hi:[1,0]
	v_pk_mul_f32 v[10:11], v[10:11], v[18:19] op_sel_hi:[1,0]
	v_pk_mul_f32 v[14:15], v[14:15], v[18:19] op_sel_hi:[1,0]
	v_pk_mul_f32 v[0:1], v[0:1], v[18:19] op_sel_hi:[1,0]
	v_pk_mul_f32 v[4:5], v[4:5], v[18:19] op_sel_hi:[1,0]
	v_mul_f32_e32 v25, 0xbfb8aa3b, v3
	v_mul_f32_e32 v18, 0xbfb8aa3b, v17
	v_mul_f32_e32 v19, 0xbfb8aa3b, v9
	v_mul_f32_e32 v20, 0xbfb8aa3b, v13
	v_mul_f32_e32 v21, 0xbfb8aa3b, v11
	v_mul_f32_e32 v22, 0xbfb8aa3b, v15
	v_mul_f32_e32 v23, 0xbfb8aa3b, v1
	v_mul_f32_e32 v24, 0xbfb8aa3b, v5
	v_exp_f32_e32 v25, v25
	v_exp_f32_e32 v18, v18
	v_exp_f32_e32 v19, v19
	v_exp_f32_e32 v20, v20
	v_exp_f32_e32 v21, v21
	v_exp_f32_e32 v22, v22
	v_exp_f32_e32 v23, v23
	v_exp_f32_e32 v24, v24
	v_add_f32_e32 v25, 1.0, v25
	v_add_f32_e32 v18, 1.0, v18
	v_add_f32_e32 v19, 1.0, v19
	v_add_f32_e32 v20, 1.0, v20
	v_add_f32_e32 v21, 1.0, v21
	v_add_f32_e32 v22, 1.0, v22
	v_add_f32_e32 v23, 1.0, v23
	v_add_f32_e32 v24, 1.0, v24
	v_rcp_f32_e32 v25, v25
	v_rcp_f32_e32 v18, v18
	v_rcp_f32_e32 v19, v19
	v_rcp_f32_e32 v20, v20
	v_rcp_f32_e32 v21, v21
	v_rcp_f32_e32 v22, v22
	v_rcp_f32_e32 v23, v23
	v_rcp_f32_e32 v24, v24
	v_mul_f32_e32 v3, v3, v25
	v_mul_f32_e32 v17, v17, v18
	v_mul_f32_e32 v9, v9, v19
	v_mul_f32_e32 v13, v13, v20
	v_mul_f32_e32 v11, v11, v21
	v_mul_f32_e32 v15, v15, v22
	v_mul_f32_e32 v1, v1, v23
	v_mul_f32_e32 v5, v5, v24
	v_mul_f32_e32 v3, v2, v3
	v_mul_f32_e32 v16, v16, v17
	v_mul_f32_e32 v8, v8, v9
	v_mul_f32_e32 v9, v12, v13
	v_mul_f32_e32 v10, v10, v11
	v_mul_f32_e32 v11, v14, v15
	v_mul_f32_e32 v12, v0, v1
	v_mul_f32_e32 v4, v4, v5
	v_cvt_pk_bf16_f32 v0, v16, v8
	v_cvt_pk_bf16_f32 v1, v9, v10
	v_cvt_pk_bf16_f32 v2, v11, v12
	v_cvt_pk_bf16_f32 v3, v4, v3
	global_store_dwordx4 v[6:7], v[0:3], off
	s_cbranch_vccz .LBB0_440
	s_waitcnt vmcnt(0)
	s_cmpk_gt_u32 s4, 0xff
	s_cbranch_scc1 .LBB0_451
	s_barrier

.LBB0_955:
	ds_read_b128 v[144:147], v151
	ds_read_b128 v[156:159], v151 offset:1024
	ds_read_b128 v[160:163], v151 offset:2048
	ds_read_b128 v[164:167], v151 offset:3072
	s_add_u32 s30, s28, 0xfffc0080
	s_addc_u32 s31, s29, -1
	s_cmp_eq_u32 s69, 12
	s_cselect_b32 s35, s17, s31
	s_cselect_b32 s34, s65, s30
	s_cselect_b32 s31, s15, s68
	s_cselect_b32 s30, s66, s67
	v_lshl_add_u64 v[172:173], s[28:29], 0, v[136:137]
	s_add_i32 m0, s27, 0xc000
	ds_read_b128 v[168:171], v152
	ds_read_b128 v[178:181], v152 offset:1024
	ds_read_b128 v[182:185], v152 offset:2048
	ds_read_b128 v[186:189], v152 offset:3072
	ds_read_b128 v[190:193], v152 offset:4096
	ds_read_b128 v[194:197], v152 offset:5120
	ds_read_b128 v[198:201], v152 offset:6144
	ds_read_b128 v[202:205], v152 offset:7168
	global_load_lds_dwordx4 v[172:173], off
	v_lshl_add_u64 v[172:173], s[28:29], 0, v[138:139]
	s_add_i32 m0, s27, 0xe000
	s_nop 0
	global_load_lds_dwordx4 v[172:173], off
	s_waitcnt lgkmcnt(8)
	s_barrier
	s_waitcnt lgkmcnt(0)
	s_setprio 1
	s_waitcnt lgkmcnt(0)
	v_mfma_f32_16x16x32_bf16 v[116:119], v[144:147], v[168:171], v[116:119]
	v_mfma_f32_16x16x32_bf16 v[112:115], v[160:163], v[168:171], v[112:115]
	v_mfma_f32_16x16x32_bf16 v[100:103], v[144:147], v[182:185], v[100:103]
	v_mfma_f32_16x16x32_bf16 v[96:99], v[160:163], v[182:185], v[96:99]
	v_mfma_f32_16x16x32_bf16 v[84:87], v[144:147], v[190:193], v[84:87]
	v_mfma_f32_16x16x32_bf16 v[80:83], v[160:163], v[190:193], v[80:83]
	v_mfma_f32_16x16x32_bf16 v[72:75], v[144:147], v[198:201], v[72:75]
	v_mfma_f32_16x16x32_bf16 v[64:67], v[160:163], v[198:201], v[64:67]
	v_mfma_f32_16x16x32_bf16 v[116:119], v[156:159], v[178:181], v[116:119]
	v_mfma_f32_16x16x32_bf16 v[112:115], v[164:167], v[178:181], v[112:115]
	v_mfma_f32_16x16x32_bf16 v[100:103], v[156:159], v[186:189], v[100:103]
	v_mfma_f32_16x16x32_bf16 v[96:99], v[164:167], v[186:189], v[96:99]
	v_mfma_f32_16x16x32_bf16 v[84:87], v[156:159], v[194:197], v[84:87]
	v_mfma_f32_16x16x32_bf16 v[80:83], v[164:167], v[194:197], v[80:83]
	v_mfma_f32_16x16x32_bf16 v[72:75], v[156:159], v[202:205], v[72:75]
	v_mfma_f32_16x16x32_bf16 v[64:67], v[164:167], v[202:205], v[64:67]
	s_setprio 0
	s_barrier
	s_add_i32 s77, s58, s36
	v_lshl_add_u64 v[172:173], s[30:31], 0, v[130:131]
	s_mov_b32 m0, s77
	ds_read_b128 v[206:209], v153
	ds_read_b128 v[210:213], v153 offset:1024
	ds_read_b128 v[214:217], v153 offset:2048
	ds_read_b128 v[218:221], v153 offset:3072
	global_load_lds_dwordx4 v[172:173], off
	v_lshl_add_u64 v[222:223], s[30:31], 0, v[134:135]
	s_add_i32 m0, s77, 0x2000
	s_nop 0
	global_load_lds_dwordx4 v[222:223], off
	s_barrier
	s_waitcnt lgkmcnt(0)
	s_setprio 1
	s_waitcnt lgkmcnt(0)
	v_mfma_f32_16x16x32_bf16 v[124:127], v[206:209], v[168:171], v[124:127]
	v_mfma_f32_16x16x32_bf16 v[120:123], v[214:217], v[168:171], v[120:123]
	v_mfma_f32_16x16x32_bf16 v[108:111], v[206:209], v[182:185], v[108:111]
	v_mfma_f32_16x16x32_bf16 v[104:107], v[214:217], v[182:185], v[104:107]
	v_mfma_f32_16x16x32_bf16 v[92:95], v[206:209], v[190:193], v[92:95]
	v_mfma_f32_16x16x32_bf16 v[88:91], v[214:217], v[190:193], v[88:91]
	v_mfma_f32_16x16x32_bf16 v[76:79], v[206:209], v[198:201], v[76:79]
	v_mfma_f32_16x16x32_bf16 v[68:71], v[214:217], v[198:201], v[68:71]
	v_mfma_f32_16x16x32_bf16 v[124:127], v[210:213], v[178:181], v[124:127]
	v_mfma_f32_16x16x32_bf16 v[120:123], v[218:221], v[178:181], v[120:123]
	v_mfma_f32_16x16x32_bf16 v[108:111], v[210:213], v[186:189], v[108:111]
	v_mfma_f32_16x16x32_bf16 v[104:107], v[218:221], v[186:189], v[104:107]
	v_mfma_f32_16x16x32_bf16 v[92:95], v[210:213], v[194:197], v[92:95]
	v_mfma_f32_16x16x32_bf16 v[88:91], v[218:221], v[194:197], v[88:91]
	v_mfma_f32_16x16x32_bf16 v[76:79], v[210:213], v[202:205], v[76:79]
	v_mfma_f32_16x16x32_bf16 v[68:71], v[218:221], v[202:205], v[68:71]
	s_setprio 0
	s_mov_b32 m0, s27
	v_lshl_add_u64 v[224:225], s[34:35], 0, v[128:129]
	s_barrier
	ds_read_b128 v[168:171], v152 offset:16384
	ds_read_b128 v[178:181], v152 offset:17408
	ds_read_b128 v[182:185], v152 offset:18432
	ds_read_b128 v[186:189], v152 offset:19456
	ds_read_b128 v[190:193], v152 offset:20480
	ds_read_b128 v[194:197], v152 offset:21504
	ds_read_b128 v[198:201], v152 offset:22528
	ds_read_b128 v[202:205], v152 offset:23552
	global_load_lds_dwordx4 v[224:225], off
	v_lshl_add_u64 v[226:227], s[34:35], 0, v[132:133]
	s_mov_b32 m0, s37
	s_nop 0
	global_load_lds_dwordx4 v[226:227], off
	s_barrier
	s_waitcnt lgkmcnt(0)
	s_setprio 1
	s_waitcnt lgkmcnt(0)
	v_mfma_f32_16x16x32_bf16 v[56:59], v[144:147], v[168:171], v[56:59]
	v_mfma_f32_16x16x32_bf16 v[48:51], v[160:163], v[168:171], v[48:51]
	v_mfma_f32_16x16x32_bf16 v[40:43], v[144:147], v[182:185], v[40:43]
	v_mfma_f32_16x16x32_bf16 v[32:35], v[160:163], v[182:185], v[32:35]
	v_mfma_f32_16x16x32_bf16 v[24:27], v[144:147], v[190:193], v[24:27]
	v_mfma_f32_16x16x32_bf16 v[16:19], v[160:163], v[190:193], v[16:19]
	v_mfma_f32_16x16x32_bf16 v[8:11], v[144:147], v[198:201], v[8:11]
	v_mfma_f32_16x16x32_bf16 v[0:3], v[160:163], v[198:201], v[0:3]
	v_mfma_f32_16x16x32_bf16 v[56:59], v[156:159], v[178:181], v[56:59]
	v_mfma_f32_16x16x32_bf16 v[48:51], v[164:167], v[178:181], v[48:51]
	v_mfma_f32_16x16x32_bf16 v[40:43], v[156:159], v[186:189], v[40:43]
	v_mfma_f32_16x16x32_bf16 v[32:35], v[164:167], v[186:189], v[32:35]
	v_mfma_f32_16x16x32_bf16 v[24:27], v[156:159], v[194:197], v[24:27]
	v_mfma_f32_16x16x32_bf16 v[16:19], v[164:167], v[194:197], v[16:19]
	v_mfma_f32_16x16x32_bf16 v[8:11], v[156:159], v[202:205], v[8:11]
	v_mfma_f32_16x16x32_bf16 v[0:3], v[164:167], v[202:205], v[0:3]
	s_setprio 0
	s_barrier
	s_add_u32 s80, s30, 0x40000
	s_addc_u32 s81, s31, 0
	s_add_i32 s77, s59, s36
	v_lshl_add_u64 v[144:145], s[80:81], 0, v[130:131]
	s_mov_b32 m0, s77
	s_nop 0
	global_load_lds_dwordx4 v[144:145], off
	v_lshl_add_u64 v[144:145], s[80:81], 0, v[134:135]
	s_add_i32 m0, s77, 0x2000
	s_nop 0
	global_load_lds_dwordx4 v[144:145], off
	s_waitcnt vmcnt(6)
	s_barrier
	s_setprio 1
	v_mfma_f32_16x16x32_bf16 v[60:63], v[206:209], v[168:171], v[60:63]
	v_mfma_f32_16x16x32_bf16 v[52:55], v[214:217], v[168:171], v[52:55]
	v_mfma_f32_16x16x32_bf16 v[44:47], v[206:209], v[182:185], v[44:47]
	v_mfma_f32_16x16x32_bf16 v[36:39], v[214:217], v[182:185], v[36:39]
	v_mfma_f32_16x16x32_bf16 v[28:31], v[206:209], v[190:193], v[28:31]
	v_mfma_f32_16x16x32_bf16 v[20:23], v[214:217], v[190:193], v[20:23]
	v_mfma_f32_16x16x32_bf16 v[12:15], v[206:209], v[198:201], v[12:15]
	v_mfma_f32_16x16x32_bf16 v[4:7], v[214:217], v[198:201], v[4:7]
	v_mfma_f32_16x16x32_bf16 v[60:63], v[210:213], v[178:181], v[60:63]
	v_mfma_f32_16x16x32_bf16 v[52:55], v[218:221], v[178:181], v[52:55]
	v_mfma_f32_16x16x32_bf16 v[44:47], v[210:213], v[186:189], v[44:47]
	v_mfma_f32_16x16x32_bf16 v[36:39], v[218:221], v[186:189], v[36:39]
	v_mfma_f32_16x16x32_bf16 v[28:31], v[210:213], v[194:197], v[28:31]
	v_mfma_f32_16x16x32_bf16 v[20:23], v[218:221], v[194:197], v[20:23]
	v_mfma_f32_16x16x32_bf16 v[12:15], v[210:213], v[202:205], v[12:15]
	v_mfma_f32_16x16x32_bf16 v[4:7], v[218:221], v[202:205], v[4:7]
	s_setprio 0
	s_add_i32 s77, 0, 0x18000
	v_add_u32_e32 v155, s77, v149
	s_barrier
	ds_read_b128 v[144:147], v155
	ds_read_b128 v[156:159], v155 offset:1024
	ds_read_b128 v[160:163], v155 offset:2048
	ds_read_b128 v[164:167], v155 offset:3072
	s_add_u32 s34, s34, 0x40000
	s_addc_u32 s35, s35, 0
	s_mov_b32 m0, s46
	v_lshl_add_u64 v[206:207], s[34:35], 0, v[128:129]
	ds_read_b128 v[168:171], v152 offset:32768
	ds_read_b128 v[178:181], v152 offset:33792
	ds_read_b128 v[182:185], v152 offset:34816
	ds_read_b128 v[186:189], v152 offset:35840
	ds_read_b128 v[190:193], v152 offset:36864
	ds_read_b128 v[194:197], v152 offset:37888
	ds_read_b128 v[198:201], v152 offset:38912
	ds_read_b128 v[202:205], v152 offset:39936
	global_load_lds_dwordx4 v[206:207], off
	v_lshl_add_u64 v[206:207], s[34:35], 0, v[132:133]
	s_mov_b32 m0, s47
	s_nop 0
	global_load_lds_dwordx4 v[206:207], off
	s_waitcnt lgkmcnt(8)
	s_barrier
	s_waitcnt lgkmcnt(0)
	s_setprio 1
	s_waitcnt lgkmcnt(0)
	v_mfma_f32_16x16x32_bf16 v[116:119], v[144:147], v[168:171], v[116:119]
	v_mfma_f32_16x16x32_bf16 v[112:115], v[160:163], v[168:171], v[112:115]
	v_mfma_f32_16x16x32_bf16 v[100:103], v[144:147], v[182:185], v[100:103]
	v_mfma_f32_16x16x32_bf16 v[96:99], v[160:163], v[182:185], v[96:99]
	v_mfma_f32_16x16x32_bf16 v[84:87], v[144:147], v[190:193], v[84:87]
	v_mfma_f32_16x16x32_bf16 v[80:83], v[160:163], v[190:193], v[80:83]
	v_mfma_f32_16x16x32_bf16 v[72:75], v[144:147], v[198:201], v[72:75]
	v_mfma_f32_16x16x32_bf16 v[64:67], v[160:163], v[198:201], v[64:67]
	v_mfma_f32_16x16x32_bf16 v[116:119], v[156:159], v[178:181], v[116:119]
	v_mfma_f32_16x16x32_bf16 v[112:115], v[164:167], v[178:181], v[112:115]
	v_mfma_f32_16x16x32_bf16 v[100:103], v[156:159], v[186:189], v[100:103]
	v_mfma_f32_16x16x32_bf16 v[96:99], v[164:167], v[186:189], v[96:99]
	v_mfma_f32_16x16x32_bf16 v[84:87], v[156:159], v[194:197], v[84:87]
	v_mfma_f32_16x16x32_bf16 v[80:83], v[164:167], v[194:197], v[80:83]
	v_mfma_f32_16x16x32_bf16 v[72:75], v[156:159], v[202:205], v[72:75]
	v_mfma_f32_16x16x32_bf16 v[64:67], v[164:167], v[202:205], v[64:67]
	s_setprio 0
	s_barrier
	s_add_i32 s34, 0, 0x1c000
	s_add_i32 s35, s77, s36
	v_add_u32_e32 v155, s34, v149
	v_lshl_add_u64 v[172:173], v[172:173], 0, s[10:11]
	s_mov_b32 m0, s35
	ds_read_b128 v[206:209], v155
	ds_read_b128 v[210:213], v155 offset:1024
	ds_read_b128 v[214:217], v155 offset:2048
	ds_read_b128 v[218:221], v155 offset:3072
	global_load_lds_dwordx4 v[172:173], off
	v_lshl_add_u64 v[172:173], v[222:223], 0, s[10:11]
	s_add_i32 m0, s35, 0x2000
	s_nop 0
	global_load_lds_dwordx4 v[172:173], off
	s_barrier
	s_waitcnt lgkmcnt(0)
	s_setprio 1
	s_waitcnt lgkmcnt(0)
	v_mfma_f32_16x16x32_bf16 v[124:127], v[206:209], v[168:171], v[124:127]
	v_mfma_f32_16x16x32_bf16 v[120:123], v[214:217], v[168:171], v[120:123]
	v_mfma_f32_16x16x32_bf16 v[108:111], v[206:209], v[182:185], v[108:111]
	v_mfma_f32_16x16x32_bf16 v[104:107], v[214:217], v[182:185], v[104:107]
	v_mfma_f32_16x16x32_bf16 v[92:95], v[206:209], v[190:193], v[92:95]
	v_mfma_f32_16x16x32_bf16 v[88:91], v[214:217], v[190:193], v[88:91]
	v_mfma_f32_16x16x32_bf16 v[76:79], v[206:209], v[198:201], v[76:79]
	v_mfma_f32_16x16x32_bf16 v[68:71], v[214:217], v[198:201], v[68:71]
	v_mfma_f32_16x16x32_bf16 v[124:127], v[210:213], v[178:181], v[124:127]
	v_mfma_f32_16x16x32_bf16 v[120:123], v[218:221], v[178:181], v[120:123]
	v_mfma_f32_16x16x32_bf16 v[108:111], v[210:213], v[186:189], v[108:111]
	v_mfma_f32_16x16x32_bf16 v[104:107], v[218:221], v[186:189], v[104:107]
	v_mfma_f32_16x16x32_bf16 v[92:95], v[210:213], v[194:197], v[92:95]
	v_mfma_f32_16x16x32_bf16 v[88:91], v[218:221], v[194:197], v[88:91]
	v_mfma_f32_16x16x32_bf16 v[76:79], v[210:213], v[202:205], v[76:79]
	v_mfma_f32_16x16x32_bf16 v[68:71], v[218:221], v[202:205], v[68:71]
	s_setprio 0
	s_mov_b32 m0, s55
	v_lshl_add_u64 v[172:173], v[224:225], 0, s[10:11]
	s_barrier
	ds_read_b128 v[168:171], v152 offset:49152
	ds_read_b128 v[178:181], v152 offset:50176
	ds_read_b128 v[182:185], v152 offset:51200
	ds_read_b128 v[186:189], v152 offset:52224
	ds_read_b128 v[190:193], v152 offset:53248
	ds_read_b128 v[194:197], v152 offset:54272
	ds_read_b128 v[198:201], v152 offset:55296
	ds_read_b128 v[202:205], v152 offset:56320
	global_load_lds_dwordx4 v[172:173], off
	v_lshl_add_u64 v[172:173], v[226:227], 0, s[10:11]
	s_mov_b32 m0, s56
	s_nop 0
	global_load_lds_dwordx4 v[172:173], off
	s_barrier
	s_waitcnt lgkmcnt(0)
	s_setprio 1
	s_waitcnt lgkmcnt(0)
	v_mfma_f32_16x16x32_bf16 v[56:59], v[144:147], v[168:171], v[56:59]
	v_mfma_f32_16x16x32_bf16 v[48:51], v[160:163], v[168:171], v[48:51]
	v_mfma_f32_16x16x32_bf16 v[40:43], v[144:147], v[182:185], v[40:43]
	v_mfma_f32_16x16x32_bf16 v[32:35], v[160:163], v[182:185], v[32:35]
	v_mfma_f32_16x16x32_bf16 v[24:27], v[144:147], v[190:193], v[24:27]
	v_mfma_f32_16x16x32_bf16 v[16:19], v[160:163], v[190:193], v[16:19]
	v_mfma_f32_16x16x32_bf16 v[8:11], v[144:147], v[198:201], v[8:11]
	v_mfma_f32_16x16x32_bf16 v[0:3], v[160:163], v[198:201], v[0:3]
	v_mfma_f32_16x16x32_bf16 v[56:59], v[156:159], v[178:181], v[56:59]
	v_mfma_f32_16x16x32_bf16 v[48:51], v[164:167], v[178:181], v[48:51]
	v_mfma_f32_16x16x32_bf16 v[40:43], v[156:159], v[186:189], v[40:43]
	v_mfma_f32_16x16x32_bf16 v[32:35], v[164:167], v[186:189], v[32:35]
	v_mfma_f32_16x16x32_bf16 v[24:27], v[156:159], v[194:197], v[24:27]
	v_mfma_f32_16x16x32_bf16 v[16:19], v[164:167], v[194:197], v[16:19]
	v_mfma_f32_16x16x32_bf16 v[8:11], v[156:159], v[202:205], v[8:11]
	v_mfma_f32_16x16x32_bf16 v[0:3], v[164:167], v[202:205], v[0:3]
	s_setprio 0
	s_barrier
	s_add_u32 s30, s30, 0x40080
	s_addc_u32 s31, s31, 0
	s_add_i32 s34, s34, s36
	v_lshl_add_u64 v[144:145], s[30:31], 0, v[130:131]
	s_mov_b32 m0, s34
	s_nop 0
	global_load_lds_dwordx4 v[144:145], off
	v_lshl_add_u64 v[144:145], s[30:31], 0, v[134:135]
	s_add_i32 m0, s34, 0x2000
	s_nop 0
	global_load_lds_dwordx4 v[144:145], off
	s_waitcnt vmcnt(6)
	s_barrier
	s_setprio 1
	v_mfma_f32_16x16x32_bf16 v[60:63], v[206:209], v[168:171], v[60:63]
	v_mfma_f32_16x16x32_bf16 v[52:55], v[214:217], v[168:171], v[52:55]
	v_mfma_f32_16x16x32_bf16 v[44:47], v[206:209], v[182:185], v[44:47]
	v_mfma_f32_16x16x32_bf16 v[36:39], v[214:217], v[182:185], v[36:39]
	v_mfma_f32_16x16x32_bf16 v[28:31], v[206:209], v[190:193], v[28:31]
	v_mfma_f32_16x16x32_bf16 v[20:23], v[214:217], v[190:193], v[20:23]
	v_mfma_f32_16x16x32_bf16 v[12:15], v[206:209], v[198:201], v[12:15]
	v_mfma_f32_16x16x32_bf16 v[4:7], v[214:217], v[198:201], v[4:7]
	v_mfma_f32_16x16x32_bf16 v[60:63], v[210:213], v[178:181], v[60:63]
	v_mfma_f32_16x16x32_bf16 v[52:55], v[218:221], v[178:181], v[52:55]
	v_mfma_f32_16x16x32_bf16 v[44:47], v[210:213], v[186:189], v[44:47]
	v_mfma_f32_16x16x32_bf16 v[36:39], v[218:221], v[186:189], v[36:39]
	v_mfma_f32_16x16x32_bf16 v[28:31], v[210:213], v[194:197], v[28:31]
	v_mfma_f32_16x16x32_bf16 v[20:23], v[218:221], v[194:197], v[20:23]
	v_mfma_f32_16x16x32_bf16 v[12:15], v[210:213], v[202:205], v[12:15]
	v_mfma_f32_16x16x32_bf16 v[4:7], v[218:221], v[202:205], v[4:7]
	s_setprio 0
	s_add_i32 s69, s69, 2
	s_add_u32 s28, s28, 0x100
	s_addc_u32 s29, s29, 0
	s_add_u32 s67, s67, 0x100
	s_addc_u32 s68, s68, 0
	s_cmp_gt_u32 s69, 13
	s_barrier
	s_cbranch_scc0 .LBB0_955
	v_lshl_add_u32 v144, s26, 8, v148
	v_ashrrev_i32_e32 v145, 31, v144
	v_lshl_add_u64 v[146:147], v[144:145], 2, s[24:25]
	global_load_dword v145, v[146:147], off
	global_load_dword v247, v[146:147], off offset:64
	global_load_dword v248, v[146:147], off offset:128
	global_load_dword v249, v[146:147], off offset:192
	global_load_dword v250, v[146:147], off offset:512
	global_load_dword v251, v[146:147], off offset:576
	global_load_dword v252, v[146:147], off offset:640
	global_load_dword v253, v[146:147], off offset:704
	v_lshl_or_b32 v156, s64, 7, v150
	v_mov_b32_e32 v161, v114
	v_mov_b32_e32 v114, v123
	v_mov_b32_e32 v158, v124
	v_mov_b32_e32 v159, v116
	v_mov_b32_e32 v116, v125
	v_mov_b32_e32 v124, v126
	v_mov_b32_e32 v125, v118
	v_mov_b32_e32 v118, v127
	v_mov_b32_e32 v126, v120
	v_mov_b32_e32 v127, v112
	v_mov_b32_e32 v112, v121
	v_mov_b32_e32 v160, v122
	v_mov_b64_e32 v[120:121], s[44:45]
	v_ashrrev_i32_e32 v157, 31, v156
	v_or_b32_e32 v164, 16, v144
	v_mad_i64_i32 v[162:163], s[28:29], v144, s63, v[120:121]
	v_lshlrev_b64 v[122:123], 1, v[156:157]
	v_ashrrev_i32_e32 v165, 31, v164
	v_lshl_add_u64 v[156:157], v[162:163], 0, v[122:123]
	v_lshl_add_u64 v[162:163], v[164:165], 2, s[24:25]
	s_mov_b32 s64, s14
	s_mov_b32 s26, s16
	s_mov_b64 s[30:31], s[20:21]
	s_waitcnt vmcnt(7)
	v_fmamk_f32 v145, v145, 0x3a800000, v154
	v_mul_f32_e32 v155, 0x4b800000, v145
	v_cmp_gt_f32_e32 vcc, s62, v145
	s_nop 1
	v_cndmask_b32_e32 v145, v145, v155, vcc
	v_rsq_f32_e32 v145, v145
	s_nop 0
	v_mul_f32_e32 v155, 0x45800000, v145
	v_cndmask_b32_e32 v166, v145, v155, vcc
	v_pk_mul_f32 v[114:115], v[114:115], v[166:167] op_sel_hi:[1,0]
	v_pk_mul_f32 v[158:159], v[158:159], v[166:167] op_sel_hi:[1,0]
	v_pk_mul_f32 v[116:117], v[116:117], v[166:167] op_sel_hi:[1,0]
	v_pk_mul_f32 v[124:125], v[124:125], v[166:167] op_sel_hi:[1,0]
	v_pk_mul_f32 v[118:119], v[118:119], v[166:167] op_sel_hi:[1,0]
	v_pk_mul_f32 v[126:127], v[126:127], v[166:167] op_sel_hi:[1,0]
	v_pk_mul_f32 v[112:113], v[112:113], v[166:167] op_sel_hi:[1,0]
	v_pk_mul_f32 v[160:161], v[160:161], v[166:167] op_sel_hi:[1,0]
	v_mul_f32_e32 v170, 0xbfb8aa3b, v115
	v_mul_f32_e32 v145, 0xbfb8aa3b, v159
	v_mul_f32_e32 v155, 0xbfb8aa3b, v117
	v_mul_f32_e32 v165, 0xbfb8aa3b, v125
	v_mul_f32_e32 v166, 0xbfb8aa3b, v119
	v_mul_f32_e32 v167, 0xbfb8aa3b, v127
	v_mul_f32_e32 v168, 0xbfb8aa3b, v113
	v_mul_f32_e32 v169, 0xbfb8aa3b, v161
	v_exp_f32_e32 v170, v170
	v_exp_f32_e32 v145, v145
	v_exp_f32_e32 v155, v155
	v_exp_f32_e32 v165, v165
	v_exp_f32_e32 v166, v166
	v_exp_f32_e32 v167, v167
	v_exp_f32_e32 v168, v168
	v_exp_f32_e32 v169, v169
	v_add_f32_e32 v170, 1.0, v170
	v_add_f32_e32 v145, 1.0, v145
	v_add_f32_e32 v155, 1.0, v155
	v_add_f32_e32 v165, 1.0, v165
	v_add_f32_e32 v166, 1.0, v166
	v_add_f32_e32 v167, 1.0, v167
	v_add_f32_e32 v168, 1.0, v168
	v_add_f32_e32 v169, 1.0, v169
	v_rcp_f32_e32 v170, v170
	v_rcp_f32_e32 v145, v145
	v_rcp_f32_e32 v155, v155
	v_rcp_f32_e32 v165, v165
	v_rcp_f32_e32 v166, v166
	v_rcp_f32_e32 v167, v167
	v_rcp_f32_e32 v168, v168
	v_rcp_f32_e32 v169, v169
	v_mul_f32_e32 v115, v115, v170
	v_mul_f32_e32 v145, v159, v145
	v_mul_f32_e32 v117, v117, v155
	v_mul_f32_e32 v125, v125, v165
	v_mul_f32_e32 v119, v119, v166
	v_mul_f32_e32 v127, v127, v167
	v_mul_f32_e32 v113, v113, v168
	v_mul_f32_e32 v155, v161, v169
	v_mul_f32_e32 v115, v114, v115
	v_mul_f32_e32 v145, v158, v145
	v_mul_f32_e32 v116, v116, v117
	v_mul_f32_e32 v117, v124, v125
	v_mul_f32_e32 v118, v118, v119
	v_mul_f32_e32 v119, v126, v127
	v_mul_f32_e32 v124, v112, v113
	v_mul_f32_e32 v125, v160, v155
	v_cvt_pk_bf16_f32 v112, v145, v116
	v_cvt_pk_bf16_f32 v113, v117, v118
	v_cvt_pk_bf16_f32 v114, v119, v124
	v_cvt_pk_bf16_f32 v115, v125, v115
	global_store_dwordx4 v[156:157], v[112:115], off
	s_nop 0
	v_mov_b32_e32 v113, v100
	v_mov_b32_e32 v100, v109
	v_mov_b32_e32 v109, v102
	v_mov_b32_e32 v102, v111
	v_mov_b32_e32 v111, v96
	v_mov_b32_e32 v96, v105
	v_mov_b32_e32 v105, v98
	v_mov_b32_e32 v98, v107
	v_mov_b32_e32 v112, v108
	v_mov_b32_e32 v108, v110
	v_mov_b32_e32 v110, v104
	v_mov_b32_e32 v104, v106
	v_or_b32_e32 v106, 32, v144
	v_mad_i64_i32 v[114:115], s[28:29], v164, s63, v[120:121]
	v_lshl_add_u64 v[114:115], v[114:115], 0, v[122:123]
	s_waitcnt vmcnt(7)
	v_mov_b32_e32 v116, v247
	v_fmamk_f32 v107, v116, 0x3a800000, v154
	v_mul_f32_e32 v116, 0x4b800000, v107
	v_cmp_gt_f32_e32 vcc, s62, v107
	s_nop 1
	v_cndmask_b32_e32 v107, v107, v116, vcc
	v_rsq_f32_e32 v118, v107
	v_ashrrev_i32_e32 v107, 31, v106
	v_lshl_add_u64 v[116:117], v[106:107], 2, s[24:25]
	v_mul_f32_e32 v107, 0x45800000, v118
	v_cndmask_b32_e32 v118, v118, v107, vcc
	v_pk_mul_f32 v[98:99], v[98:99], v[118:119] op_sel_hi:[1,0]
	v_pk_mul_f32 v[112:113], v[112:113], v[118:119] op_sel_hi:[1,0]
	v_pk_mul_f32 v[100:101], v[100:101], v[118:119] op_sel_hi:[1,0]
	v_pk_mul_f32 v[108:109], v[108:109], v[118:119] op_sel_hi:[1,0]
	v_pk_mul_f32 v[102:103], v[102:103], v[118:119] op_sel_hi:[1,0]
	v_pk_mul_f32 v[110:111], v[110:111], v[118:119] op_sel_hi:[1,0]
	v_pk_mul_f32 v[96:97], v[96:97], v[118:119] op_sel_hi:[1,0]
	v_pk_mul_f32 v[104:105], v[104:105], v[118:119] op_sel_hi:[1,0]
	v_mul_f32_e32 v145, 0xbfb8aa3b, v99
	v_mul_f32_e32 v107, 0xbfb8aa3b, v113
	v_mul_f32_e32 v118, 0xbfb8aa3b, v101
	v_mul_f32_e32 v119, 0xbfb8aa3b, v109
	v_mul_f32_e32 v124, 0xbfb8aa3b, v103
	v_mul_f32_e32 v125, 0xbfb8aa3b, v111
	v_mul_f32_e32 v126, 0xbfb8aa3b, v97
	v_mul_f32_e32 v127, 0xbfb8aa3b, v105
	v_exp_f32_e32 v145, v145
	v_exp_f32_e32 v107, v107
	v_exp_f32_e32 v118, v118
	v_exp_f32_e32 v119, v119
	v_exp_f32_e32 v124, v124
	v_exp_f32_e32 v125, v125
	v_exp_f32_e32 v126, v126
	v_exp_f32_e32 v127, v127
	v_add_f32_e32 v145, 1.0, v145
	v_add_f32_e32 v107, 1.0, v107
	v_add_f32_e32 v118, 1.0, v118
	v_add_f32_e32 v119, 1.0, v119
	v_add_f32_e32 v124, 1.0, v124
	v_add_f32_e32 v125, 1.0, v125
	v_add_f32_e32 v126, 1.0, v126
	v_add_f32_e32 v127, 1.0, v127
	v_rcp_f32_e32 v145, v145
	v_rcp_f32_e32 v107, v107
	v_rcp_f32_e32 v118, v118
	v_rcp_f32_e32 v119, v119
	v_rcp_f32_e32 v124, v124
	v_rcp_f32_e32 v125, v125
	v_rcp_f32_e32 v126, v126
	v_rcp_f32_e32 v127, v127
	v_mul_f32_e32 v99, v99, v145
	v_mul_f32_e32 v107, v113, v107
	v_mul_f32_e32 v101, v101, v118
	v_mul_f32_e32 v109, v109, v119
	v_mul_f32_e32 v103, v103, v124
	v_mul_f32_e32 v111, v111, v125
	v_mul_f32_e32 v97, v97, v126
	v_mul_f32_e32 v105, v105, v127
	v_mul_f32_e32 v99, v98, v99
	v_mul_f32_e32 v107, v112, v107
	v_mul_f32_e32 v100, v100, v101
	v_mul_f32_e32 v101, v108, v109
	v_mul_f32_e32 v102, v102, v103
	v_mul_f32_e32 v103, v110, v111
	v_mul_f32_e32 v108, v96, v97
	v_mul_f32_e32 v104, v104, v105
	v_cvt_pk_bf16_f32 v96, v107, v100
	v_cvt_pk_bf16_f32 v97, v101, v102
	v_cvt_pk_bf16_f32 v98, v103, v108
	v_cvt_pk_bf16_f32 v99, v104, v99
	global_store_dwordx4 v[114:115], v[96:99], off
	s_nop 0
	v_mov_b32_e32 v97, v84
	v_mov_b32_e32 v84, v93
	v_mov_b32_e32 v93, v86
	v_mov_b32_e32 v86, v95
	v_mov_b32_e32 v95, v80
	v_mov_b32_e32 v80, v89
	v_mov_b32_e32 v89, v82
	v_mov_b32_e32 v82, v91
	v_mov_b32_e32 v96, v92
	v_mov_b32_e32 v92, v94
	v_mov_b32_e32 v94, v88
	v_mov_b32_e32 v88, v90
	v_or_b32_e32 v90, 48, v144
	v_mad_i64_i32 v[98:99], s[28:29], v106, s63, v[120:121]
	v_lshl_add_u64 v[98:99], v[98:99], 0, v[122:123]
	s_waitcnt vmcnt(7)
	v_mov_b32_e32 v100, v248
	v_fmamk_f32 v91, v100, 0x3a800000, v154
	v_mul_f32_e32 v100, 0x4b800000, v91
	v_cmp_gt_f32_e32 vcc, s62, v91
	s_nop 1
	v_cndmask_b32_e32 v91, v91, v100, vcc
	v_rsq_f32_e32 v102, v91
	v_ashrrev_i32_e32 v91, 31, v90
	v_lshl_add_u64 v[100:101], v[90:91], 2, s[24:25]
	v_mul_f32_e32 v91, 0x45800000, v102
	v_cndmask_b32_e32 v102, v102, v91, vcc
	v_pk_mul_f32 v[82:83], v[82:83], v[102:103] op_sel_hi:[1,0]
	v_pk_mul_f32 v[96:97], v[96:97], v[102:103] op_sel_hi:[1,0]
	v_pk_mul_f32 v[84:85], v[84:85], v[102:103] op_sel_hi:[1,0]
	v_pk_mul_f32 v[92:93], v[92:93], v[102:103] op_sel_hi:[1,0]
	v_pk_mul_f32 v[86:87], v[86:87], v[102:103] op_sel_hi:[1,0]
	v_pk_mul_f32 v[94:95], v[94:95], v[102:103] op_sel_hi:[1,0]
	v_pk_mul_f32 v[80:81], v[80:81], v[102:103] op_sel_hi:[1,0]
	v_pk_mul_f32 v[88:89], v[88:89], v[102:103] op_sel_hi:[1,0]
	v_mul_f32_e32 v108, 0xbfb8aa3b, v83
	v_mul_f32_e32 v91, 0xbfb8aa3b, v97
	v_mul_f32_e32 v102, 0xbfb8aa3b, v85
	v_mul_f32_e32 v103, 0xbfb8aa3b, v93
	v_mul_f32_e32 v104, 0xbfb8aa3b, v87
	v_mul_f32_e32 v105, 0xbfb8aa3b, v95
	v_mul_f32_e32 v106, 0xbfb8aa3b, v81
	v_mul_f32_e32 v107, 0xbfb8aa3b, v89
	v_exp_f32_e32 v108, v108
	v_exp_f32_e32 v91, v91
	v_exp_f32_e32 v102, v102
	v_exp_f32_e32 v103, v103
	v_exp_f32_e32 v104, v104
	v_exp_f32_e32 v105, v105
	v_exp_f32_e32 v106, v106
	v_exp_f32_e32 v107, v107
	v_add_f32_e32 v108, 1.0, v108
	v_add_f32_e32 v91, 1.0, v91
	v_add_f32_e32 v102, 1.0, v102
	v_add_f32_e32 v103, 1.0, v103
	v_add_f32_e32 v104, 1.0, v104
	v_add_f32_e32 v105, 1.0, v105
	v_add_f32_e32 v106, 1.0, v106
	v_add_f32_e32 v107, 1.0, v107
	v_rcp_f32_e32 v108, v108
	v_rcp_f32_e32 v91, v91
	v_rcp_f32_e32 v102, v102
	v_rcp_f32_e32 v103, v103
	v_rcp_f32_e32 v104, v104
	v_rcp_f32_e32 v105, v105
	v_rcp_f32_e32 v106, v106
	v_rcp_f32_e32 v107, v107
	v_mul_f32_e32 v83, v83, v108
	v_mul_f32_e32 v91, v97, v91
	v_mul_f32_e32 v85, v85, v102
	v_mul_f32_e32 v93, v93, v103
	v_mul_f32_e32 v87, v87, v104
	v_mul_f32_e32 v95, v95, v105
	v_mul_f32_e32 v81, v81, v106
	v_mul_f32_e32 v89, v89, v107
	v_mul_f32_e32 v83, v82, v83
	v_mul_f32_e32 v91, v96, v91
	v_mul_f32_e32 v84, v84, v85
	v_mul_f32_e32 v85, v92, v93
	v_mul_f32_e32 v86, v86, v87
	v_mul_f32_e32 v87, v94, v95
	v_mul_f32_e32 v92, v80, v81
	v_mul_f32_e32 v88, v88, v89
	v_cvt_pk_bf16_f32 v80, v91, v84
	v_cvt_pk_bf16_f32 v81, v85, v86
	v_cvt_pk_bf16_f32 v82, v87, v92
	v_cvt_pk_bf16_f32 v83, v88, v83
	global_store_dwordx4 v[98:99], v[80:83], off
	s_nop 0
	v_mov_b32_e32 v80, v76
	v_mov_b32_e32 v76, v78
	v_mov_b32_e32 v78, v68
	v_mov_b32_e32 v68, v70
	v_mov_b32_e32 v81, v72
	v_mov_b32_e32 v72, v77
	v_mov_b32_e32 v77, v74
	v_mov_b32_e32 v74, v79
	v_mov_b32_e32 v79, v64
	v_mov_b32_e32 v64, v69
	v_mov_b32_e32 v69, v66
	v_mov_b32_e32 v66, v71
	s_waitcnt vmcnt(7)
	v_mov_b32_e32 v82, v249
	v_fmamk_f32 v70, v82, 0x3a800000, v154
	v_mul_f32_e32 v71, 0x4b800000, v70
	v_cmp_gt_f32_e32 vcc, s62, v70
	s_nop 1
	v_cndmask_b32_e32 v70, v70, v71, vcc
	v_rsq_f32_e32 v82, v70
	v_mad_i64_i32 v[70:71], s[28:29], v90, s63, v[120:121]
	v_lshl_add_u64 v[70:71], v[70:71], 0, v[122:123]
	v_mul_f32_e32 v83, 0x45800000, v82
	v_cndmask_b32_e32 v82, v82, v83, vcc
	v_pk_mul_f32 v[66:67], v[66:67], v[82:83] op_sel_hi:[1,0]
	v_pk_mul_f32 v[80:81], v[80:81], v[82:83] op_sel_hi:[1,0]
	v_pk_mul_f32 v[72:73], v[72:73], v[82:83] op_sel_hi:[1,0]
	v_pk_mul_f32 v[76:77], v[76:77], v[82:83] op_sel_hi:[1,0]
	v_pk_mul_f32 v[74:75], v[74:75], v[82:83] op_sel_hi:[1,0]
	v_pk_mul_f32 v[78:79], v[78:79], v[82:83] op_sel_hi:[1,0]
	v_pk_mul_f32 v[64:65], v[64:65], v[82:83] op_sel_hi:[1,0]
	v_pk_mul_f32 v[68:69], v[68:69], v[82:83] op_sel_hi:[1,0]
	v_mul_f32_e32 v89, 0xbfb8aa3b, v67
	v_mul_f32_e32 v82, 0xbfb8aa3b, v81
	v_mul_f32_e32 v83, 0xbfb8aa3b, v73
	v_mul_f32_e32 v84, 0xbfb8aa3b, v77
	v_mul_f32_e32 v85, 0xbfb8aa3b, v75
	v_mul_f32_e32 v86, 0xbfb8aa3b, v79
	v_mul_f32_e32 v87, 0xbfb8aa3b, v65
	v_mul_f32_e32 v88, 0xbfb8aa3b, v69
	v_exp_f32_e32 v89, v89
	v_exp_f32_e32 v82, v82
	v_exp_f32_e32 v83, v83
	v_exp_f32_e32 v84, v84
	v_exp_f32_e32 v85, v85
	v_exp_f32_e32 v86, v86
	v_exp_f32_e32 v87, v87
	v_exp_f32_e32 v88, v88
	v_add_f32_e32 v89, 1.0, v89
	v_add_f32_e32 v82, 1.0, v82
	v_add_f32_e32 v83, 1.0, v83
	v_add_f32_e32 v84, 1.0, v84
	v_add_f32_e32 v85, 1.0, v85
	v_add_f32_e32 v86, 1.0, v86
	v_add_f32_e32 v87, 1.0, v87
	v_add_f32_e32 v88, 1.0, v88
	v_rcp_f32_e32 v89, v89
	v_rcp_f32_e32 v82, v82
	v_rcp_f32_e32 v83, v83
	v_rcp_f32_e32 v84, v84
	v_rcp_f32_e32 v85, v85
	v_rcp_f32_e32 v86, v86
	v_rcp_f32_e32 v87, v87
	v_rcp_f32_e32 v88, v88
	v_mul_f32_e32 v67, v67, v89
	v_mul_f32_e32 v81, v81, v82
	v_mul_f32_e32 v73, v73, v83
	v_mul_f32_e32 v77, v77, v84
	v_mul_f32_e32 v75, v75, v85
	v_mul_f32_e32 v79, v79, v86
	v_mul_f32_e32 v65, v65, v87
	v_mul_f32_e32 v69, v69, v88
	v_mul_f32_e32 v67, v66, v67
	v_mul_f32_e32 v80, v80, v81
	v_mul_f32_e32 v72, v72, v73
	v_mul_f32_e32 v73, v76, v77
	v_mul_f32_e32 v74, v74, v75
	v_mul_f32_e32 v75, v78, v79
	v_mul_f32_e32 v76, v64, v65
	v_mul_f32_e32 v68, v68, v69
	v_cvt_pk_bf16_f32 v64, v80, v72
	v_cvt_pk_bf16_f32 v65, v73, v74
	v_cvt_pk_bf16_f32 v66, v75, v76
	v_cvt_pk_bf16_f32 v67, v68, v67
	global_store_dwordx4 v[70:71], v[64:67], off
	s_nop 0
	v_mov_b32_e32 v65, v56
	v_mov_b32_e32 v56, v61
	v_mov_b32_e32 v61, v58
	v_mov_b32_e32 v58, v63
	v_mov_b32_e32 v63, v48
	v_mov_b32_e32 v48, v53
	v_mov_b32_e32 v53, v50
	v_mov_b32_e32 v50, v55
	v_mov_b32_e32 v64, v60
	v_mov_b32_e32 v60, v62
	v_mov_b32_e32 v62, v52
	v_mov_b32_e32 v52, v54
	v_add_u32_e32 v54, 0x80, v144
	s_waitcnt vmcnt(7)
	v_mov_b32_e32 v66, v250
	v_fmamk_f32 v55, v66, 0x3a800000, v154
	v_mul_f32_e32 v66, 0x4b800000, v55
	v_cmp_gt_f32_e32 vcc, s62, v55
	s_nop 1
	v_cndmask_b32_e32 v55, v55, v66, vcc
	v_rsq_f32_e32 v66, v55
	v_mad_i64_i32 v[54:55], s[28:29], v54, s63, v[120:121]
	v_lshl_add_u64 v[54:55], v[54:55], 0, v[122:123]
	v_mul_f32_e32 v67, 0x45800000, v66
	v_cndmask_b32_e32 v66, v66, v67, vcc
	v_pk_mul_f32 v[50:51], v[50:51], v[66:67] op_sel_hi:[1,0]
	v_pk_mul_f32 v[64:65], v[64:65], v[66:67] op_sel_hi:[1,0]
	v_pk_mul_f32 v[56:57], v[56:57], v[66:67] op_sel_hi:[1,0]
	v_pk_mul_f32 v[60:61], v[60:61], v[66:67] op_sel_hi:[1,0]
	v_pk_mul_f32 v[58:59], v[58:59], v[66:67] op_sel_hi:[1,0]
	v_pk_mul_f32 v[62:63], v[62:63], v[66:67] op_sel_hi:[1,0]
	v_pk_mul_f32 v[48:49], v[48:49], v[66:67] op_sel_hi:[1,0]
	v_pk_mul_f32 v[52:53], v[52:53], v[66:67] op_sel_hi:[1,0]
	v_mul_f32_e32 v73, 0xbfb8aa3b, v51
	v_mul_f32_e32 v66, 0xbfb8aa3b, v65
	v_mul_f32_e32 v67, 0xbfb8aa3b, v57
	v_mul_f32_e32 v68, 0xbfb8aa3b, v61
	v_mul_f32_e32 v69, 0xbfb8aa3b, v59
	v_mul_f32_e32 v70, 0xbfb8aa3b, v63
	v_mul_f32_e32 v71, 0xbfb8aa3b, v49
	v_mul_f32_e32 v72, 0xbfb8aa3b, v53
	v_exp_f32_e32 v73, v73
	v_exp_f32_e32 v66, v66
	v_exp_f32_e32 v67, v67
	v_exp_f32_e32 v68, v68
	v_exp_f32_e32 v69, v69
	v_exp_f32_e32 v70, v70
	v_exp_f32_e32 v71, v71
	v_exp_f32_e32 v72, v72
	v_add_f32_e32 v73, 1.0, v73
	v_add_f32_e32 v66, 1.0, v66
	v_add_f32_e32 v67, 1.0, v67
	v_add_f32_e32 v68, 1.0, v68
	v_add_f32_e32 v69, 1.0, v69
	v_add_f32_e32 v70, 1.0, v70
	v_add_f32_e32 v71, 1.0, v71
	v_add_f32_e32 v72, 1.0, v72
	v_rcp_f32_e32 v73, v73
	v_rcp_f32_e32 v66, v66
	v_rcp_f32_e32 v67, v67
	v_rcp_f32_e32 v68, v68
	v_rcp_f32_e32 v69, v69
	v_rcp_f32_e32 v70, v70
	v_rcp_f32_e32 v71, v71
	v_rcp_f32_e32 v72, v72
	v_mul_f32_e32 v51, v51, v73
	v_mul_f32_e32 v65, v65, v66
	v_mul_f32_e32 v57, v57, v67
	v_mul_f32_e32 v61, v61, v68
	v_mul_f32_e32 v59, v59, v69
	v_mul_f32_e32 v63, v63, v70
	v_mul_f32_e32 v49, v49, v71
	v_mul_f32_e32 v53, v53, v72
	v_mul_f32_e32 v51, v50, v51
	v_mul_f32_e32 v64, v64, v65
	v_mul_f32_e32 v56, v56, v57
	v_mul_f32_e32 v57, v60, v61
	v_mul_f32_e32 v58, v58, v59
	v_mul_f32_e32 v59, v62, v63
	v_mul_f32_e32 v60, v48, v49
	v_mul_f32_e32 v52, v52, v53
	v_cvt_pk_bf16_f32 v48, v64, v56
	v_cvt_pk_bf16_f32 v49, v57, v58
	v_cvt_pk_bf16_f32 v50, v59, v60
	v_cvt_pk_bf16_f32 v51, v52, v51
	global_store_dwordx4 v[54:55], v[48:51], off
	s_nop 0
	v_mov_b32_e32 v49, v40
	v_mov_b32_e32 v40, v45
	v_mov_b32_e32 v45, v42
	v_mov_b32_e32 v42, v47
	v_mov_b32_e32 v47, v32
	v_mov_b32_e32 v32, v37
	v_mov_b32_e32 v37, v34
	v_mov_b32_e32 v34, v39
	v_mov_b32_e32 v48, v44
	v_mov_b32_e32 v44, v46
	v_mov_b32_e32 v46, v36
	v_mov_b32_e32 v36, v38
	v_add_u32_e32 v38, 0x90, v144
	s_waitcnt vmcnt(7)
	v_mov_b32_e32 v50, v251
	v_fmamk_f32 v39, v50, 0x3a800000, v154
	v_mul_f32_e32 v50, 0x4b800000, v39
	v_cmp_gt_f32_e32 vcc, s62, v39
	s_nop 1
	v_cndmask_b32_e32 v39, v39, v50, vcc
	v_rsq_f32_e32 v50, v39
	v_mad_i64_i32 v[38:39], s[28:29], v38, s63, v[120:121]
	v_lshl_add_u64 v[38:39], v[38:39], 0, v[122:123]
	v_mul_f32_e32 v51, 0x45800000, v50
	v_cndmask_b32_e32 v50, v50, v51, vcc
	v_pk_mul_f32 v[34:35], v[34:35], v[50:51] op_sel_hi:[1,0]
	v_pk_mul_f32 v[48:49], v[48:49], v[50:51] op_sel_hi:[1,0]
	v_pk_mul_f32 v[40:41], v[40:41], v[50:51] op_sel_hi:[1,0]
	v_pk_mul_f32 v[44:45], v[44:45], v[50:51] op_sel_hi:[1,0]
	v_pk_mul_f32 v[42:43], v[42:43], v[50:51] op_sel_hi:[1,0]
	v_pk_mul_f32 v[46:47], v[46:47], v[50:51] op_sel_hi:[1,0]
	v_pk_mul_f32 v[32:33], v[32:33], v[50:51] op_sel_hi:[1,0]
	v_pk_mul_f32 v[36:37], v[36:37], v[50:51] op_sel_hi:[1,0]
	v_mul_f32_e32 v57, 0xbfb8aa3b, v35
	v_mul_f32_e32 v50, 0xbfb8aa3b, v49
	v_mul_f32_e32 v51, 0xbfb8aa3b, v41
	v_mul_f32_e32 v52, 0xbfb8aa3b, v45
	v_mul_f32_e32 v53, 0xbfb8aa3b, v43
	v_mul_f32_e32 v54, 0xbfb8aa3b, v47
	v_mul_f32_e32 v55, 0xbfb8aa3b, v33
	v_mul_f32_e32 v56, 0xbfb8aa3b, v37
	v_exp_f32_e32 v57, v57
	v_exp_f32_e32 v50, v50
	v_exp_f32_e32 v51, v51
	v_exp_f32_e32 v52, v52
	v_exp_f32_e32 v53, v53
	v_exp_f32_e32 v54, v54
	v_exp_f32_e32 v55, v55
	v_exp_f32_e32 v56, v56
	v_add_f32_e32 v57, 1.0, v57
	v_add_f32_e32 v50, 1.0, v50
	v_add_f32_e32 v51, 1.0, v51
	v_add_f32_e32 v52, 1.0, v52
	v_add_f32_e32 v53, 1.0, v53
	v_add_f32_e32 v54, 1.0, v54
	v_add_f32_e32 v55, 1.0, v55
	v_add_f32_e32 v56, 1.0, v56
	v_rcp_f32_e32 v57, v57
	v_rcp_f32_e32 v50, v50
	v_rcp_f32_e32 v51, v51
	v_rcp_f32_e32 v52, v52
	v_rcp_f32_e32 v53, v53
	v_rcp_f32_e32 v54, v54
	v_rcp_f32_e32 v55, v55
	v_rcp_f32_e32 v56, v56
	v_mul_f32_e32 v35, v35, v57
	v_mul_f32_e32 v49, v49, v50
	v_mul_f32_e32 v41, v41, v51
	v_mul_f32_e32 v45, v45, v52
	v_mul_f32_e32 v43, v43, v53
	v_mul_f32_e32 v47, v47, v54
	v_mul_f32_e32 v33, v33, v55
	v_mul_f32_e32 v37, v37, v56
	v_mul_f32_e32 v35, v34, v35
	v_mul_f32_e32 v48, v48, v49
	v_mul_f32_e32 v40, v40, v41
	v_mul_f32_e32 v41, v44, v45
	v_mul_f32_e32 v42, v42, v43
	v_mul_f32_e32 v43, v46, v47
	v_mul_f32_e32 v44, v32, v33
	v_mul_f32_e32 v36, v36, v37
	v_cvt_pk_bf16_f32 v32, v48, v40
	v_cvt_pk_bf16_f32 v33, v41, v42
	v_cvt_pk_bf16_f32 v34, v43, v44
	v_cvt_pk_bf16_f32 v35, v36, v35
	global_store_dwordx4 v[38:39], v[32:35], off
	s_nop 0
	v_mov_b32_e32 v33, v24
	v_mov_b32_e32 v24, v29
	v_mov_b32_e32 v29, v26
	v_mov_b32_e32 v26, v31
	v_mov_b32_e32 v31, v16
	v_mov_b32_e32 v16, v21
	v_mov_b32_e32 v21, v18
	v_mov_b32_e32 v18, v23
	v_mov_b32_e32 v32, v28
	v_mov_b32_e32 v28, v30
	v_mov_b32_e32 v30, v20
	v_mov_b32_e32 v20, v22
	v_add_u32_e32 v22, 0xa0, v144
	s_waitcnt vmcnt(7)
	v_mov_b32_e32 v34, v252
	v_fmamk_f32 v23, v34, 0x3a800000, v154
	v_mul_f32_e32 v34, 0x4b800000, v23
	v_cmp_gt_f32_e32 vcc, s62, v23
	s_nop 1
	v_cndmask_b32_e32 v23, v23, v34, vcc
	v_rsq_f32_e32 v34, v23
	v_mad_i64_i32 v[22:23], s[28:29], v22, s63, v[120:121]
	v_lshl_add_u64 v[22:23], v[22:23], 0, v[122:123]
	v_mul_f32_e32 v35, 0x45800000, v34
	v_cndmask_b32_e32 v34, v34, v35, vcc
	v_pk_mul_f32 v[18:19], v[18:19], v[34:35] op_sel_hi:[1,0]
	v_pk_mul_f32 v[32:33], v[32:33], v[34:35] op_sel_hi:[1,0]
	v_pk_mul_f32 v[24:25], v[24:25], v[34:35] op_sel_hi:[1,0]
	v_pk_mul_f32 v[28:29], v[28:29], v[34:35] op_sel_hi:[1,0]
	v_pk_mul_f32 v[26:27], v[26:27], v[34:35] op_sel_hi:[1,0]
	v_pk_mul_f32 v[30:31], v[30:31], v[34:35] op_sel_hi:[1,0]
	v_pk_mul_f32 v[16:17], v[16:17], v[34:35] op_sel_hi:[1,0]
	v_pk_mul_f32 v[20:21], v[20:21], v[34:35] op_sel_hi:[1,0]
	v_mul_f32_e32 v41, 0xbfb8aa3b, v19
	v_mul_f32_e32 v34, 0xbfb8aa3b, v33
	v_mul_f32_e32 v35, 0xbfb8aa3b, v25
	v_mul_f32_e32 v36, 0xbfb8aa3b, v29
	v_mul_f32_e32 v37, 0xbfb8aa3b, v27
	v_mul_f32_e32 v38, 0xbfb8aa3b, v31
	v_mul_f32_e32 v39, 0xbfb8aa3b, v17
	v_mul_f32_e32 v40, 0xbfb8aa3b, v21
	v_exp_f32_e32 v41, v41
	v_exp_f32_e32 v34, v34
	v_exp_f32_e32 v35, v35
	v_exp_f32_e32 v36, v36
	v_exp_f32_e32 v37, v37
	v_exp_f32_e32 v38, v38
	v_exp_f32_e32 v39, v39
	v_exp_f32_e32 v40, v40
	v_add_f32_e32 v41, 1.0, v41
	v_add_f32_e32 v34, 1.0, v34
	v_add_f32_e32 v35, 1.0, v35
	v_add_f32_e32 v36, 1.0, v36
	v_add_f32_e32 v37, 1.0, v37
	v_add_f32_e32 v38, 1.0, v38
	v_add_f32_e32 v39, 1.0, v39
	v_add_f32_e32 v40, 1.0, v40
	v_rcp_f32_e32 v41, v41
	v_rcp_f32_e32 v34, v34
	v_rcp_f32_e32 v35, v35
	v_rcp_f32_e32 v36, v36
	v_rcp_f32_e32 v37, v37
	v_rcp_f32_e32 v38, v38
	v_rcp_f32_e32 v39, v39
	v_rcp_f32_e32 v40, v40
	v_mul_f32_e32 v19, v19, v41
	v_mul_f32_e32 v33, v33, v34
	v_mul_f32_e32 v25, v25, v35
	v_mul_f32_e32 v29, v29, v36
	v_mul_f32_e32 v27, v27, v37
	v_mul_f32_e32 v31, v31, v38
	v_mul_f32_e32 v17, v17, v39
	v_mul_f32_e32 v21, v21, v40
	v_mul_f32_e32 v19, v18, v19
	v_mul_f32_e32 v32, v32, v33
	v_mul_f32_e32 v24, v24, v25
	v_mul_f32_e32 v25, v28, v29
	v_mul_f32_e32 v26, v26, v27
	v_mul_f32_e32 v27, v30, v31
	v_mul_f32_e32 v28, v16, v17
	v_mul_f32_e32 v20, v20, v21
	v_cvt_pk_bf16_f32 v16, v32, v24
	v_cvt_pk_bf16_f32 v17, v25, v26
	v_cvt_pk_bf16_f32 v18, v27, v28
	v_cvt_pk_bf16_f32 v19, v20, v19
	global_store_dwordx4 v[22:23], v[16:19], off
	s_and_b64 vcc, exec, s[8:9]
	v_mov_b32_e32 v17, v8
	v_mov_b32_e32 v8, v13
	v_mov_b32_e32 v13, v10
	v_mov_b32_e32 v10, v15
	v_mov_b32_e32 v15, v0
	v_mov_b32_e32 v0, v5
	v_mov_b32_e32 v5, v2
	v_mov_b32_e32 v2, v7
	v_mov_b32_e32 v16, v12
	v_mov_b32_e32 v12, v14
	v_mov_b32_e32 v14, v4
	v_mov_b32_e32 v4, v6
	v_add_u32_e32 v6, 0xb0, v144
	s_mov_b64 s[28:29], s[18:19]
	s_waitcnt vmcnt(7)
	v_mov_b32_e32 v18, v253
	v_fmamk_f32 v7, v18, 0x3a800000, v154
	v_mul_f32_e32 v18, 0x4b800000, v7
	v_cmp_gt_f32_e64 s[8:9], s62, v7
	s_nop 1
	v_cndmask_b32_e64 v7, v7, v18, s[8:9]
	v_rsq_f32_e32 v18, v7
	v_mad_i64_i32 v[6:7], s[18:19], v6, s63, v[120:121]
	v_lshl_add_u64 v[6:7], v[6:7], 0, v[122:123]
	v_mul_f32_e32 v19, 0x45800000, v18
	v_cndmask_b32_e64 v18, v18, v19, s[8:9]
	v_pk_mul_f32 v[2:3], v[2:3], v[18:19] op_sel_hi:[1,0]
	v_pk_mul_f32 v[16:17], v[16:17], v[18:19] op_sel_hi:[1,0]
	v_pk_mul_f32 v[8:9], v[8:9], v[18:19] op_sel_hi:[1,0]
	v_pk_mul_f32 v[12:13], v[12:13], v[18:19] op_sel_hi:[1,0]
	v_pk_mul_f32 v[10:11], v[10:11], v[18:19] op_sel_hi:[1,0]
	v_pk_mul_f32 v[14:15], v[14:15], v[18:19] op_sel_hi:[1,0]
	v_pk_mul_f32 v[0:1], v[0:1], v[18:19] op_sel_hi:[1,0]
	v_pk_mul_f32 v[4:5], v[4:5], v[18:19] op_sel_hi:[1,0]
	v_mul_f32_e32 v25, 0xbfb8aa3b, v3
	v_mul_f32_e32 v18, 0xbfb8aa3b, v17
	v_mul_f32_e32 v19, 0xbfb8aa3b, v9
	v_mul_f32_e32 v20, 0xbfb8aa3b, v13
	v_mul_f32_e32 v21, 0xbfb8aa3b, v11
	v_mul_f32_e32 v22, 0xbfb8aa3b, v15
	v_mul_f32_e32 v23, 0xbfb8aa3b, v1
	v_mul_f32_e32 v24, 0xbfb8aa3b, v5
	v_exp_f32_e32 v25, v25
	v_exp_f32_e32 v18, v18
	v_exp_f32_e32 v19, v19
	v_exp_f32_e32 v20, v20
	v_exp_f32_e32 v21, v21
	v_exp_f32_e32 v22, v22
	v_exp_f32_e32 v23, v23
	v_exp_f32_e32 v24, v24
	v_add_f32_e32 v25, 1.0, v25
	v_add_f32_e32 v18, 1.0, v18
	v_add_f32_e32 v19, 1.0, v19
	v_add_f32_e32 v20, 1.0, v20
	v_add_f32_e32 v21, 1.0, v21
	v_add_f32_e32 v22, 1.0, v22
	v_add_f32_e32 v23, 1.0, v23
	v_add_f32_e32 v24, 1.0, v24
	v_rcp_f32_e32 v25, v25
	v_rcp_f32_e32 v18, v18
	v_rcp_f32_e32 v19, v19
	v_rcp_f32_e32 v20, v20
	v_rcp_f32_e32 v21, v21
	v_rcp_f32_e32 v22, v22
	v_rcp_f32_e32 v23, v23
	v_rcp_f32_e32 v24, v24
	v_mul_f32_e32 v3, v3, v25
	v_mul_f32_e32 v17, v17, v18
	v_mul_f32_e32 v9, v9, v19
	v_mul_f32_e32 v13, v13, v20
	v_mul_f32_e32 v11, v11, v21
	v_mul_f32_e32 v15, v15, v22
	v_mul_f32_e32 v1, v1, v23
	v_mul_f32_e32 v5, v5, v24
	v_mul_f32_e32 v3, v2, v3
	v_mul_f32_e32 v16, v16, v17
	v_mul_f32_e32 v8, v8, v9
	v_mul_f32_e32 v9, v12, v13
	v_mul_f32_e32 v10, v10, v11
	v_mul_f32_e32 v11, v14, v15
	v_mul_f32_e32 v12, v0, v1
	v_mul_f32_e32 v4, v4, v5
	v_cvt_pk_bf16_f32 v0, v16, v8
	v_cvt_pk_bf16_f32 v1, v9, v10
	v_cvt_pk_bf16_f32 v2, v11, v12
	v_cvt_pk_bf16_f32 v3, v4, v3
	global_store_dwordx4 v[6:7], v[0:3], off
	s_cbranch_vccz .LBB0_948
	s_waitcnt vmcnt(0)
	s_cmpk_gt_u32 s4, 0xff
	s_cbranch_scc1 .LBB0_959
	s_barrier

.LBB0_1456:
	ds_read_b128 v[144:147], v151
	ds_read_b128 v[156:159], v151 offset:1024
	ds_read_b128 v[160:163], v151 offset:2048
	ds_read_b128 v[164:167], v151 offset:3072
	s_add_u32 s26, s24, 0xfffc0080
	s_addc_u32 s27, s25, -1
	s_cmp_eq_u32 s55, 12
	s_cselect_b32 s29, s17, s27
	s_cselect_b32 s28, s51, s26
	s_cselect_b32 s27, s15, s54
	s_cselect_b32 s26, s52, s53
	v_lshl_add_u64 v[172:173], s[24:25], 0, v[136:137]
	s_add_i32 m0, s23, 0xc000
	ds_read_b128 v[168:171], v152
	ds_read_b128 v[178:181], v152 offset:1024
	ds_read_b128 v[182:185], v152 offset:2048
	ds_read_b128 v[186:189], v152 offset:3072
	ds_read_b128 v[190:193], v152 offset:4096
	ds_read_b128 v[194:197], v152 offset:5120
	ds_read_b128 v[198:201], v152 offset:6144
	ds_read_b128 v[202:205], v152 offset:7168
	global_load_lds_dwordx4 v[172:173], off
	v_lshl_add_u64 v[172:173], s[24:25], 0, v[138:139]
	s_add_i32 m0, s23, 0xe000
	s_nop 0
	global_load_lds_dwordx4 v[172:173], off
	s_waitcnt lgkmcnt(8)
	s_barrier
	s_waitcnt lgkmcnt(0)
	s_setprio 1
	s_waitcnt lgkmcnt(0)
	v_mfma_f32_16x16x32_bf16 v[116:119], v[144:147], v[168:171], v[116:119]
	v_mfma_f32_16x16x32_bf16 v[112:115], v[160:163], v[168:171], v[112:115]
	v_mfma_f32_16x16x32_bf16 v[100:103], v[144:147], v[182:185], v[100:103]
	v_mfma_f32_16x16x32_bf16 v[96:99], v[160:163], v[182:185], v[96:99]
	v_mfma_f32_16x16x32_bf16 v[84:87], v[144:147], v[190:193], v[84:87]
	v_mfma_f32_16x16x32_bf16 v[80:83], v[160:163], v[190:193], v[80:83]
	v_mfma_f32_16x16x32_bf16 v[72:75], v[144:147], v[198:201], v[72:75]
	v_mfma_f32_16x16x32_bf16 v[64:67], v[160:163], v[198:201], v[64:67]
	v_mfma_f32_16x16x32_bf16 v[116:119], v[156:159], v[178:181], v[116:119]
	v_mfma_f32_16x16x32_bf16 v[112:115], v[164:167], v[178:181], v[112:115]
	v_mfma_f32_16x16x32_bf16 v[100:103], v[156:159], v[186:189], v[100:103]
	v_mfma_f32_16x16x32_bf16 v[96:99], v[164:167], v[186:189], v[96:99]
	v_mfma_f32_16x16x32_bf16 v[84:87], v[156:159], v[194:197], v[84:87]
	v_mfma_f32_16x16x32_bf16 v[80:83], v[164:167], v[194:197], v[80:83]
	v_mfma_f32_16x16x32_bf16 v[72:75], v[156:159], v[202:205], v[72:75]
	v_mfma_f32_16x16x32_bf16 v[64:67], v[164:167], v[202:205], v[64:67]
	s_setprio 0
	s_barrier
	s_add_i32 s56, s46, s31
	v_lshl_add_u64 v[172:173], s[26:27], 0, v[130:131]
	s_mov_b32 m0, s56
	ds_read_b128 v[206:209], v153
	ds_read_b128 v[210:213], v153 offset:1024
	ds_read_b128 v[214:217], v153 offset:2048
	ds_read_b128 v[218:221], v153 offset:3072
	global_load_lds_dwordx4 v[172:173], off
	v_lshl_add_u64 v[222:223], s[26:27], 0, v[134:135]
	s_add_i32 m0, s56, 0x2000
	s_nop 0
	global_load_lds_dwordx4 v[222:223], off
	s_barrier
	s_waitcnt lgkmcnt(0)
	s_setprio 1
	s_waitcnt lgkmcnt(0)
	v_mfma_f32_16x16x32_bf16 v[124:127], v[206:209], v[168:171], v[124:127]
	v_mfma_f32_16x16x32_bf16 v[120:123], v[214:217], v[168:171], v[120:123]
	v_mfma_f32_16x16x32_bf16 v[108:111], v[206:209], v[182:185], v[108:111]
	v_mfma_f32_16x16x32_bf16 v[104:107], v[214:217], v[182:185], v[104:107]
	v_mfma_f32_16x16x32_bf16 v[92:95], v[206:209], v[190:193], v[92:95]
	v_mfma_f32_16x16x32_bf16 v[88:91], v[214:217], v[190:193], v[88:91]
	v_mfma_f32_16x16x32_bf16 v[76:79], v[206:209], v[198:201], v[76:79]
	v_mfma_f32_16x16x32_bf16 v[68:71], v[214:217], v[198:201], v[68:71]
	v_mfma_f32_16x16x32_bf16 v[124:127], v[210:213], v[178:181], v[124:127]
	v_mfma_f32_16x16x32_bf16 v[120:123], v[218:221], v[178:181], v[120:123]
	v_mfma_f32_16x16x32_bf16 v[108:111], v[210:213], v[186:189], v[108:111]
	v_mfma_f32_16x16x32_bf16 v[104:107], v[218:221], v[186:189], v[104:107]
	v_mfma_f32_16x16x32_bf16 v[92:95], v[210:213], v[194:197], v[92:95]
	v_mfma_f32_16x16x32_bf16 v[88:91], v[218:221], v[194:197], v[88:91]
	v_mfma_f32_16x16x32_bf16 v[76:79], v[210:213], v[202:205], v[76:79]
	v_mfma_f32_16x16x32_bf16 v[68:71], v[218:221], v[202:205], v[68:71]
	s_setprio 0
	s_mov_b32 m0, s23
	v_lshl_add_u64 v[224:225], s[28:29], 0, v[128:129]
	s_barrier
	ds_read_b128 v[168:171], v152 offset:16384
	ds_read_b128 v[178:181], v152 offset:17408
	ds_read_b128 v[182:185], v152 offset:18432
	ds_read_b128 v[186:189], v152 offset:19456
	ds_read_b128 v[190:193], v152 offset:20480
	ds_read_b128 v[194:197], v152 offset:21504
	ds_read_b128 v[198:201], v152 offset:22528
	ds_read_b128 v[202:205], v152 offset:23552
	global_load_lds_dwordx4 v[224:225], off
	v_lshl_add_u64 v[226:227], s[28:29], 0, v[132:133]
	s_mov_b32 m0, s34
	s_nop 0
	global_load_lds_dwordx4 v[226:227], off
	s_barrier
	s_waitcnt lgkmcnt(0)
	s_setprio 1
	s_waitcnt lgkmcnt(0)
	v_mfma_f32_16x16x32_bf16 v[56:59], v[144:147], v[168:171], v[56:59]
	v_mfma_f32_16x16x32_bf16 v[48:51], v[160:163], v[168:171], v[48:51]
	v_mfma_f32_16x16x32_bf16 v[40:43], v[144:147], v[182:185], v[40:43]
	v_mfma_f32_16x16x32_bf16 v[32:35], v[160:163], v[182:185], v[32:35]
	v_mfma_f32_16x16x32_bf16 v[24:27], v[144:147], v[190:193], v[24:27]
	v_mfma_f32_16x16x32_bf16 v[16:19], v[160:163], v[190:193], v[16:19]
	v_mfma_f32_16x16x32_bf16 v[8:11], v[144:147], v[198:201], v[8:11]
	v_mfma_f32_16x16x32_bf16 v[0:3], v[160:163], v[198:201], v[0:3]
	v_mfma_f32_16x16x32_bf16 v[56:59], v[156:159], v[178:181], v[56:59]
	v_mfma_f32_16x16x32_bf16 v[48:51], v[164:167], v[178:181], v[48:51]
	v_mfma_f32_16x16x32_bf16 v[40:43], v[156:159], v[186:189], v[40:43]
	v_mfma_f32_16x16x32_bf16 v[32:35], v[164:167], v[186:189], v[32:35]
	v_mfma_f32_16x16x32_bf16 v[24:27], v[156:159], v[194:197], v[24:27]
	v_mfma_f32_16x16x32_bf16 v[16:19], v[164:167], v[194:197], v[16:19]
	v_mfma_f32_16x16x32_bf16 v[8:11], v[156:159], v[202:205], v[8:11]
	v_mfma_f32_16x16x32_bf16 v[0:3], v[164:167], v[202:205], v[0:3]
	s_setprio 0
	s_barrier
	s_add_u32 s56, s26, 0x40000
	s_addc_u32 s57, s27, 0
	s_add_i32 s58, s47, s31
	v_lshl_add_u64 v[144:145], s[56:57], 0, v[130:131]
	s_mov_b32 m0, s58
	s_nop 0
	global_load_lds_dwordx4 v[144:145], off
	v_lshl_add_u64 v[144:145], s[56:57], 0, v[134:135]
	s_add_i32 m0, s58, 0x2000
	s_nop 0
	global_load_lds_dwordx4 v[144:145], off
	s_waitcnt vmcnt(6)
	s_barrier
	s_setprio 1
	v_mfma_f32_16x16x32_bf16 v[60:63], v[206:209], v[168:171], v[60:63]
	v_mfma_f32_16x16x32_bf16 v[52:55], v[214:217], v[168:171], v[52:55]
	v_mfma_f32_16x16x32_bf16 v[44:47], v[206:209], v[182:185], v[44:47]
	v_mfma_f32_16x16x32_bf16 v[36:39], v[214:217], v[182:185], v[36:39]
	v_mfma_f32_16x16x32_bf16 v[28:31], v[206:209], v[190:193], v[28:31]
	v_mfma_f32_16x16x32_bf16 v[20:23], v[214:217], v[190:193], v[20:23]
	v_mfma_f32_16x16x32_bf16 v[12:15], v[206:209], v[198:201], v[12:15]
	v_mfma_f32_16x16x32_bf16 v[4:7], v[214:217], v[198:201], v[4:7]
	v_mfma_f32_16x16x32_bf16 v[60:63], v[210:213], v[178:181], v[60:63]
	v_mfma_f32_16x16x32_bf16 v[52:55], v[218:221], v[178:181], v[52:55]
	v_mfma_f32_16x16x32_bf16 v[44:47], v[210:213], v[186:189], v[44:47]
	v_mfma_f32_16x16x32_bf16 v[36:39], v[218:221], v[186:189], v[36:39]
	v_mfma_f32_16x16x32_bf16 v[28:31], v[210:213], v[194:197], v[28:31]
	v_mfma_f32_16x16x32_bf16 v[20:23], v[218:221], v[194:197], v[20:23]
	v_mfma_f32_16x16x32_bf16 v[12:15], v[210:213], v[202:205], v[12:15]
	v_mfma_f32_16x16x32_bf16 v[4:7], v[218:221], v[202:205], v[4:7]
	s_setprio 0
	s_add_i32 s56, 0, 0x18000
	v_add_u32_e32 v155, s56, v149
	s_barrier
	ds_read_b128 v[144:147], v155
	ds_read_b128 v[156:159], v155 offset:1024
	ds_read_b128 v[160:163], v155 offset:2048
	ds_read_b128 v[164:167], v155 offset:3072
	s_add_u32 s28, s28, 0x40000
	s_addc_u32 s29, s29, 0
	s_mov_b32 m0, s35
	v_lshl_add_u64 v[206:207], s[28:29], 0, v[128:129]
	ds_read_b128 v[168:171], v152 offset:32768
	ds_read_b128 v[178:181], v152 offset:33792
	ds_read_b128 v[182:185], v152 offset:34816
	ds_read_b128 v[186:189], v152 offset:35840
	ds_read_b128 v[190:193], v152 offset:36864
	ds_read_b128 v[194:197], v152 offset:37888
	ds_read_b128 v[198:201], v152 offset:38912
	ds_read_b128 v[202:205], v152 offset:39936
	global_load_lds_dwordx4 v[206:207], off
	v_lshl_add_u64 v[206:207], s[28:29], 0, v[132:133]
	s_mov_b32 m0, s36
	s_nop 0
	global_load_lds_dwordx4 v[206:207], off
	s_waitcnt lgkmcnt(8)
	s_barrier
	s_waitcnt lgkmcnt(0)
	s_setprio 1
	s_waitcnt lgkmcnt(0)
	v_mfma_f32_16x16x32_bf16 v[116:119], v[144:147], v[168:171], v[116:119]
	v_mfma_f32_16x16x32_bf16 v[112:115], v[160:163], v[168:171], v[112:115]
	v_mfma_f32_16x16x32_bf16 v[100:103], v[144:147], v[182:185], v[100:103]
	v_mfma_f32_16x16x32_bf16 v[96:99], v[160:163], v[182:185], v[96:99]
	v_mfma_f32_16x16x32_bf16 v[84:87], v[144:147], v[190:193], v[84:87]
	v_mfma_f32_16x16x32_bf16 v[80:83], v[160:163], v[190:193], v[80:83]
	v_mfma_f32_16x16x32_bf16 v[72:75], v[144:147], v[198:201], v[72:75]
	v_mfma_f32_16x16x32_bf16 v[64:67], v[160:163], v[198:201], v[64:67]
	v_mfma_f32_16x16x32_bf16 v[116:119], v[156:159], v[178:181], v[116:119]
	v_mfma_f32_16x16x32_bf16 v[112:115], v[164:167], v[178:181], v[112:115]
	v_mfma_f32_16x16x32_bf16 v[100:103], v[156:159], v[186:189], v[100:103]
	v_mfma_f32_16x16x32_bf16 v[96:99], v[164:167], v[186:189], v[96:99]
	v_mfma_f32_16x16x32_bf16 v[84:87], v[156:159], v[194:197], v[84:87]
	v_mfma_f32_16x16x32_bf16 v[80:83], v[164:167], v[194:197], v[80:83]
	v_mfma_f32_16x16x32_bf16 v[72:75], v[156:159], v[202:205], v[72:75]
	v_mfma_f32_16x16x32_bf16 v[64:67], v[164:167], v[202:205], v[64:67]
	s_setprio 0
	s_barrier
	s_add_i32 s28, 0, 0x1c000
	s_add_i32 s29, s56, s31
	v_add_u32_e32 v155, s28, v149
	v_lshl_add_u64 v[172:173], v[172:173], 0, s[8:9]
	s_mov_b32 m0, s29
	ds_read_b128 v[206:209], v155
	ds_read_b128 v[210:213], v155 offset:1024
	ds_read_b128 v[214:217], v155 offset:2048
	ds_read_b128 v[218:221], v155 offset:3072
	global_load_lds_dwordx4 v[172:173], off
	v_lshl_add_u64 v[172:173], v[222:223], 0, s[8:9]
	s_add_i32 m0, s29, 0x2000
	s_nop 0
	global_load_lds_dwordx4 v[172:173], off
	s_barrier
	s_waitcnt lgkmcnt(0)
	s_setprio 1
	s_waitcnt lgkmcnt(0)
	v_mfma_f32_16x16x32_bf16 v[124:127], v[206:209], v[168:171], v[124:127]
	v_mfma_f32_16x16x32_bf16 v[120:123], v[214:217], v[168:171], v[120:123]
	v_mfma_f32_16x16x32_bf16 v[108:111], v[206:209], v[182:185], v[108:111]
	v_mfma_f32_16x16x32_bf16 v[104:107], v[214:217], v[182:185], v[104:107]
	v_mfma_f32_16x16x32_bf16 v[92:95], v[206:209], v[190:193], v[92:95]
	v_mfma_f32_16x16x32_bf16 v[88:91], v[214:217], v[190:193], v[88:91]
	v_mfma_f32_16x16x32_bf16 v[76:79], v[206:209], v[198:201], v[76:79]
	v_mfma_f32_16x16x32_bf16 v[68:71], v[214:217], v[198:201], v[68:71]
	v_mfma_f32_16x16x32_bf16 v[124:127], v[210:213], v[178:181], v[124:127]
	v_mfma_f32_16x16x32_bf16 v[120:123], v[218:221], v[178:181], v[120:123]
	v_mfma_f32_16x16x32_bf16 v[108:111], v[210:213], v[186:189], v[108:111]
	v_mfma_f32_16x16x32_bf16 v[104:107], v[218:221], v[186:189], v[104:107]
	v_mfma_f32_16x16x32_bf16 v[92:95], v[210:213], v[194:197], v[92:95]
	v_mfma_f32_16x16x32_bf16 v[88:91], v[218:221], v[194:197], v[88:91]
	v_mfma_f32_16x16x32_bf16 v[76:79], v[210:213], v[202:205], v[76:79]
	v_mfma_f32_16x16x32_bf16 v[68:71], v[218:221], v[202:205], v[68:71]
	s_setprio 0
	s_mov_b32 m0, s42
	v_lshl_add_u64 v[172:173], v[224:225], 0, s[8:9]
	s_barrier
	ds_read_b128 v[168:171], v152 offset:49152
	ds_read_b128 v[178:181], v152 offset:50176
	ds_read_b128 v[182:185], v152 offset:51200
	ds_read_b128 v[186:189], v152 offset:52224
	ds_read_b128 v[190:193], v152 offset:53248
	ds_read_b128 v[194:197], v152 offset:54272
	ds_read_b128 v[198:201], v152 offset:55296
	ds_read_b128 v[202:205], v152 offset:56320
	global_load_lds_dwordx4 v[172:173], off
	v_lshl_add_u64 v[172:173], v[226:227], 0, s[8:9]
	s_mov_b32 m0, s43
	s_nop 0
	global_load_lds_dwordx4 v[172:173], off
	s_barrier
	s_waitcnt lgkmcnt(0)
	s_setprio 1
	s_waitcnt lgkmcnt(0)
	v_mfma_f32_16x16x32_bf16 v[56:59], v[144:147], v[168:171], v[56:59]
	v_mfma_f32_16x16x32_bf16 v[48:51], v[160:163], v[168:171], v[48:51]
	v_mfma_f32_16x16x32_bf16 v[40:43], v[144:147], v[182:185], v[40:43]
	v_mfma_f32_16x16x32_bf16 v[32:35], v[160:163], v[182:185], v[32:35]
	v_mfma_f32_16x16x32_bf16 v[24:27], v[144:147], v[190:193], v[24:27]
	v_mfma_f32_16x16x32_bf16 v[16:19], v[160:163], v[190:193], v[16:19]
	v_mfma_f32_16x16x32_bf16 v[8:11], v[144:147], v[198:201], v[8:11]
	v_mfma_f32_16x16x32_bf16 v[0:3], v[160:163], v[198:201], v[0:3]
	v_mfma_f32_16x16x32_bf16 v[56:59], v[156:159], v[178:181], v[56:59]
	v_mfma_f32_16x16x32_bf16 v[48:51], v[164:167], v[178:181], v[48:51]
	v_mfma_f32_16x16x32_bf16 v[40:43], v[156:159], v[186:189], v[40:43]
	v_mfma_f32_16x16x32_bf16 v[32:35], v[164:167], v[186:189], v[32:35]
	v_mfma_f32_16x16x32_bf16 v[24:27], v[156:159], v[194:197], v[24:27]
	v_mfma_f32_16x16x32_bf16 v[16:19], v[164:167], v[194:197], v[16:19]
	v_mfma_f32_16x16x32_bf16 v[8:11], v[156:159], v[202:205], v[8:11]
	v_mfma_f32_16x16x32_bf16 v[0:3], v[164:167], v[202:205], v[0:3]
	s_setprio 0
	s_barrier
	s_add_u32 s26, s26, 0x40080
	s_addc_u32 s27, s27, 0
	s_add_i32 s28, s28, s31
	v_lshl_add_u64 v[144:145], s[26:27], 0, v[130:131]
	s_mov_b32 m0, s28
	s_nop 0
	global_load_lds_dwordx4 v[144:145], off
	v_lshl_add_u64 v[144:145], s[26:27], 0, v[134:135]
	s_add_i32 m0, s28, 0x2000
	s_nop 0
	global_load_lds_dwordx4 v[144:145], off
	s_waitcnt vmcnt(6)
	s_barrier
	s_setprio 1
	v_mfma_f32_16x16x32_bf16 v[60:63], v[206:209], v[168:171], v[60:63]
	v_mfma_f32_16x16x32_bf16 v[52:55], v[214:217], v[168:171], v[52:55]
	v_mfma_f32_16x16x32_bf16 v[44:47], v[206:209], v[182:185], v[44:47]
	v_mfma_f32_16x16x32_bf16 v[36:39], v[214:217], v[182:185], v[36:39]
	v_mfma_f32_16x16x32_bf16 v[28:31], v[206:209], v[190:193], v[28:31]
	v_mfma_f32_16x16x32_bf16 v[20:23], v[214:217], v[190:193], v[20:23]
	v_mfma_f32_16x16x32_bf16 v[12:15], v[206:209], v[198:201], v[12:15]
	v_mfma_f32_16x16x32_bf16 v[4:7], v[214:217], v[198:201], v[4:7]
	v_mfma_f32_16x16x32_bf16 v[60:63], v[210:213], v[178:181], v[60:63]
	v_mfma_f32_16x16x32_bf16 v[52:55], v[218:221], v[178:181], v[52:55]
	v_mfma_f32_16x16x32_bf16 v[44:47], v[210:213], v[186:189], v[44:47]
	v_mfma_f32_16x16x32_bf16 v[36:39], v[218:221], v[186:189], v[36:39]
	v_mfma_f32_16x16x32_bf16 v[28:31], v[210:213], v[194:197], v[28:31]
	v_mfma_f32_16x16x32_bf16 v[20:23], v[218:221], v[194:197], v[20:23]
	v_mfma_f32_16x16x32_bf16 v[12:15], v[210:213], v[202:205], v[12:15]
	v_mfma_f32_16x16x32_bf16 v[4:7], v[218:221], v[202:205], v[4:7]
	s_setprio 0
	s_add_i32 s55, s55, 2
	s_add_u32 s24, s24, 0x100
	s_addc_u32 s25, s25, 0
	s_add_u32 s53, s53, 0x100
	s_addc_u32 s54, s54, 0
	s_cmp_gt_u32 s55, 13
	s_barrier
	s_cbranch_scc0 .LBB0_1456
	v_lshl_add_u32 v144, s22, 8, v148
	v_ashrrev_i32_e32 v145, 31, v144
	v_lshl_add_u64 v[146:147], v[144:145], 2, s[12:13]
	global_load_dword v145, v[146:147], off
	global_load_dword v247, v[146:147], off offset:64
	global_load_dword v248, v[146:147], off offset:128
	global_load_dword v249, v[146:147], off offset:192
	global_load_dword v250, v[146:147], off offset:512
	global_load_dword v251, v[146:147], off offset:576
	global_load_dword v252, v[146:147], off offset:640
	global_load_dword v253, v[146:147], off offset:704
	v_lshl_or_b32 v156, s50, 7, v150
	v_mov_b32_e32 v161, v114
	v_mov_b32_e32 v114, v123
	v_mov_b32_e32 v158, v124
	v_mov_b32_e32 v159, v116
	v_mov_b32_e32 v116, v125
	v_mov_b32_e32 v124, v126
	v_mov_b32_e32 v125, v118
	v_mov_b32_e32 v118, v127
	v_mov_b32_e32 v126, v120
	v_mov_b32_e32 v127, v112
	v_mov_b32_e32 v112, v121
	v_mov_b32_e32 v160, v122
	v_mov_b64_e32 v[120:121], s[44:45]
	v_ashrrev_i32_e32 v157, 31, v156
	v_or_b32_e32 v164, 16, v144
	v_mad_i64_i32 v[162:163], s[24:25], v144, s49, v[120:121]
	v_lshlrev_b64 v[122:123], 1, v[156:157]
	v_ashrrev_i32_e32 v165, 31, v164
	v_lshl_add_u64 v[156:157], v[162:163], 0, v[122:123]
	v_lshl_add_u64 v[162:163], v[164:165], 2, s[12:13]
	s_mov_b32 s50, s14
	s_mov_b32 s22, s16
	s_mov_b64 s[26:27], s[20:21]
	s_waitcnt vmcnt(7)
	v_fmamk_f32 v145, v145, 0x3a800000, v154
	v_mul_f32_e32 v155, 0x4b800000, v145
	v_cmp_gt_f32_e32 vcc, s48, v145
	s_nop 1
	v_cndmask_b32_e32 v145, v145, v155, vcc
	v_rsq_f32_e32 v145, v145
	s_nop 0
	v_mul_f32_e32 v155, 0x45800000, v145
	v_cndmask_b32_e32 v166, v145, v155, vcc
	v_pk_mul_f32 v[114:115], v[114:115], v[166:167] op_sel_hi:[1,0]
	v_pk_mul_f32 v[158:159], v[158:159], v[166:167] op_sel_hi:[1,0]
	v_pk_mul_f32 v[116:117], v[116:117], v[166:167] op_sel_hi:[1,0]
	v_pk_mul_f32 v[124:125], v[124:125], v[166:167] op_sel_hi:[1,0]
	v_pk_mul_f32 v[118:119], v[118:119], v[166:167] op_sel_hi:[1,0]
	v_pk_mul_f32 v[126:127], v[126:127], v[166:167] op_sel_hi:[1,0]
	v_pk_mul_f32 v[112:113], v[112:113], v[166:167] op_sel_hi:[1,0]
	v_pk_mul_f32 v[160:161], v[160:161], v[166:167] op_sel_hi:[1,0]
	v_mul_f32_e32 v170, 0xbfb8aa3b, v115
	v_mul_f32_e32 v145, 0xbfb8aa3b, v159
	v_mul_f32_e32 v155, 0xbfb8aa3b, v117
	v_mul_f32_e32 v165, 0xbfb8aa3b, v125
	v_mul_f32_e32 v166, 0xbfb8aa3b, v119
	v_mul_f32_e32 v167, 0xbfb8aa3b, v127
	v_mul_f32_e32 v168, 0xbfb8aa3b, v113
	v_mul_f32_e32 v169, 0xbfb8aa3b, v161
	v_exp_f32_e32 v170, v170
	v_exp_f32_e32 v145, v145
	v_exp_f32_e32 v155, v155
	v_exp_f32_e32 v165, v165
	v_exp_f32_e32 v166, v166
	v_exp_f32_e32 v167, v167
	v_exp_f32_e32 v168, v168
	v_exp_f32_e32 v169, v169
	v_add_f32_e32 v170, 1.0, v170
	v_add_f32_e32 v145, 1.0, v145
	v_add_f32_e32 v155, 1.0, v155
	v_add_f32_e32 v165, 1.0, v165
	v_add_f32_e32 v166, 1.0, v166
	v_add_f32_e32 v167, 1.0, v167
	v_add_f32_e32 v168, 1.0, v168
	v_add_f32_e32 v169, 1.0, v169
	v_rcp_f32_e32 v170, v170
	v_rcp_f32_e32 v145, v145
	v_rcp_f32_e32 v155, v155
	v_rcp_f32_e32 v165, v165
	v_rcp_f32_e32 v166, v166
	v_rcp_f32_e32 v167, v167
	v_rcp_f32_e32 v168, v168
	v_rcp_f32_e32 v169, v169
	v_mul_f32_e32 v115, v115, v170
	v_mul_f32_e32 v145, v159, v145
	v_mul_f32_e32 v117, v117, v155
	v_mul_f32_e32 v125, v125, v165
	v_mul_f32_e32 v119, v119, v166
	v_mul_f32_e32 v127, v127, v167
	v_mul_f32_e32 v113, v113, v168
	v_mul_f32_e32 v155, v161, v169
	v_mul_f32_e32 v115, v114, v115
	v_mul_f32_e32 v145, v158, v145
	v_mul_f32_e32 v116, v116, v117
	v_mul_f32_e32 v117, v124, v125
	v_mul_f32_e32 v118, v118, v119
	v_mul_f32_e32 v119, v126, v127
	v_mul_f32_e32 v124, v112, v113
	v_mul_f32_e32 v125, v160, v155
	v_cvt_pk_bf16_f32 v112, v145, v116
	v_cvt_pk_bf16_f32 v113, v117, v118
	v_cvt_pk_bf16_f32 v114, v119, v124
	v_cvt_pk_bf16_f32 v115, v125, v115
	global_store_dwordx4 v[156:157], v[112:115], off
	s_nop 0
	v_mov_b32_e32 v113, v100
	v_mov_b32_e32 v100, v109
	v_mov_b32_e32 v109, v102
	v_mov_b32_e32 v102, v111
	v_mov_b32_e32 v111, v96
	v_mov_b32_e32 v96, v105
	v_mov_b32_e32 v105, v98
	v_mov_b32_e32 v98, v107
	v_mov_b32_e32 v112, v108
	v_mov_b32_e32 v108, v110
	v_mov_b32_e32 v110, v104
	v_mov_b32_e32 v104, v106
	v_or_b32_e32 v106, 32, v144
	v_mad_i64_i32 v[114:115], s[24:25], v164, s49, v[120:121]
	v_lshl_add_u64 v[114:115], v[114:115], 0, v[122:123]
	s_waitcnt vmcnt(7)
	v_mov_b32_e32 v116, v247
	v_fmamk_f32 v107, v116, 0x3a800000, v154
	v_mul_f32_e32 v116, 0x4b800000, v107
	v_cmp_gt_f32_e32 vcc, s48, v107
	s_nop 1
	v_cndmask_b32_e32 v107, v107, v116, vcc
	v_rsq_f32_e32 v118, v107
	v_ashrrev_i32_e32 v107, 31, v106
	v_lshl_add_u64 v[116:117], v[106:107], 2, s[12:13]
	v_mul_f32_e32 v107, 0x45800000, v118
	v_cndmask_b32_e32 v118, v118, v107, vcc
	v_pk_mul_f32 v[98:99], v[98:99], v[118:119] op_sel_hi:[1,0]
	v_pk_mul_f32 v[112:113], v[112:113], v[118:119] op_sel_hi:[1,0]
	v_pk_mul_f32 v[100:101], v[100:101], v[118:119] op_sel_hi:[1,0]
	v_pk_mul_f32 v[108:109], v[108:109], v[118:119] op_sel_hi:[1,0]
	v_pk_mul_f32 v[102:103], v[102:103], v[118:119] op_sel_hi:[1,0]
	v_pk_mul_f32 v[110:111], v[110:111], v[118:119] op_sel_hi:[1,0]
	v_pk_mul_f32 v[96:97], v[96:97], v[118:119] op_sel_hi:[1,0]
	v_pk_mul_f32 v[104:105], v[104:105], v[118:119] op_sel_hi:[1,0]
	v_mul_f32_e32 v145, 0xbfb8aa3b, v99
	v_mul_f32_e32 v107, 0xbfb8aa3b, v113
	v_mul_f32_e32 v118, 0xbfb8aa3b, v101
	v_mul_f32_e32 v119, 0xbfb8aa3b, v109
	v_mul_f32_e32 v124, 0xbfb8aa3b, v103
	v_mul_f32_e32 v125, 0xbfb8aa3b, v111
	v_mul_f32_e32 v126, 0xbfb8aa3b, v97
	v_mul_f32_e32 v127, 0xbfb8aa3b, v105
	v_exp_f32_e32 v145, v145
	v_exp_f32_e32 v107, v107
	v_exp_f32_e32 v118, v118
	v_exp_f32_e32 v119, v119
	v_exp_f32_e32 v124, v124
	v_exp_f32_e32 v125, v125
	v_exp_f32_e32 v126, v126
	v_exp_f32_e32 v127, v127
	v_add_f32_e32 v145, 1.0, v145
	v_add_f32_e32 v107, 1.0, v107
	v_add_f32_e32 v118, 1.0, v118
	v_add_f32_e32 v119, 1.0, v119
	v_add_f32_e32 v124, 1.0, v124
	v_add_f32_e32 v125, 1.0, v125
	v_add_f32_e32 v126, 1.0, v126
	v_add_f32_e32 v127, 1.0, v127
	v_rcp_f32_e32 v145, v145
	v_rcp_f32_e32 v107, v107
	v_rcp_f32_e32 v118, v118
	v_rcp_f32_e32 v119, v119
	v_rcp_f32_e32 v124, v124
	v_rcp_f32_e32 v125, v125
	v_rcp_f32_e32 v126, v126
	v_rcp_f32_e32 v127, v127
	v_mul_f32_e32 v99, v99, v145
	v_mul_f32_e32 v107, v113, v107
	v_mul_f32_e32 v101, v101, v118
	v_mul_f32_e32 v109, v109, v119
	v_mul_f32_e32 v103, v103, v124
	v_mul_f32_e32 v111, v111, v125
	v_mul_f32_e32 v97, v97, v126
	v_mul_f32_e32 v105, v105, v127
	v_mul_f32_e32 v99, v98, v99
	v_mul_f32_e32 v107, v112, v107
	v_mul_f32_e32 v100, v100, v101
	v_mul_f32_e32 v101, v108, v109
	v_mul_f32_e32 v102, v102, v103
	v_mul_f32_e32 v103, v110, v111
	v_mul_f32_e32 v108, v96, v97
	v_mul_f32_e32 v104, v104, v105
	v_cvt_pk_bf16_f32 v96, v107, v100
	v_cvt_pk_bf16_f32 v97, v101, v102
	v_cvt_pk_bf16_f32 v98, v103, v108
	v_cvt_pk_bf16_f32 v99, v104, v99
	global_store_dwordx4 v[114:115], v[96:99], off
	s_nop 0
	v_mov_b32_e32 v97, v84
	v_mov_b32_e32 v84, v93
	v_mov_b32_e32 v93, v86
	v_mov_b32_e32 v86, v95
	v_mov_b32_e32 v95, v80
	v_mov_b32_e32 v80, v89
	v_mov_b32_e32 v89, v82
	v_mov_b32_e32 v82, v91
	v_mov_b32_e32 v96, v92
	v_mov_b32_e32 v92, v94
	v_mov_b32_e32 v94, v88
	v_mov_b32_e32 v88, v90
	v_or_b32_e32 v90, 48, v144
	v_mad_i64_i32 v[98:99], s[24:25], v106, s49, v[120:121]
	v_lshl_add_u64 v[98:99], v[98:99], 0, v[122:123]
	s_waitcnt vmcnt(7)
	v_mov_b32_e32 v100, v248
	v_fmamk_f32 v91, v100, 0x3a800000, v154
	v_mul_f32_e32 v100, 0x4b800000, v91
	v_cmp_gt_f32_e32 vcc, s48, v91
	s_nop 1
	v_cndmask_b32_e32 v91, v91, v100, vcc
	v_rsq_f32_e32 v102, v91
	v_ashrrev_i32_e32 v91, 31, v90
	v_lshl_add_u64 v[100:101], v[90:91], 2, s[12:13]
	v_mul_f32_e32 v91, 0x45800000, v102
	v_cndmask_b32_e32 v102, v102, v91, vcc
	v_pk_mul_f32 v[82:83], v[82:83], v[102:103] op_sel_hi:[1,0]
	v_pk_mul_f32 v[96:97], v[96:97], v[102:103] op_sel_hi:[1,0]
	v_pk_mul_f32 v[84:85], v[84:85], v[102:103] op_sel_hi:[1,0]
	v_pk_mul_f32 v[92:93], v[92:93], v[102:103] op_sel_hi:[1,0]
	v_pk_mul_f32 v[86:87], v[86:87], v[102:103] op_sel_hi:[1,0]
	v_pk_mul_f32 v[94:95], v[94:95], v[102:103] op_sel_hi:[1,0]
	v_pk_mul_f32 v[80:81], v[80:81], v[102:103] op_sel_hi:[1,0]
	v_pk_mul_f32 v[88:89], v[88:89], v[102:103] op_sel_hi:[1,0]
	v_mul_f32_e32 v108, 0xbfb8aa3b, v83
	v_mul_f32_e32 v91, 0xbfb8aa3b, v97
	v_mul_f32_e32 v102, 0xbfb8aa3b, v85
	v_mul_f32_e32 v103, 0xbfb8aa3b, v93
	v_mul_f32_e32 v104, 0xbfb8aa3b, v87
	v_mul_f32_e32 v105, 0xbfb8aa3b, v95
	v_mul_f32_e32 v106, 0xbfb8aa3b, v81
	v_mul_f32_e32 v107, 0xbfb8aa3b, v89
	v_exp_f32_e32 v108, v108
	v_exp_f32_e32 v91, v91
	v_exp_f32_e32 v102, v102
	v_exp_f32_e32 v103, v103
	v_exp_f32_e32 v104, v104
	v_exp_f32_e32 v105, v105
	v_exp_f32_e32 v106, v106
	v_exp_f32_e32 v107, v107
	v_add_f32_e32 v108, 1.0, v108
	v_add_f32_e32 v91, 1.0, v91
	v_add_f32_e32 v102, 1.0, v102
	v_add_f32_e32 v103, 1.0, v103
	v_add_f32_e32 v104, 1.0, v104
	v_add_f32_e32 v105, 1.0, v105
	v_add_f32_e32 v106, 1.0, v106
	v_add_f32_e32 v107, 1.0, v107
	v_rcp_f32_e32 v108, v108
	v_rcp_f32_e32 v91, v91
	v_rcp_f32_e32 v102, v102
	v_rcp_f32_e32 v103, v103
	v_rcp_f32_e32 v104, v104
	v_rcp_f32_e32 v105, v105
	v_rcp_f32_e32 v106, v106
	v_rcp_f32_e32 v107, v107
	v_mul_f32_e32 v83, v83, v108
	v_mul_f32_e32 v91, v97, v91
	v_mul_f32_e32 v85, v85, v102
	v_mul_f32_e32 v93, v93, v103
	v_mul_f32_e32 v87, v87, v104
	v_mul_f32_e32 v95, v95, v105
	v_mul_f32_e32 v81, v81, v106
	v_mul_f32_e32 v89, v89, v107
	v_mul_f32_e32 v83, v82, v83
	v_mul_f32_e32 v91, v96, v91
	v_mul_f32_e32 v84, v84, v85
	v_mul_f32_e32 v85, v92, v93
	v_mul_f32_e32 v86, v86, v87
	v_mul_f32_e32 v87, v94, v95
	v_mul_f32_e32 v92, v80, v81
	v_mul_f32_e32 v88, v88, v89
	v_cvt_pk_bf16_f32 v80, v91, v84
	v_cvt_pk_bf16_f32 v81, v85, v86
	v_cvt_pk_bf16_f32 v82, v87, v92
	v_cvt_pk_bf16_f32 v83, v88, v83
	global_store_dwordx4 v[98:99], v[80:83], off
	s_nop 0
	v_mov_b32_e32 v80, v76
	v_mov_b32_e32 v76, v78
	v_mov_b32_e32 v78, v68
	v_mov_b32_e32 v68, v70
	v_mov_b32_e32 v81, v72
	v_mov_b32_e32 v72, v77
	v_mov_b32_e32 v77, v74
	v_mov_b32_e32 v74, v79
	v_mov_b32_e32 v79, v64
	v_mov_b32_e32 v64, v69
	v_mov_b32_e32 v69, v66
	v_mov_b32_e32 v66, v71
	s_waitcnt vmcnt(7)
	v_mov_b32_e32 v82, v249
	v_fmamk_f32 v70, v82, 0x3a800000, v154
	v_mul_f32_e32 v71, 0x4b800000, v70
	v_cmp_gt_f32_e32 vcc, s48, v70
	s_nop 1
	v_cndmask_b32_e32 v70, v70, v71, vcc
	v_rsq_f32_e32 v82, v70
	v_mad_i64_i32 v[70:71], s[24:25], v90, s49, v[120:121]
	v_lshl_add_u64 v[70:71], v[70:71], 0, v[122:123]
	v_mul_f32_e32 v83, 0x45800000, v82
	v_cndmask_b32_e32 v82, v82, v83, vcc
	v_pk_mul_f32 v[66:67], v[66:67], v[82:83] op_sel_hi:[1,0]
	v_pk_mul_f32 v[80:81], v[80:81], v[82:83] op_sel_hi:[1,0]
	v_pk_mul_f32 v[72:73], v[72:73], v[82:83] op_sel_hi:[1,0]
	v_pk_mul_f32 v[76:77], v[76:77], v[82:83] op_sel_hi:[1,0]
	v_pk_mul_f32 v[74:75], v[74:75], v[82:83] op_sel_hi:[1,0]
	v_pk_mul_f32 v[78:79], v[78:79], v[82:83] op_sel_hi:[1,0]
	v_pk_mul_f32 v[64:65], v[64:65], v[82:83] op_sel_hi:[1,0]
	v_pk_mul_f32 v[68:69], v[68:69], v[82:83] op_sel_hi:[1,0]
	v_mul_f32_e32 v89, 0xbfb8aa3b, v67
	v_mul_f32_e32 v82, 0xbfb8aa3b, v81
	v_mul_f32_e32 v83, 0xbfb8aa3b, v73
	v_mul_f32_e32 v84, 0xbfb8aa3b, v77
	v_mul_f32_e32 v85, 0xbfb8aa3b, v75
	v_mul_f32_e32 v86, 0xbfb8aa3b, v79
	v_mul_f32_e32 v87, 0xbfb8aa3b, v65
	v_mul_f32_e32 v88, 0xbfb8aa3b, v69
	v_exp_f32_e32 v89, v89
	v_exp_f32_e32 v82, v82
	v_exp_f32_e32 v83, v83
	v_exp_f32_e32 v84, v84
	v_exp_f32_e32 v85, v85
	v_exp_f32_e32 v86, v86
	v_exp_f32_e32 v87, v87
	v_exp_f32_e32 v88, v88
	v_add_f32_e32 v89, 1.0, v89
	v_add_f32_e32 v82, 1.0, v82
	v_add_f32_e32 v83, 1.0, v83
	v_add_f32_e32 v84, 1.0, v84
	v_add_f32_e32 v85, 1.0, v85
	v_add_f32_e32 v86, 1.0, v86
	v_add_f32_e32 v87, 1.0, v87
	v_add_f32_e32 v88, 1.0, v88
	v_rcp_f32_e32 v89, v89
	v_rcp_f32_e32 v82, v82
	v_rcp_f32_e32 v83, v83
	v_rcp_f32_e32 v84, v84
	v_rcp_f32_e32 v85, v85
	v_rcp_f32_e32 v86, v86
	v_rcp_f32_e32 v87, v87
	v_rcp_f32_e32 v88, v88
	v_mul_f32_e32 v67, v67, v89
	v_mul_f32_e32 v81, v81, v82
	v_mul_f32_e32 v73, v73, v83
	v_mul_f32_e32 v77, v77, v84
	v_mul_f32_e32 v75, v75, v85
	v_mul_f32_e32 v79, v79, v86
	v_mul_f32_e32 v65, v65, v87
	v_mul_f32_e32 v69, v69, v88
	v_mul_f32_e32 v67, v66, v67
	v_mul_f32_e32 v80, v80, v81
	v_mul_f32_e32 v72, v72, v73
	v_mul_f32_e32 v73, v76, v77
	v_mul_f32_e32 v74, v74, v75
	v_mul_f32_e32 v75, v78, v79
	v_mul_f32_e32 v76, v64, v65
	v_mul_f32_e32 v68, v68, v69
	v_cvt_pk_bf16_f32 v64, v80, v72
	v_cvt_pk_bf16_f32 v65, v73, v74
	v_cvt_pk_bf16_f32 v66, v75, v76
	v_cvt_pk_bf16_f32 v67, v68, v67
	global_store_dwordx4 v[70:71], v[64:67], off
	s_nop 0
	v_mov_b32_e32 v65, v56
	v_mov_b32_e32 v56, v61
	v_mov_b32_e32 v61, v58
	v_mov_b32_e32 v58, v63
	v_mov_b32_e32 v63, v48
	v_mov_b32_e32 v48, v53
	v_mov_b32_e32 v53, v50
	v_mov_b32_e32 v50, v55
	v_mov_b32_e32 v64, v60
	v_mov_b32_e32 v60, v62
	v_mov_b32_e32 v62, v52
	v_mov_b32_e32 v52, v54
	v_add_u32_e32 v54, 0x80, v144
	s_waitcnt vmcnt(7)
	v_mov_b32_e32 v66, v250
	v_fmamk_f32 v55, v66, 0x3a800000, v154
	v_mul_f32_e32 v66, 0x4b800000, v55
	v_cmp_gt_f32_e32 vcc, s48, v55
	s_nop 1
	v_cndmask_b32_e32 v55, v55, v66, vcc
	v_rsq_f32_e32 v66, v55
	v_mad_i64_i32 v[54:55], s[24:25], v54, s49, v[120:121]
	v_lshl_add_u64 v[54:55], v[54:55], 0, v[122:123]
	v_mul_f32_e32 v67, 0x45800000, v66
	v_cndmask_b32_e32 v66, v66, v67, vcc
	v_pk_mul_f32 v[50:51], v[50:51], v[66:67] op_sel_hi:[1,0]
	v_pk_mul_f32 v[64:65], v[64:65], v[66:67] op_sel_hi:[1,0]
	v_pk_mul_f32 v[56:57], v[56:57], v[66:67] op_sel_hi:[1,0]
	v_pk_mul_f32 v[60:61], v[60:61], v[66:67] op_sel_hi:[1,0]
	v_pk_mul_f32 v[58:59], v[58:59], v[66:67] op_sel_hi:[1,0]
	v_pk_mul_f32 v[62:63], v[62:63], v[66:67] op_sel_hi:[1,0]
	v_pk_mul_f32 v[48:49], v[48:49], v[66:67] op_sel_hi:[1,0]
	v_pk_mul_f32 v[52:53], v[52:53], v[66:67] op_sel_hi:[1,0]
	v_mul_f32_e32 v73, 0xbfb8aa3b, v51
	v_mul_f32_e32 v66, 0xbfb8aa3b, v65
	v_mul_f32_e32 v67, 0xbfb8aa3b, v57
	v_mul_f32_e32 v68, 0xbfb8aa3b, v61
	v_mul_f32_e32 v69, 0xbfb8aa3b, v59
	v_mul_f32_e32 v70, 0xbfb8aa3b, v63
	v_mul_f32_e32 v71, 0xbfb8aa3b, v49
	v_mul_f32_e32 v72, 0xbfb8aa3b, v53
	v_exp_f32_e32 v73, v73
	v_exp_f32_e32 v66, v66
	v_exp_f32_e32 v67, v67
	v_exp_f32_e32 v68, v68
	v_exp_f32_e32 v69, v69
	v_exp_f32_e32 v70, v70
	v_exp_f32_e32 v71, v71
	v_exp_f32_e32 v72, v72
	v_add_f32_e32 v73, 1.0, v73
	v_add_f32_e32 v66, 1.0, v66
	v_add_f32_e32 v67, 1.0, v67
	v_add_f32_e32 v68, 1.0, v68
	v_add_f32_e32 v69, 1.0, v69
	v_add_f32_e32 v70, 1.0, v70
	v_add_f32_e32 v71, 1.0, v71
	v_add_f32_e32 v72, 1.0, v72
	v_rcp_f32_e32 v73, v73
	v_rcp_f32_e32 v66, v66
	v_rcp_f32_e32 v67, v67
	v_rcp_f32_e32 v68, v68
	v_rcp_f32_e32 v69, v69
	v_rcp_f32_e32 v70, v70
	v_rcp_f32_e32 v71, v71
	v_rcp_f32_e32 v72, v72
	v_mul_f32_e32 v51, v51, v73
	v_mul_f32_e32 v65, v65, v66
	v_mul_f32_e32 v57, v57, v67
	v_mul_f32_e32 v61, v61, v68
	v_mul_f32_e32 v59, v59, v69
	v_mul_f32_e32 v63, v63, v70
	v_mul_f32_e32 v49, v49, v71
	v_mul_f32_e32 v53, v53, v72
	v_mul_f32_e32 v51, v50, v51
	v_mul_f32_e32 v64, v64, v65
	v_mul_f32_e32 v56, v56, v57
	v_mul_f32_e32 v57, v60, v61
	v_mul_f32_e32 v58, v58, v59
	v_mul_f32_e32 v59, v62, v63
	v_mul_f32_e32 v60, v48, v49
	v_mul_f32_e32 v52, v52, v53
	v_cvt_pk_bf16_f32 v48, v64, v56
	v_cvt_pk_bf16_f32 v49, v57, v58
	v_cvt_pk_bf16_f32 v50, v59, v60
	v_cvt_pk_bf16_f32 v51, v52, v51
	global_store_dwordx4 v[54:55], v[48:51], off
	s_nop 0
	v_mov_b32_e32 v49, v40
	v_mov_b32_e32 v40, v45
	v_mov_b32_e32 v45, v42
	v_mov_b32_e32 v42, v47
	v_mov_b32_e32 v47, v32
	v_mov_b32_e32 v32, v37
	v_mov_b32_e32 v37, v34
	v_mov_b32_e32 v34, v39
	v_mov_b32_e32 v48, v44
	v_mov_b32_e32 v44, v46
	v_mov_b32_e32 v46, v36
	v_mov_b32_e32 v36, v38
	v_add_u32_e32 v38, 0x90, v144
	s_waitcnt vmcnt(7)
	v_mov_b32_e32 v50, v251
	v_fmamk_f32 v39, v50, 0x3a800000, v154
	v_mul_f32_e32 v50, 0x4b800000, v39
	v_cmp_gt_f32_e32 vcc, s48, v39
	s_nop 1
	v_cndmask_b32_e32 v39, v39, v50, vcc
	v_rsq_f32_e32 v50, v39
	v_mad_i64_i32 v[38:39], s[24:25], v38, s49, v[120:121]
	v_lshl_add_u64 v[38:39], v[38:39], 0, v[122:123]
	v_mul_f32_e32 v51, 0x45800000, v50
	v_cndmask_b32_e32 v50, v50, v51, vcc
	v_pk_mul_f32 v[34:35], v[34:35], v[50:51] op_sel_hi:[1,0]
	v_pk_mul_f32 v[48:49], v[48:49], v[50:51] op_sel_hi:[1,0]
	v_pk_mul_f32 v[40:41], v[40:41], v[50:51] op_sel_hi:[1,0]
	v_pk_mul_f32 v[44:45], v[44:45], v[50:51] op_sel_hi:[1,0]
	v_pk_mul_f32 v[42:43], v[42:43], v[50:51] op_sel_hi:[1,0]
	v_pk_mul_f32 v[46:47], v[46:47], v[50:51] op_sel_hi:[1,0]
	v_pk_mul_f32 v[32:33], v[32:33], v[50:51] op_sel_hi:[1,0]
	v_pk_mul_f32 v[36:37], v[36:37], v[50:51] op_sel_hi:[1,0]
	v_mul_f32_e32 v57, 0xbfb8aa3b, v35
	v_mul_f32_e32 v50, 0xbfb8aa3b, v49
	v_mul_f32_e32 v51, 0xbfb8aa3b, v41
	v_mul_f32_e32 v52, 0xbfb8aa3b, v45
	v_mul_f32_e32 v53, 0xbfb8aa3b, v43
	v_mul_f32_e32 v54, 0xbfb8aa3b, v47
	v_mul_f32_e32 v55, 0xbfb8aa3b, v33
	v_mul_f32_e32 v56, 0xbfb8aa3b, v37
	v_exp_f32_e32 v57, v57
	v_exp_f32_e32 v50, v50
	v_exp_f32_e32 v51, v51
	v_exp_f32_e32 v52, v52
	v_exp_f32_e32 v53, v53
	v_exp_f32_e32 v54, v54
	v_exp_f32_e32 v55, v55
	v_exp_f32_e32 v56, v56
	v_add_f32_e32 v57, 1.0, v57
	v_add_f32_e32 v50, 1.0, v50
	v_add_f32_e32 v51, 1.0, v51
	v_add_f32_e32 v52, 1.0, v52
	v_add_f32_e32 v53, 1.0, v53
	v_add_f32_e32 v54, 1.0, v54
	v_add_f32_e32 v55, 1.0, v55
	v_add_f32_e32 v56, 1.0, v56
	v_rcp_f32_e32 v57, v57
	v_rcp_f32_e32 v50, v50
	v_rcp_f32_e32 v51, v51
	v_rcp_f32_e32 v52, v52
	v_rcp_f32_e32 v53, v53
	v_rcp_f32_e32 v54, v54
	v_rcp_f32_e32 v55, v55
	v_rcp_f32_e32 v56, v56
	v_mul_f32_e32 v35, v35, v57
	v_mul_f32_e32 v49, v49, v50
	v_mul_f32_e32 v41, v41, v51
	v_mul_f32_e32 v45, v45, v52
	v_mul_f32_e32 v43, v43, v53
	v_mul_f32_e32 v47, v47, v54
	v_mul_f32_e32 v33, v33, v55
	v_mul_f32_e32 v37, v37, v56
	v_mul_f32_e32 v35, v34, v35
	v_mul_f32_e32 v48, v48, v49
	v_mul_f32_e32 v40, v40, v41
	v_mul_f32_e32 v41, v44, v45
	v_mul_f32_e32 v42, v42, v43
	v_mul_f32_e32 v43, v46, v47
	v_mul_f32_e32 v44, v32, v33
	v_mul_f32_e32 v36, v36, v37
	v_cvt_pk_bf16_f32 v32, v48, v40
	v_cvt_pk_bf16_f32 v33, v41, v42
	v_cvt_pk_bf16_f32 v34, v43, v44
	v_cvt_pk_bf16_f32 v35, v36, v35
	global_store_dwordx4 v[38:39], v[32:35], off
	s_nop 0
	v_mov_b32_e32 v33, v24
	v_mov_b32_e32 v24, v29
	v_mov_b32_e32 v29, v26
	v_mov_b32_e32 v26, v31
	v_mov_b32_e32 v31, v16
	v_mov_b32_e32 v16, v21
	v_mov_b32_e32 v21, v18
	v_mov_b32_e32 v18, v23
	v_mov_b32_e32 v32, v28
	v_mov_b32_e32 v28, v30
	v_mov_b32_e32 v30, v20
	v_mov_b32_e32 v20, v22
	v_add_u32_e32 v22, 0xa0, v144
	s_waitcnt vmcnt(7)
	v_mov_b32_e32 v34, v252
	v_fmamk_f32 v23, v34, 0x3a800000, v154
	v_mul_f32_e32 v34, 0x4b800000, v23
	v_cmp_gt_f32_e32 vcc, s48, v23
	s_nop 1
	v_cndmask_b32_e32 v23, v23, v34, vcc
	v_rsq_f32_e32 v34, v23
	v_mad_i64_i32 v[22:23], s[24:25], v22, s49, v[120:121]
	v_lshl_add_u64 v[22:23], v[22:23], 0, v[122:123]
	v_mul_f32_e32 v35, 0x45800000, v34
	v_cndmask_b32_e32 v34, v34, v35, vcc
	v_pk_mul_f32 v[18:19], v[18:19], v[34:35] op_sel_hi:[1,0]
	v_pk_mul_f32 v[32:33], v[32:33], v[34:35] op_sel_hi:[1,0]
	v_pk_mul_f32 v[24:25], v[24:25], v[34:35] op_sel_hi:[1,0]
	v_pk_mul_f32 v[28:29], v[28:29], v[34:35] op_sel_hi:[1,0]
	v_pk_mul_f32 v[26:27], v[26:27], v[34:35] op_sel_hi:[1,0]
	v_pk_mul_f32 v[30:31], v[30:31], v[34:35] op_sel_hi:[1,0]
	v_pk_mul_f32 v[16:17], v[16:17], v[34:35] op_sel_hi:[1,0]
	v_pk_mul_f32 v[20:21], v[20:21], v[34:35] op_sel_hi:[1,0]
	v_mul_f32_e32 v41, 0xbfb8aa3b, v19
	v_mul_f32_e32 v34, 0xbfb8aa3b, v33
	v_mul_f32_e32 v35, 0xbfb8aa3b, v25
	v_mul_f32_e32 v36, 0xbfb8aa3b, v29
	v_mul_f32_e32 v37, 0xbfb8aa3b, v27
	v_mul_f32_e32 v38, 0xbfb8aa3b, v31
	v_mul_f32_e32 v39, 0xbfb8aa3b, v17
	v_mul_f32_e32 v40, 0xbfb8aa3b, v21
	v_exp_f32_e32 v41, v41
	v_exp_f32_e32 v34, v34
	v_exp_f32_e32 v35, v35
	v_exp_f32_e32 v36, v36
	v_exp_f32_e32 v37, v37
	v_exp_f32_e32 v38, v38
	v_exp_f32_e32 v39, v39
	v_exp_f32_e32 v40, v40
	v_add_f32_e32 v41, 1.0, v41
	v_add_f32_e32 v34, 1.0, v34
	v_add_f32_e32 v35, 1.0, v35
	v_add_f32_e32 v36, 1.0, v36
	v_add_f32_e32 v37, 1.0, v37
	v_add_f32_e32 v38, 1.0, v38
	v_add_f32_e32 v39, 1.0, v39
	v_add_f32_e32 v40, 1.0, v40
	v_rcp_f32_e32 v41, v41
	v_rcp_f32_e32 v34, v34
	v_rcp_f32_e32 v35, v35
	v_rcp_f32_e32 v36, v36
	v_rcp_f32_e32 v37, v37
	v_rcp_f32_e32 v38, v38
	v_rcp_f32_e32 v39, v39
	v_rcp_f32_e32 v40, v40
	v_mul_f32_e32 v19, v19, v41
	v_mul_f32_e32 v33, v33, v34
	v_mul_f32_e32 v25, v25, v35
	v_mul_f32_e32 v29, v29, v36
	v_mul_f32_e32 v27, v27, v37
	v_mul_f32_e32 v31, v31, v38
	v_mul_f32_e32 v17, v17, v39
	v_mul_f32_e32 v21, v21, v40
	v_mul_f32_e32 v19, v18, v19
	v_mul_f32_e32 v32, v32, v33
	v_mul_f32_e32 v24, v24, v25
	v_mul_f32_e32 v25, v28, v29
	v_mul_f32_e32 v26, v26, v27
	v_mul_f32_e32 v27, v30, v31
	v_mul_f32_e32 v28, v16, v17
	v_mul_f32_e32 v20, v20, v21
	v_cvt_pk_bf16_f32 v16, v32, v24
	v_cvt_pk_bf16_f32 v17, v25, v26
	v_cvt_pk_bf16_f32 v18, v27, v28
	v_cvt_pk_bf16_f32 v19, v20, v19
	global_store_dwordx4 v[22:23], v[16:19], off
	s_and_b64 vcc, exec, s[6:7]
	v_mov_b32_e32 v17, v8
	v_mov_b32_e32 v8, v13
	v_mov_b32_e32 v13, v10
	v_mov_b32_e32 v10, v15
	v_mov_b32_e32 v15, v0
	v_mov_b32_e32 v0, v5
	v_mov_b32_e32 v5, v2
	v_mov_b32_e32 v2, v7
	v_mov_b32_e32 v16, v12
	v_mov_b32_e32 v12, v14
	v_mov_b32_e32 v14, v4
	v_mov_b32_e32 v4, v6
	v_add_u32_e32 v6, 0xb0, v144
	s_mov_b64 s[24:25], s[18:19]
	s_waitcnt vmcnt(7)
	v_mov_b32_e32 v18, v253
	v_fmamk_f32 v7, v18, 0x3a800000, v154
	v_mul_f32_e32 v18, 0x4b800000, v7
	v_cmp_gt_f32_e64 s[6:7], s48, v7
	s_nop 1
	v_cndmask_b32_e64 v7, v7, v18, s[6:7]
	v_rsq_f32_e32 v18, v7
	v_mad_i64_i32 v[6:7], s[18:19], v6, s49, v[120:121]
	v_lshl_add_u64 v[6:7], v[6:7], 0, v[122:123]
	v_mul_f32_e32 v19, 0x45800000, v18
	v_cndmask_b32_e64 v18, v18, v19, s[6:7]
	v_pk_mul_f32 v[2:3], v[2:3], v[18:19] op_sel_hi:[1,0]
	v_pk_mul_f32 v[16:17], v[16:17], v[18:19] op_sel_hi:[1,0]
	v_pk_mul_f32 v[8:9], v[8:9], v[18:19] op_sel_hi:[1,0]
	v_pk_mul_f32 v[12:13], v[12:13], v[18:19] op_sel_hi:[1,0]
	v_pk_mul_f32 v[10:11], v[10:11], v[18:19] op_sel_hi:[1,0]
	v_pk_mul_f32 v[14:15], v[14:15], v[18:19] op_sel_hi:[1,0]
	v_pk_mul_f32 v[0:1], v[0:1], v[18:19] op_sel_hi:[1,0]
	v_pk_mul_f32 v[4:5], v[4:5], v[18:19] op_sel_hi:[1,0]
	v_mul_f32_e32 v25, 0xbfb8aa3b, v3
	v_mul_f32_e32 v18, 0xbfb8aa3b, v17
	v_mul_f32_e32 v19, 0xbfb8aa3b, v9
	v_mul_f32_e32 v20, 0xbfb8aa3b, v13
	v_mul_f32_e32 v21, 0xbfb8aa3b, v11
	v_mul_f32_e32 v22, 0xbfb8aa3b, v15
	v_mul_f32_e32 v23, 0xbfb8aa3b, v1
	v_mul_f32_e32 v24, 0xbfb8aa3b, v5
	v_exp_f32_e32 v25, v25
	v_exp_f32_e32 v18, v18
	v_exp_f32_e32 v19, v19
	v_exp_f32_e32 v20, v20
	v_exp_f32_e32 v21, v21
	v_exp_f32_e32 v22, v22
	v_exp_f32_e32 v23, v23
	v_exp_f32_e32 v24, v24
	v_add_f32_e32 v25, 1.0, v25
	v_add_f32_e32 v18, 1.0, v18
	v_add_f32_e32 v19, 1.0, v19
	v_add_f32_e32 v20, 1.0, v20
	v_add_f32_e32 v21, 1.0, v21
	v_add_f32_e32 v22, 1.0, v22
	v_add_f32_e32 v23, 1.0, v23
	v_add_f32_e32 v24, 1.0, v24
	v_rcp_f32_e32 v25, v25
	v_rcp_f32_e32 v18, v18
	v_rcp_f32_e32 v19, v19
	v_rcp_f32_e32 v20, v20
	v_rcp_f32_e32 v21, v21
	v_rcp_f32_e32 v22, v22
	v_rcp_f32_e32 v23, v23
	v_rcp_f32_e32 v24, v24
	v_mul_f32_e32 v3, v3, v25
	v_mul_f32_e32 v17, v17, v18
	v_mul_f32_e32 v9, v9, v19
	v_mul_f32_e32 v13, v13, v20
	v_mul_f32_e32 v11, v11, v21
	v_mul_f32_e32 v15, v15, v22
	v_mul_f32_e32 v1, v1, v23
	v_mul_f32_e32 v5, v5, v24
	v_mul_f32_e32 v3, v2, v3
	v_mul_f32_e32 v16, v16, v17
	v_mul_f32_e32 v8, v8, v9
	v_mul_f32_e32 v9, v12, v13
	v_mul_f32_e32 v10, v10, v11
	v_mul_f32_e32 v11, v14, v15
	v_mul_f32_e32 v12, v0, v1
	v_mul_f32_e32 v4, v4, v5
	v_cvt_pk_bf16_f32 v0, v16, v8
	v_cvt_pk_bf16_f32 v1, v9, v10
	v_cvt_pk_bf16_f32 v2, v11, v12
	v_cvt_pk_bf16_f32 v3, v4, v3
	global_store_dwordx4 v[6:7], v[0:3], off
	s_cbranch_vccz .LBB0_1449
	s_waitcnt vmcnt(0)
	s_cmpk_gt_u32 s3, 0xff
	s_cbranch_scc1 .LBB0_1460
	s_barrier
